# all 12 GEMM mainloops: s_setprio 1 hoisted above the pre-MFMA barrier, redundant lgkmcnt(0) and mid-cluster prio flips removed, s_setprio 0 after post-MFMA barrier
# speedup vs baseline: 1.0142x; 1.0062x over previous
.LBB7_327:
	ds_read_b128 v[128:131], v177
	ds_read_b128 v[132:135], v177 offset:1024
	ds_read_b128 v[136:139], v177 offset:2048
	ds_read_b128 v[140:143], v177 offset:3072
	ds_read_b128 v[160:163], v178
	ds_read_b128 v[164:167], v178 offset:1024
	ds_read_b128 v[168:171], v178 offset:2048
	ds_read_b128 v[180:183], v178 offset:3072
	s_add_i32 s87, s40, 2
	s_add_u32 s41, s38, 0xfffc0080
	s_addc_u32 s42, s39, -1
	s_cmp_eq_u32 s57, s40
	s_cselect_b32 s40, s84, s85
	s_cselect_b32 s43, s81, s42
	s_cselect_b32 s42, s82, s41
	s_cselect_b32 s41, s83, s86
	v_lshl_add_u64 v[172:173], s[38:39], 0, v[152:153]
	s_add_i32 m0, s48, 0xc000
	ds_read_b128 v[184:187], v179
	ds_read_b128 v[188:191], v179 offset:1024
	ds_read_b128 v[192:195], v179 offset:2048
	ds_read_b128 v[196:199], v179 offset:3072
	ds_read_b128 v[202:205], v179 offset:4096
	ds_read_b128 v[206:209], v179 offset:5120
	ds_read_b128 v[210:213], v179 offset:6144
	ds_read_b128 v[214:217], v179 offset:7168
	global_load_lds_dwordx4 v[172:173], off
	v_lshl_add_u64 v[172:173], s[38:39], 0, v[154:155]
	s_add_i32 m0, s48, 0xe000
	s_nop 0
	global_load_lds_dwordx4 v[172:173], off
	s_waitcnt vmcnt(8)
	s_waitcnt lgkmcnt(0)
	s_setprio 1
	s_barrier
	v_mfma_f32_16x16x32_bf16 v[124:127], v[128:131], v[184:187], v[124:127]
	v_mfma_f32_16x16x32_bf16 v[120:123], v[136:139], v[184:187], v[120:123]
	v_mfma_f32_16x16x32_bf16 v[108:111], v[128:131], v[192:195], v[108:111]
	v_mfma_f32_16x16x32_bf16 v[104:107], v[136:139], v[192:195], v[104:107]
	v_mfma_f32_16x16x32_bf16 v[92:95], v[128:131], v[202:205], v[92:95]
	v_mfma_f32_16x16x32_bf16 v[88:91], v[136:139], v[202:205], v[88:91]
	v_mfma_f32_16x16x32_bf16 v[76:79], v[128:131], v[210:213], v[76:79]
	v_mfma_f32_16x16x32_bf16 v[72:75], v[136:139], v[210:213], v[72:75]
	v_mfma_f32_16x16x32_bf16 v[124:127], v[132:135], v[188:191], v[124:127]
	v_mfma_f32_16x16x32_bf16 v[120:123], v[140:143], v[188:191], v[120:123]
	v_mfma_f32_16x16x32_bf16 v[108:111], v[132:135], v[196:199], v[108:111]
	v_mfma_f32_16x16x32_bf16 v[104:107], v[140:143], v[196:199], v[104:107]
	v_mfma_f32_16x16x32_bf16 v[92:95], v[132:135], v[206:209], v[92:95]
	v_mfma_f32_16x16x32_bf16 v[88:91], v[140:143], v[206:209], v[88:91]
	v_mfma_f32_16x16x32_bf16 v[76:79], v[132:135], v[214:217], v[76:79]
	v_mfma_f32_16x16x32_bf16 v[72:75], v[140:143], v[214:217], v[72:75]
	v_mfma_f32_16x16x32_bf16 v[116:119], v[160:163], v[184:187], v[116:119]
	v_mfma_f32_16x16x32_bf16 v[112:115], v[168:171], v[184:187], v[112:115]
	v_mfma_f32_16x16x32_bf16 v[100:103], v[160:163], v[192:195], v[100:103]
	v_mfma_f32_16x16x32_bf16 v[96:99], v[168:171], v[192:195], v[96:99]
	v_mfma_f32_16x16x32_bf16 v[84:87], v[160:163], v[202:205], v[84:87]
	v_mfma_f32_16x16x32_bf16 v[80:83], v[168:171], v[202:205], v[80:83]
	v_mfma_f32_16x16x32_bf16 v[68:71], v[160:163], v[210:213], v[68:71]
	v_mfma_f32_16x16x32_bf16 v[64:67], v[168:171], v[210:213], v[64:67]
	v_mfma_f32_16x16x32_bf16 v[116:119], v[164:167], v[188:191], v[116:119]
	v_mfma_f32_16x16x32_bf16 v[112:115], v[180:183], v[188:191], v[112:115]
	v_mfma_f32_16x16x32_bf16 v[100:103], v[164:167], v[196:199], v[100:103]
	v_mfma_f32_16x16x32_bf16 v[96:99], v[180:183], v[196:199], v[96:99]
	v_mfma_f32_16x16x32_bf16 v[84:87], v[164:167], v[206:209], v[84:87]
	v_mfma_f32_16x16x32_bf16 v[80:83], v[180:183], v[206:209], v[80:83]
	v_mfma_f32_16x16x32_bf16 v[68:71], v[164:167], v[214:217], v[68:71]
	v_mfma_f32_16x16x32_bf16 v[64:67], v[180:183], v[214:217], v[64:67]
	s_barrier
	s_setprio 0
	s_add_i32 s88, s58, s33
	v_lshl_add_u64 v[172:173], s[40:41], 0, v[148:149]
	s_mov_b32 m0, s88
	ds_read_b128 v[184:187], v179 offset:16384
	ds_read_b128 v[188:191], v179 offset:17408
	ds_read_b128 v[192:195], v179 offset:18432
	ds_read_b128 v[196:199], v179 offset:19456
	ds_read_b128 v[202:205], v179 offset:20480
	ds_read_b128 v[206:209], v179 offset:21504
	ds_read_b128 v[210:213], v179 offset:22528
	ds_read_b128 v[214:217], v179 offset:23552
	global_load_lds_dwordx4 v[172:173], off
	s_add_i32 m0, s88, 0x2000
	s_add_u32 s88, s40, 0x40000
	v_lshl_add_u64 v[218:219], s[40:41], 0, v[144:145]
	s_addc_u32 s89, s41, 0
	s_add_i32 s90, s64, s33
	global_load_lds_dwordx4 v[218:219], off
	v_lshl_add_u64 v[220:221], s[88:89], 0, v[148:149]
	s_mov_b32 m0, s90
	v_lshl_add_u64 v[222:223], s[42:43], 0, v[146:147]
	global_load_lds_dwordx4 v[220:221], off
	v_lshl_add_u64 v[220:221], s[88:89], 0, v[144:145]
	s_add_i32 m0, s90, 0x2000
	s_nop 0
	global_load_lds_dwordx4 v[220:221], off
	v_lshl_add_u64 v[220:221], s[42:43], 0, v[150:151]
	s_mov_b32 m0, s48
	s_nop 0
	global_load_lds_dwordx4 v[220:221], off
	s_mov_b32 m0, s49
	s_nop 0
	global_load_lds_dwordx4 v[222:223], off
	s_waitcnt vmcnt(8)
	s_waitcnt lgkmcnt(0)
	s_setprio 1
	s_barrier
	v_mfma_f32_16x16x32_bf16 v[60:63], v[128:131], v[184:187], v[60:63]
	v_mfma_f32_16x16x32_bf16 v[56:59], v[136:139], v[184:187], v[56:59]
	v_mfma_f32_16x16x32_bf16 v[44:47], v[128:131], v[192:195], v[44:47]
	v_mfma_f32_16x16x32_bf16 v[40:43], v[136:139], v[192:195], v[40:43]
	v_mfma_f32_16x16x32_bf16 v[28:31], v[128:131], v[202:205], v[28:31]
	v_mfma_f32_16x16x32_bf16 v[24:27], v[136:139], v[202:205], v[24:27]
	v_mfma_f32_16x16x32_bf16 v[12:15], v[128:131], v[210:213], v[12:15]
	v_mfma_f32_16x16x32_bf16 v[8:11], v[136:139], v[210:213], v[8:11]
	v_mfma_f32_16x16x32_bf16 v[60:63], v[132:135], v[188:191], v[60:63]
	v_mfma_f32_16x16x32_bf16 v[56:59], v[140:143], v[188:191], v[56:59]
	v_mfma_f32_16x16x32_bf16 v[44:47], v[132:135], v[196:199], v[44:47]
	v_mfma_f32_16x16x32_bf16 v[40:43], v[140:143], v[196:199], v[40:43]
	v_mfma_f32_16x16x32_bf16 v[28:31], v[132:135], v[206:209], v[28:31]
	v_mfma_f32_16x16x32_bf16 v[24:27], v[140:143], v[206:209], v[24:27]
	v_mfma_f32_16x16x32_bf16 v[12:15], v[132:135], v[214:217], v[12:15]
	v_mfma_f32_16x16x32_bf16 v[8:11], v[140:143], v[214:217], v[8:11]
	v_mfma_f32_16x16x32_bf16 v[52:55], v[160:163], v[184:187], v[52:55]
	v_mfma_f32_16x16x32_bf16 v[48:51], v[168:171], v[184:187], v[48:51]
	v_mfma_f32_16x16x32_bf16 v[36:39], v[160:163], v[192:195], v[36:39]
	v_mfma_f32_16x16x32_bf16 v[32:35], v[168:171], v[192:195], v[32:35]
	v_mfma_f32_16x16x32_bf16 v[20:23], v[160:163], v[202:205], v[20:23]
	v_mfma_f32_16x16x32_bf16 v[16:19], v[168:171], v[202:205], v[16:19]
	v_mfma_f32_16x16x32_bf16 v[4:7], v[160:163], v[210:213], v[4:7]
	v_mfma_f32_16x16x32_bf16 v[0:3], v[168:171], v[210:213], v[0:3]
	v_mfma_f32_16x16x32_bf16 v[52:55], v[164:167], v[188:191], v[52:55]
	v_mfma_f32_16x16x32_bf16 v[48:51], v[180:183], v[188:191], v[48:51]
	v_mfma_f32_16x16x32_bf16 v[36:39], v[164:167], v[196:199], v[36:39]
	v_mfma_f32_16x16x32_bf16 v[32:35], v[180:183], v[196:199], v[32:35]
	v_mfma_f32_16x16x32_bf16 v[20:23], v[164:167], v[206:209], v[20:23]
	v_mfma_f32_16x16x32_bf16 v[16:19], v[180:183], v[206:209], v[16:19]
	v_mfma_f32_16x16x32_bf16 v[4:7], v[164:167], v[214:217], v[4:7]
	v_mfma_f32_16x16x32_bf16 v[0:3], v[180:183], v[214:217], v[0:3]
	s_barrier
	s_setprio 0
	s_add_i32 s88, 0, 0x18000
	s_add_i32 s89, 0, 0x1c000
	v_add_u32_e32 v140, s88, v175
	v_add_u32_e32 v180, s89, v175
	ds_read_b128 v[128:131], v140
	ds_read_b128 v[132:135], v140 offset:1024
	ds_read_b128 v[136:139], v140 offset:2048
	ds_read_b128 v[140:143], v140 offset:3072
	ds_read_b128 v[160:163], v180
	ds_read_b128 v[164:167], v180 offset:1024
	ds_read_b128 v[168:171], v180 offset:2048
	ds_read_b128 v[180:183], v180 offset:3072
	s_add_u32 s42, s42, 0x40000
	s_addc_u32 s43, s43, 0
	s_mov_b32 m0, s50
	v_lshl_add_u64 v[224:225], s[42:43], 0, v[150:151]
	ds_read_b128 v[184:187], v179 offset:32768
	ds_read_b128 v[188:191], v179 offset:33792
	ds_read_b128 v[192:195], v179 offset:34816
	ds_read_b128 v[196:199], v179 offset:35840
	ds_read_b128 v[202:205], v179 offset:36864
	ds_read_b128 v[206:209], v179 offset:37888
	ds_read_b128 v[210:213], v179 offset:38912
	ds_read_b128 v[214:217], v179 offset:39936
	global_load_lds_dwordx4 v[224:225], off
	v_lshl_add_u64 v[224:225], s[42:43], 0, v[146:147]
	s_mov_b32 m0, s51
	s_nop 0
	global_load_lds_dwordx4 v[224:225], off
	s_waitcnt vmcnt(8)
	s_waitcnt lgkmcnt(0)
	s_setprio 1
	s_barrier
	v_mfma_f32_16x16x32_bf16 v[124:127], v[128:131], v[184:187], v[124:127]
	v_mfma_f32_16x16x32_bf16 v[120:123], v[136:139], v[184:187], v[120:123]
	v_mfma_f32_16x16x32_bf16 v[108:111], v[128:131], v[192:195], v[108:111]
	v_mfma_f32_16x16x32_bf16 v[104:107], v[136:139], v[192:195], v[104:107]
	v_mfma_f32_16x16x32_bf16 v[92:95], v[128:131], v[202:205], v[92:95]
	v_mfma_f32_16x16x32_bf16 v[88:91], v[136:139], v[202:205], v[88:91]
	v_mfma_f32_16x16x32_bf16 v[76:79], v[128:131], v[210:213], v[76:79]
	v_mfma_f32_16x16x32_bf16 v[72:75], v[136:139], v[210:213], v[72:75]
	v_mfma_f32_16x16x32_bf16 v[124:127], v[132:135], v[188:191], v[124:127]
	v_mfma_f32_16x16x32_bf16 v[120:123], v[140:143], v[188:191], v[120:123]
	v_mfma_f32_16x16x32_bf16 v[108:111], v[132:135], v[196:199], v[108:111]
	v_mfma_f32_16x16x32_bf16 v[104:107], v[140:143], v[196:199], v[104:107]
	v_mfma_f32_16x16x32_bf16 v[92:95], v[132:135], v[206:209], v[92:95]
	v_mfma_f32_16x16x32_bf16 v[88:91], v[140:143], v[206:209], v[88:91]
	v_mfma_f32_16x16x32_bf16 v[76:79], v[132:135], v[214:217], v[76:79]
	v_mfma_f32_16x16x32_bf16 v[72:75], v[140:143], v[214:217], v[72:75]
	v_mfma_f32_16x16x32_bf16 v[116:119], v[160:163], v[184:187], v[116:119]
	v_mfma_f32_16x16x32_bf16 v[112:115], v[168:171], v[184:187], v[112:115]
	v_mfma_f32_16x16x32_bf16 v[100:103], v[160:163], v[192:195], v[100:103]
	v_mfma_f32_16x16x32_bf16 v[96:99], v[168:171], v[192:195], v[96:99]
	v_mfma_f32_16x16x32_bf16 v[84:87], v[160:163], v[202:205], v[84:87]
	v_mfma_f32_16x16x32_bf16 v[80:83], v[168:171], v[202:205], v[80:83]
	v_mfma_f32_16x16x32_bf16 v[68:71], v[160:163], v[210:213], v[68:71]
	v_mfma_f32_16x16x32_bf16 v[64:67], v[168:171], v[210:213], v[64:67]
	v_mfma_f32_16x16x32_bf16 v[116:119], v[164:167], v[188:191], v[116:119]
	v_mfma_f32_16x16x32_bf16 v[112:115], v[180:183], v[188:191], v[112:115]
	v_mfma_f32_16x16x32_bf16 v[100:103], v[164:167], v[196:199], v[100:103]
	v_mfma_f32_16x16x32_bf16 v[96:99], v[180:183], v[196:199], v[96:99]
	v_mfma_f32_16x16x32_bf16 v[84:87], v[164:167], v[206:209], v[84:87]
	v_mfma_f32_16x16x32_bf16 v[80:83], v[180:183], v[206:209], v[80:83]
	v_mfma_f32_16x16x32_bf16 v[68:71], v[164:167], v[214:217], v[68:71]
	v_mfma_f32_16x16x32_bf16 v[64:67], v[180:183], v[214:217], v[64:67]
	s_barrier
	s_setprio 0
	s_add_i32 s42, s88, s33
	v_lshl_add_u64 v[172:173], v[172:173], 0, s[10:11]
	s_mov_b32 m0, s42
	ds_read_b128 v[184:187], v179 offset:49152
	ds_read_b128 v[188:191], v179 offset:50176
	ds_read_b128 v[192:195], v179 offset:51200
	ds_read_b128 v[196:199], v179 offset:52224
	ds_read_b128 v[202:205], v179 offset:53248
	ds_read_b128 v[206:209], v179 offset:54272
	ds_read_b128 v[210:213], v179 offset:55296
	ds_read_b128 v[214:217], v179 offset:56320
	global_load_lds_dwordx4 v[172:173], off
	s_add_i32 m0, s42, 0x2000
	s_add_u32 s40, s40, 0x40080
	v_lshl_add_u64 v[172:173], v[218:219], 0, s[10:11]
	s_addc_u32 s41, s41, 0
	s_add_i32 s42, s89, s33
	global_load_lds_dwordx4 v[172:173], off
	v_lshl_add_u64 v[172:173], s[40:41], 0, v[148:149]
	s_mov_b32 m0, s42
	s_nop 0
	global_load_lds_dwordx4 v[172:173], off
	v_lshl_add_u64 v[172:173], s[40:41], 0, v[144:145]
	s_add_i32 m0, s42, 0x2000
	s_nop 0
	global_load_lds_dwordx4 v[172:173], off
	v_lshl_add_u64 v[172:173], v[220:221], 0, s[10:11]
	s_mov_b32 m0, s55
	s_nop 0
	global_load_lds_dwordx4 v[172:173], off
	v_lshl_add_u64 v[172:173], v[222:223], 0, s[10:11]
	s_mov_b32 m0, s56
	s_nop 0
	global_load_lds_dwordx4 v[172:173], off
	s_waitcnt vmcnt(8)
	s_waitcnt lgkmcnt(0)
	s_setprio 1
	s_barrier
	v_mfma_f32_16x16x32_bf16 v[60:63], v[128:131], v[184:187], v[60:63]
	v_mfma_f32_16x16x32_bf16 v[56:59], v[136:139], v[184:187], v[56:59]
	v_mfma_f32_16x16x32_bf16 v[44:47], v[128:131], v[192:195], v[44:47]
	v_mfma_f32_16x16x32_bf16 v[40:43], v[136:139], v[192:195], v[40:43]
	v_mfma_f32_16x16x32_bf16 v[28:31], v[128:131], v[202:205], v[28:31]
	v_mfma_f32_16x16x32_bf16 v[24:27], v[136:139], v[202:205], v[24:27]
	v_mfma_f32_16x16x32_bf16 v[12:15], v[128:131], v[210:213], v[12:15]
	v_mfma_f32_16x16x32_bf16 v[8:11], v[136:139], v[210:213], v[8:11]
	v_mfma_f32_16x16x32_bf16 v[60:63], v[132:135], v[188:191], v[60:63]
	v_mfma_f32_16x16x32_bf16 v[56:59], v[140:143], v[188:191], v[56:59]
	v_mfma_f32_16x16x32_bf16 v[44:47], v[132:135], v[196:199], v[44:47]
	v_mfma_f32_16x16x32_bf16 v[40:43], v[140:143], v[196:199], v[40:43]
	v_mfma_f32_16x16x32_bf16 v[28:31], v[132:135], v[206:209], v[28:31]
	v_mfma_f32_16x16x32_bf16 v[24:27], v[140:143], v[206:209], v[24:27]
	v_mfma_f32_16x16x32_bf16 v[12:15], v[132:135], v[214:217], v[12:15]
	v_mfma_f32_16x16x32_bf16 v[8:11], v[140:143], v[214:217], v[8:11]
	v_mfma_f32_16x16x32_bf16 v[52:55], v[160:163], v[184:187], v[52:55]
	v_mfma_f32_16x16x32_bf16 v[48:51], v[168:171], v[184:187], v[48:51]
	v_mfma_f32_16x16x32_bf16 v[36:39], v[160:163], v[192:195], v[36:39]
	v_mfma_f32_16x16x32_bf16 v[32:35], v[168:171], v[192:195], v[32:35]
	v_mfma_f32_16x16x32_bf16 v[20:23], v[160:163], v[202:205], v[20:23]
	v_mfma_f32_16x16x32_bf16 v[16:19], v[168:171], v[202:205], v[16:19]
	v_mfma_f32_16x16x32_bf16 v[4:7], v[160:163], v[210:213], v[4:7]
	v_mfma_f32_16x16x32_bf16 v[0:3], v[168:171], v[210:213], v[0:3]
	v_mfma_f32_16x16x32_bf16 v[52:55], v[164:167], v[188:191], v[52:55]
	v_mfma_f32_16x16x32_bf16 v[48:51], v[180:183], v[188:191], v[48:51]
	v_mfma_f32_16x16x32_bf16 v[36:39], v[164:167], v[196:199], v[36:39]
	v_mfma_f32_16x16x32_bf16 v[32:35], v[180:183], v[196:199], v[32:35]
	v_mfma_f32_16x16x32_bf16 v[20:23], v[164:167], v[206:209], v[20:23]
	v_mfma_f32_16x16x32_bf16 v[16:19], v[180:183], v[206:209], v[16:19]
	v_mfma_f32_16x16x32_bf16 v[4:7], v[164:167], v[214:217], v[4:7]
	v_mfma_f32_16x16x32_bf16 v[0:3], v[180:183], v[214:217], v[0:3]
	s_barrier
	s_setprio 0
	s_add_u32 s38, s38, 0x100
	s_addc_u32 s39, s39, 0
	s_add_u32 s85, s85, 0x100
	s_addc_u32 s86, s86, 0
	s_cmp_ge_i32 s87, s26
	s_mov_b32 s40, s87
	s_cbranch_scc0 .LBB7_327
	v_readlane_b32 s87, v251, 12
	v_readlane_b32 s89, v251, 13
	s_and_b64 vcc, exec, s[12:13]
	s_cbranch_vccz .LBB7_330

.LBB7_357:
	s_add_i32 s86, s42, 2
	s_add_u32 s29, s16, 0xfffc0080
	s_addc_u32 s37, s17, -1
	s_add_i32 s74, 0, 0x10000
	s_cmp_eq_u32 s20, s42
	s_cselect_b32 s73, s9, s37
	s_cselect_b32 s72, s13, s29
	v_add_u32_e32 v170, s74, v179
	s_cselect_b32 s43, s28, s57
	s_cselect_b32 s42, s39, s56
	s_add_i32 s29, 0, 0x14000
	ds_read_b128 v[130:133], v170
	ds_read_b128 v[180:183], v170 offset:1024
	ds_read_b128 v[184:187], v170 offset:2048
	ds_read_b128 v[188:191], v170 offset:3072
	v_add_u32_e32 v170, s29, v179
	ds_read_b128 v[192:195], v170
	ds_read_b128 v[196:199], v170 offset:1024
	ds_read_b128 v[204:207], v170 offset:2048
	ds_read_b128 v[208:211], v170 offset:3072
	v_lshl_add_u64 v[244:245], s[16:17], 0, v[174:175]
	s_add_i32 m0, s4, 0xc000
	ds_read_b128 v[212:215], v143
	ds_read_b128 v[216:219], v143 offset:1024
	ds_read_b128 v[220:223], v143 offset:2048
	ds_read_b128 v[224:227], v143 offset:3072
	ds_read_b128 v[228:231], v143 offset:4096
	ds_read_b128 v[232:235], v143 offset:5120
	ds_read_b128 v[236:239], v143 offset:6144
	ds_read_b128 v[240:243], v143 offset:7168
	global_load_lds_dwordx4 v[244:245], off
	v_lshl_add_u64 v[244:245], s[16:17], 0, v[176:177]
	s_add_i32 m0, s4, 0xe000
	s_nop 0
	global_load_lds_dwordx4 v[244:245], off
	s_waitcnt vmcnt(8)
	s_waitcnt lgkmcnt(0)
	s_setprio 1
	s_barrier
	v_mfma_f32_16x16x32_bf16 v[126:129], v[130:133], v[212:215], v[126:129]
	v_mfma_f32_16x16x32_bf16 v[118:121], v[184:187], v[212:215], v[118:121]
	v_mfma_f32_16x16x32_bf16 v[110:113], v[130:133], v[220:223], v[110:113]
	v_mfma_f32_16x16x32_bf16 v[102:105], v[184:187], v[220:223], v[102:105]
	v_mfma_f32_16x16x32_bf16 v[94:97], v[130:133], v[228:231], v[94:97]
	v_mfma_f32_16x16x32_bf16 v[86:89], v[184:187], v[228:231], v[86:89]
	v_mfma_f32_16x16x32_bf16 v[78:81], v[130:133], v[236:239], v[78:81]
	v_mfma_f32_16x16x32_bf16 v[70:73], v[184:187], v[236:239], v[70:73]
	v_mfma_f32_16x16x32_bf16 v[126:129], v[180:183], v[216:219], v[126:129]
	v_mfma_f32_16x16x32_bf16 v[118:121], v[188:191], v[216:219], v[118:121]
	v_mfma_f32_16x16x32_bf16 v[110:113], v[180:183], v[224:227], v[110:113]
	v_mfma_f32_16x16x32_bf16 v[102:105], v[188:191], v[224:227], v[102:105]
	v_mfma_f32_16x16x32_bf16 v[94:97], v[180:183], v[232:235], v[94:97]
	v_mfma_f32_16x16x32_bf16 v[86:89], v[188:191], v[232:235], v[86:89]
	v_mfma_f32_16x16x32_bf16 v[78:81], v[180:183], v[240:243], v[78:81]
	v_mfma_f32_16x16x32_bf16 v[70:73], v[188:191], v[240:243], v[70:73]
	v_mfma_f32_16x16x32_bf16 v[122:125], v[192:195], v[212:215], v[122:125]
	v_mfma_f32_16x16x32_bf16 v[114:117], v[204:207], v[212:215], v[114:117]
	v_mfma_f32_16x16x32_bf16 v[106:109], v[192:195], v[220:223], v[106:109]
	v_mfma_f32_16x16x32_bf16 v[98:101], v[204:207], v[220:223], v[98:101]
	v_mfma_f32_16x16x32_bf16 v[90:93], v[192:195], v[228:231], v[90:93]
	v_mfma_f32_16x16x32_bf16 v[82:85], v[204:207], v[228:231], v[82:85]
	v_mfma_f32_16x16x32_bf16 v[74:77], v[192:195], v[236:239], v[74:77]
	v_mfma_f32_16x16x32_bf16 v[66:69], v[204:207], v[236:239], v[66:69]
	v_mfma_f32_16x16x32_bf16 v[122:125], v[196:199], v[216:219], v[122:125]
	v_mfma_f32_16x16x32_bf16 v[114:117], v[208:211], v[216:219], v[114:117]
	v_mfma_f32_16x16x32_bf16 v[106:109], v[196:199], v[224:227], v[106:109]
	v_mfma_f32_16x16x32_bf16 v[98:101], v[208:211], v[224:227], v[98:101]
	v_mfma_f32_16x16x32_bf16 v[90:93], v[196:199], v[232:235], v[90:93]
	v_mfma_f32_16x16x32_bf16 v[82:85], v[208:211], v[232:235], v[82:85]
	v_mfma_f32_16x16x32_bf16 v[74:77], v[196:199], v[240:243], v[74:77]
	v_mfma_f32_16x16x32_bf16 v[66:69], v[208:211], v[240:243], v[66:69]
	s_barrier
	s_setprio 0
	s_add_i32 s37, s74, s84
	v_lshl_add_u64 v[244:245], s[42:43], 0, v[138:139]
	s_mov_b32 m0, s37
	ds_read_b128 v[212:215], v143 offset:16384
	ds_read_b128 v[216:219], v143 offset:17408
	ds_read_b128 v[220:223], v143 offset:18432
	ds_read_b128 v[224:227], v143 offset:19456
	ds_read_b128 v[228:231], v143 offset:20480
	ds_read_b128 v[232:235], v143 offset:21504
	ds_read_b128 v[236:239], v143 offset:22528
	ds_read_b128 v[240:243], v143 offset:23552
	global_load_lds_dwordx4 v[244:245], off
	s_add_i32 m0, s37, 0x2000
	s_add_u32 s74, s42, 0x40000
	v_lshl_add_u64 v[246:247], s[42:43], 0, v[134:135]
	s_addc_u32 s75, s43, 0
	s_add_i32 s29, s29, s84
	global_load_lds_dwordx4 v[246:247], off
	v_lshl_add_u64 v[248:249], s[74:75], 0, v[138:139]
	s_mov_b32 m0, s29
	v_lshl_add_u64 v[170:171], s[72:73], 0, v[136:137]
	global_load_lds_dwordx4 v[248:249], off
	v_lshl_add_u64 v[248:249], s[74:75], 0, v[134:135]
	s_add_i32 m0, s29, 0x2000
	s_nop 0
	global_load_lds_dwordx4 v[248:249], off
	v_lshl_add_u64 v[248:249], s[72:73], 0, v[140:141]
	s_mov_b32 m0, s4
	s_nop 0
	global_load_lds_dwordx4 v[248:249], off
	s_mov_b32 m0, s5
	s_nop 0
	global_load_lds_dwordx4 v[170:171], off
	s_waitcnt vmcnt(8)
	s_waitcnt lgkmcnt(0)
	s_setprio 1
	s_barrier
	v_mfma_f32_16x16x32_bf16 v[62:65], v[130:133], v[212:215], v[62:65]
	v_mfma_f32_16x16x32_bf16 v[54:57], v[184:187], v[212:215], v[54:57]
	v_mfma_f32_16x16x32_bf16 v[46:49], v[130:133], v[220:223], v[46:49]
	v_mfma_f32_16x16x32_bf16 v[38:41], v[184:187], v[220:223], v[38:41]
	v_mfma_f32_16x16x32_bf16 v[30:33], v[130:133], v[228:231], v[30:33]
	v_mfma_f32_16x16x32_bf16 v[22:25], v[184:187], v[228:231], v[22:25]
	v_mfma_f32_16x16x32_bf16 v[14:17], v[130:133], v[236:239], v[14:17]
	v_mfma_f32_16x16x32_bf16 v[6:9], v[184:187], v[236:239], v[6:9]
	v_mfma_f32_16x16x32_bf16 v[62:65], v[180:183], v[216:219], v[62:65]
	v_mfma_f32_16x16x32_bf16 v[54:57], v[188:191], v[216:219], v[54:57]
	v_mfma_f32_16x16x32_bf16 v[46:49], v[180:183], v[224:227], v[46:49]
	v_mfma_f32_16x16x32_bf16 v[38:41], v[188:191], v[224:227], v[38:41]
	v_mfma_f32_16x16x32_bf16 v[30:33], v[180:183], v[232:235], v[30:33]
	v_mfma_f32_16x16x32_bf16 v[22:25], v[188:191], v[232:235], v[22:25]
	v_mfma_f32_16x16x32_bf16 v[14:17], v[180:183], v[240:243], v[14:17]
	v_mfma_f32_16x16x32_bf16 v[6:9], v[188:191], v[240:243], v[6:9]
	v_mfma_f32_16x16x32_bf16 v[58:61], v[192:195], v[212:215], v[58:61]
	v_mfma_f32_16x16x32_bf16 v[50:53], v[204:207], v[212:215], v[50:53]
	v_mfma_f32_16x16x32_bf16 v[42:45], v[192:195], v[220:223], v[42:45]
	v_mfma_f32_16x16x32_bf16 v[34:37], v[204:207], v[220:223], v[34:37]
	v_mfma_f32_16x16x32_bf16 v[26:29], v[192:195], v[228:231], v[26:29]
	v_mfma_f32_16x16x32_bf16 v[18:21], v[204:207], v[228:231], v[18:21]
	v_mfma_f32_16x16x32_bf16 v[10:13], v[192:195], v[236:239], v[10:13]
	v_mfma_f32_16x16x32_bf16 v[2:5], v[204:207], v[236:239], v[2:5]
	v_mfma_f32_16x16x32_bf16 v[58:61], v[196:199], v[216:219], v[58:61]
	v_mfma_f32_16x16x32_bf16 v[50:53], v[208:211], v[216:219], v[50:53]
	v_mfma_f32_16x16x32_bf16 v[42:45], v[196:199], v[224:227], v[42:45]
	v_mfma_f32_16x16x32_bf16 v[34:37], v[208:211], v[224:227], v[34:37]
	v_mfma_f32_16x16x32_bf16 v[26:29], v[196:199], v[232:235], v[26:29]
	v_mfma_f32_16x16x32_bf16 v[18:21], v[208:211], v[232:235], v[18:21]
	v_mfma_f32_16x16x32_bf16 v[10:13], v[196:199], v[240:243], v[10:13]
	v_mfma_f32_16x16x32_bf16 v[2:5], v[208:211], v[240:243], v[2:5]
	s_barrier
	s_setprio 0
	s_add_i32 s29, 0, 0x18000
	v_add_u32_e32 v172, s29, v179
	s_add_i32 s37, 0, 0x1c000
	ds_read_b128 v[130:133], v172
	ds_read_b128 v[180:183], v172 offset:1024
	ds_read_b128 v[184:187], v172 offset:2048
	ds_read_b128 v[188:191], v172 offset:3072
	v_add_u32_e32 v172, s37, v179
	ds_read_b128 v[192:195], v172
	ds_read_b128 v[196:199], v172 offset:1024
	ds_read_b128 v[204:207], v172 offset:2048
	ds_read_b128 v[208:211], v172 offset:3072
	s_add_u32 s72, s72, 0x40000
	s_addc_u32 s73, s73, 0
	s_mov_b32 m0, s93
	v_lshl_add_u64 v[172:173], s[72:73], 0, v[140:141]
	ds_read_b128 v[212:215], v143 offset:32768
	ds_read_b128 v[216:219], v143 offset:33792
	ds_read_b128 v[220:223], v143 offset:34816
	ds_read_b128 v[224:227], v143 offset:35840
	ds_read_b128 v[228:231], v143 offset:36864
	ds_read_b128 v[232:235], v143 offset:37888
	ds_read_b128 v[236:239], v143 offset:38912
	ds_read_b128 v[240:243], v143 offset:39936
	global_load_lds_dwordx4 v[172:173], off
	v_lshl_add_u64 v[172:173], s[72:73], 0, v[136:137]
	s_mov_b32 m0, s33
	s_nop 0
	global_load_lds_dwordx4 v[172:173], off
	s_waitcnt vmcnt(8)
	s_waitcnt lgkmcnt(0)
	s_setprio 1
	s_barrier
	v_mfma_f32_16x16x32_bf16 v[126:129], v[130:133], v[212:215], v[126:129]
	v_mfma_f32_16x16x32_bf16 v[118:121], v[184:187], v[212:215], v[118:121]
	v_mfma_f32_16x16x32_bf16 v[110:113], v[130:133], v[220:223], v[110:113]
	v_mfma_f32_16x16x32_bf16 v[102:105], v[184:187], v[220:223], v[102:105]
	v_mfma_f32_16x16x32_bf16 v[94:97], v[130:133], v[228:231], v[94:97]
	v_mfma_f32_16x16x32_bf16 v[86:89], v[184:187], v[228:231], v[86:89]
	v_mfma_f32_16x16x32_bf16 v[78:81], v[130:133], v[236:239], v[78:81]
	v_mfma_f32_16x16x32_bf16 v[70:73], v[184:187], v[236:239], v[70:73]
	v_mfma_f32_16x16x32_bf16 v[126:129], v[180:183], v[216:219], v[126:129]
	v_mfma_f32_16x16x32_bf16 v[118:121], v[188:191], v[216:219], v[118:121]
	v_mfma_f32_16x16x32_bf16 v[110:113], v[180:183], v[224:227], v[110:113]
	v_mfma_f32_16x16x32_bf16 v[102:105], v[188:191], v[224:227], v[102:105]
	v_mfma_f32_16x16x32_bf16 v[94:97], v[180:183], v[232:235], v[94:97]
	v_mfma_f32_16x16x32_bf16 v[86:89], v[188:191], v[232:235], v[86:89]
	v_mfma_f32_16x16x32_bf16 v[78:81], v[180:183], v[240:243], v[78:81]
	v_mfma_f32_16x16x32_bf16 v[70:73], v[188:191], v[240:243], v[70:73]
	v_mfma_f32_16x16x32_bf16 v[122:125], v[192:195], v[212:215], v[122:125]
	v_mfma_f32_16x16x32_bf16 v[114:117], v[204:207], v[212:215], v[114:117]
	v_mfma_f32_16x16x32_bf16 v[106:109], v[192:195], v[220:223], v[106:109]
	v_mfma_f32_16x16x32_bf16 v[98:101], v[204:207], v[220:223], v[98:101]
	v_mfma_f32_16x16x32_bf16 v[90:93], v[192:195], v[228:231], v[90:93]
	v_mfma_f32_16x16x32_bf16 v[82:85], v[204:207], v[228:231], v[82:85]
	v_mfma_f32_16x16x32_bf16 v[74:77], v[192:195], v[236:239], v[74:77]
	v_mfma_f32_16x16x32_bf16 v[66:69], v[204:207], v[236:239], v[66:69]
	v_mfma_f32_16x16x32_bf16 v[122:125], v[196:199], v[216:219], v[122:125]
	v_mfma_f32_16x16x32_bf16 v[114:117], v[208:211], v[216:219], v[114:117]
	v_mfma_f32_16x16x32_bf16 v[106:109], v[196:199], v[224:227], v[106:109]
	v_mfma_f32_16x16x32_bf16 v[98:101], v[208:211], v[224:227], v[98:101]
	v_mfma_f32_16x16x32_bf16 v[90:93], v[196:199], v[232:235], v[90:93]
	v_mfma_f32_16x16x32_bf16 v[82:85], v[208:211], v[232:235], v[82:85]
	v_mfma_f32_16x16x32_bf16 v[74:77], v[196:199], v[240:243], v[74:77]
	v_mfma_f32_16x16x32_bf16 v[66:69], v[208:211], v[240:243], v[66:69]
	s_barrier
	s_setprio 0
	s_add_i32 s29, s29, s84
	v_lshl_add_u64 v[172:173], v[244:245], 0, s[24:25]
	s_mov_b32 m0, s29
	ds_read_b128 v[212:215], v143 offset:49152
	ds_read_b128 v[216:219], v143 offset:50176
	ds_read_b128 v[220:223], v143 offset:51200
	ds_read_b128 v[224:227], v143 offset:52224
	ds_read_b128 v[228:231], v143 offset:53248
	ds_read_b128 v[232:235], v143 offset:54272
	ds_read_b128 v[236:239], v143 offset:55296
	ds_read_b128 v[240:243], v143 offset:56320
	global_load_lds_dwordx4 v[172:173], off
	s_add_i32 m0, s29, 0x2000
	s_add_u32 s42, s42, 0x40080
	v_lshl_add_u64 v[172:173], v[246:247], 0, s[24:25]
	s_addc_u32 s43, s43, 0
	s_add_i32 s29, s37, s84
	global_load_lds_dwordx4 v[172:173], off
	v_lshl_add_u64 v[172:173], s[42:43], 0, v[138:139]
	s_mov_b32 m0, s29
	v_lshl_add_u64 v[170:171], v[170:171], 0, s[24:25]
	global_load_lds_dwordx4 v[172:173], off
	v_lshl_add_u64 v[172:173], s[42:43], 0, v[134:135]
	s_add_i32 m0, s29, 0x2000
	s_nop 0
	global_load_lds_dwordx4 v[172:173], off
	v_lshl_add_u64 v[172:173], v[248:249], 0, s[24:25]
	s_mov_b32 m0, s97
	s_nop 0
	global_load_lds_dwordx4 v[172:173], off
	s_mov_b32 m0, s3
	s_nop 0
	global_load_lds_dwordx4 v[170:171], off
	s_waitcnt vmcnt(8)
	s_waitcnt lgkmcnt(0)
	s_setprio 1
	s_barrier
	v_mfma_f32_16x16x32_bf16 v[62:65], v[130:133], v[212:215], v[62:65]
	v_mfma_f32_16x16x32_bf16 v[54:57], v[184:187], v[212:215], v[54:57]
	v_mfma_f32_16x16x32_bf16 v[46:49], v[130:133], v[220:223], v[46:49]
	v_mfma_f32_16x16x32_bf16 v[38:41], v[184:187], v[220:223], v[38:41]
	v_mfma_f32_16x16x32_bf16 v[30:33], v[130:133], v[228:231], v[30:33]
	v_mfma_f32_16x16x32_bf16 v[22:25], v[184:187], v[228:231], v[22:25]
	v_mfma_f32_16x16x32_bf16 v[14:17], v[130:133], v[236:239], v[14:17]
	v_mfma_f32_16x16x32_bf16 v[6:9], v[184:187], v[236:239], v[6:9]
	v_mfma_f32_16x16x32_bf16 v[62:65], v[180:183], v[216:219], v[62:65]
	v_mfma_f32_16x16x32_bf16 v[54:57], v[188:191], v[216:219], v[54:57]
	v_mfma_f32_16x16x32_bf16 v[46:49], v[180:183], v[224:227], v[46:49]
	v_mfma_f32_16x16x32_bf16 v[38:41], v[188:191], v[224:227], v[38:41]
	v_mfma_f32_16x16x32_bf16 v[30:33], v[180:183], v[232:235], v[30:33]
	v_mfma_f32_16x16x32_bf16 v[22:25], v[188:191], v[232:235], v[22:25]
	v_mfma_f32_16x16x32_bf16 v[14:17], v[180:183], v[240:243], v[14:17]
	v_mfma_f32_16x16x32_bf16 v[6:9], v[188:191], v[240:243], v[6:9]
	v_mfma_f32_16x16x32_bf16 v[58:61], v[192:195], v[212:215], v[58:61]
	v_mfma_f32_16x16x32_bf16 v[50:53], v[204:207], v[212:215], v[50:53]
	v_mfma_f32_16x16x32_bf16 v[42:45], v[192:195], v[220:223], v[42:45]
	v_mfma_f32_16x16x32_bf16 v[34:37], v[204:207], v[220:223], v[34:37]
	v_mfma_f32_16x16x32_bf16 v[26:29], v[192:195], v[228:231], v[26:29]
	v_mfma_f32_16x16x32_bf16 v[18:21], v[204:207], v[228:231], v[18:21]
	v_mfma_f32_16x16x32_bf16 v[10:13], v[192:195], v[236:239], v[10:13]
	v_mfma_f32_16x16x32_bf16 v[2:5], v[204:207], v[236:239], v[2:5]
	v_mfma_f32_16x16x32_bf16 v[58:61], v[196:199], v[216:219], v[58:61]
	v_mfma_f32_16x16x32_bf16 v[50:53], v[208:211], v[216:219], v[50:53]
	v_mfma_f32_16x16x32_bf16 v[42:45], v[196:199], v[224:227], v[42:45]
	v_mfma_f32_16x16x32_bf16 v[34:37], v[208:211], v[224:227], v[34:37]
	v_mfma_f32_16x16x32_bf16 v[26:29], v[196:199], v[232:235], v[26:29]
	v_mfma_f32_16x16x32_bf16 v[18:21], v[208:211], v[232:235], v[18:21]
	v_mfma_f32_16x16x32_bf16 v[10:13], v[196:199], v[240:243], v[10:13]
	v_mfma_f32_16x16x32_bf16 v[2:5], v[208:211], v[240:243], v[2:5]
	s_barrier
	s_setprio 0
	s_add_u32 s16, s16, 0x100
	s_addc_u32 s17, s17, 0
	s_add_u32 s56, s56, 0x100
	s_addc_u32 s57, s57, 0
	s_cmp_ge_i32 s86, s23
	s_mov_b32 s42, s86
	s_cbranch_scc0 .LBB7_357
	s_mov_b32 s56, s61

.LBB7_434:
	s_add_i32 s75, s72, 2
	s_add_u32 s76, s16, 0x4000
	s_addc_u32 s73, s17, 0
	s_cmp_eq_u32 s3, s72
	s_cselect_b32 s72, s86, s76
	s_cselect_b32 s73, s20, s73
	s_cselect_b32 s84, s37, s29
	s_cselect_b32 s85, s87, s74
	s_add_u32 vcc_lo, s72, 0x8000
	s_addc_u32 vcc_hi, s73, 0
	s_add_i32 s76, 0, 0x10000
	v_add_u32_e32 v0, s76, v205
	s_add_i32 s91, 0, 0x14000
	ds_read_b128 v[132:135], v0
	ds_read_b128 v[136:139], v0 offset:1024
	ds_read_b128 v[140:143], v0 offset:2048
	ds_read_b128 v[144:147], v0 offset:3072
	v_add_u32_e32 v0, s91, v205
	ds_read_b128 v[148:151], v0
	ds_read_b128 v[152:155], v0 offset:1024
	ds_read_b128 v[156:159], v0 offset:2048
	ds_read_b128 v[184:187], v0 offset:3072
	s_waitcnt lgkmcnt(0)
	v_lshl_add_u64 v[2:3], s[16:17], 0, v[180:181]
	s_add_i32 m0, s23, 0xc000
	ds_read_b128 v[188:191], v207
	ds_read_b128 v[192:195], v207 offset:1024
	ds_read_b128 v[196:199], v207 offset:2048
	ds_read_b128 v[208:211], v207 offset:3072
	ds_read_b128 v[212:215], v207 offset:4096
	ds_read_b128 v[216:219], v207 offset:5120
	ds_read_b128 v[220:223], v207 offset:6144
	ds_read_b128 v[224:227], v207 offset:7168
	global_load_lds_dwordx4 v[2:3], off
	v_lshl_add_u64 v[2:3], s[16:17], 0, v[182:183]
	s_add_i32 m0, s23, 0xe000
	s_nop 0
	global_load_lds_dwordx4 v[2:3], off
	s_waitcnt vmcnt(8)
	s_waitcnt lgkmcnt(0)
	s_setprio 1
	s_barrier
	v_mfma_f32_16x16x32_bf16 v[128:131], v[132:135], v[188:191], v[128:131]
	v_mfma_f32_16x16x32_bf16 v[124:127], v[140:143], v[188:191], v[124:127]
	v_mfma_f32_16x16x32_bf16 v[120:123], v[132:135], v[196:199], v[120:123]
	v_mfma_f32_16x16x32_bf16 v[116:119], v[140:143], v[196:199], v[116:119]
	v_mfma_f32_16x16x32_bf16 v[112:115], v[132:135], v[212:215], v[112:115]
	v_mfma_f32_16x16x32_bf16 v[108:111], v[140:143], v[212:215], v[108:111]
	v_mfma_f32_16x16x32_bf16 v[104:107], v[132:135], v[220:223], v[104:107]
	v_mfma_f32_16x16x32_bf16 v[100:103], v[140:143], v[220:223], v[100:103]
	v_mfma_f32_16x16x32_bf16 v[128:131], v[136:139], v[192:195], v[128:131]
	v_mfma_f32_16x16x32_bf16 v[124:127], v[144:147], v[192:195], v[124:127]
	v_mfma_f32_16x16x32_bf16 v[120:123], v[136:139], v[208:211], v[120:123]
	v_mfma_f32_16x16x32_bf16 v[116:119], v[144:147], v[208:211], v[116:119]
	v_mfma_f32_16x16x32_bf16 v[112:115], v[136:139], v[216:219], v[112:115]
	v_mfma_f32_16x16x32_bf16 v[108:111], v[144:147], v[216:219], v[108:111]
	v_mfma_f32_16x16x32_bf16 v[104:107], v[136:139], v[224:227], v[104:107]
	v_mfma_f32_16x16x32_bf16 v[100:103], v[144:147], v[224:227], v[100:103]
	v_mfma_f32_16x16x32_bf16 v[96:99], v[148:151], v[188:191], v[96:99]
	v_mfma_f32_16x16x32_bf16 v[92:95], v[156:159], v[188:191], v[92:95]
	v_mfma_f32_16x16x32_bf16 v[88:91], v[148:151], v[196:199], v[88:91]
	v_mfma_f32_16x16x32_bf16 v[84:87], v[156:159], v[196:199], v[84:87]
	v_mfma_f32_16x16x32_bf16 v[80:83], v[148:151], v[212:215], v[80:83]
	v_mfma_f32_16x16x32_bf16 v[76:79], v[156:159], v[212:215], v[76:79]
	v_mfma_f32_16x16x32_bf16 v[72:75], v[148:151], v[220:223], v[72:75]
	v_mfma_f32_16x16x32_bf16 v[64:67], v[156:159], v[220:223], v[64:67]
	v_mfma_f32_16x16x32_bf16 v[96:99], v[152:155], v[192:195], v[96:99]
	v_mfma_f32_16x16x32_bf16 v[92:95], v[184:187], v[192:195], v[92:95]
	v_mfma_f32_16x16x32_bf16 v[88:91], v[152:155], v[208:211], v[88:91]
	v_mfma_f32_16x16x32_bf16 v[84:87], v[184:187], v[208:211], v[84:87]
	v_mfma_f32_16x16x32_bf16 v[80:83], v[152:155], v[216:219], v[80:83]
	v_mfma_f32_16x16x32_bf16 v[76:79], v[184:187], v[216:219], v[76:79]
	v_mfma_f32_16x16x32_bf16 v[72:75], v[152:155], v[224:227], v[72:75]
	v_mfma_f32_16x16x32_bf16 v[64:67], v[184:187], v[224:227], v[64:67]
	s_barrier
	s_setprio 0
	s_add_i32 s76, s76, s4
	v_lshl_add_u64 v[2:3], s[84:85], 0, v[176:177]
	s_mov_b32 m0, s76
	ds_read_b128 v[188:191], v207 offset:16384
	ds_read_b128 v[192:195], v207 offset:17408
	ds_read_b128 v[196:199], v207 offset:18432
	ds_read_b128 v[208:211], v207 offset:19456
	ds_read_b128 v[212:215], v207 offset:20480
	ds_read_b128 v[216:219], v207 offset:21504
	ds_read_b128 v[220:223], v207 offset:22528
	ds_read_b128 v[224:227], v207 offset:23552
	global_load_lds_dwordx4 v[2:3], off
	s_add_i32 m0, s76, 0x2000
	s_add_u32 s76, s84, 0x4000
	v_lshl_add_u64 v[2:3], s[84:85], 0, v[160:161]
	s_addc_u32 s77, s85, 0
	s_add_i32 s91, s91, s4
	global_load_lds_dwordx4 v[2:3], off
	v_lshl_add_u64 v[2:3], s[76:77], 0, v[176:177]
	s_mov_b32 m0, s91
	s_nop 0
	global_load_lds_dwordx4 v[2:3], off
	v_lshl_add_u64 v[2:3], s[76:77], 0, v[160:161]
	s_add_i32 m0, s91, 0x2000
	s_nop 0
	global_load_lds_dwordx4 v[2:3], off
	v_lshl_add_u64 v[2:3], s[72:73], 0, v[178:179]
	s_mov_b32 m0, s23
	s_nop 0
	global_load_lds_dwordx4 v[2:3], off
	v_lshl_add_u64 v[2:3], s[72:73], 0, v[174:175]
	s_mov_b32 m0, s31
	s_nop 0
	global_load_lds_dwordx4 v[2:3], off
	s_waitcnt vmcnt(8)
	s_waitcnt lgkmcnt(0)
	s_setprio 1
	s_barrier
	v_mfma_f32_16x16x32_bf16 v[68:71], v[132:135], v[188:191], v[68:71]
	v_mfma_f32_16x16x32_bf16 v[60:63], v[140:143], v[188:191], v[60:63]
	v_mfma_f32_16x16x32_bf16 v[56:59], v[132:135], v[196:199], v[56:59]
	v_mfma_f32_16x16x32_bf16 v[52:55], v[140:143], v[196:199], v[52:55]
	v_mfma_f32_16x16x32_bf16 v[48:51], v[132:135], v[212:215], v[48:51]
	v_mfma_f32_16x16x32_bf16 v[44:47], v[140:143], v[212:215], v[44:47]
	v_mfma_f32_16x16x32_bf16 v[40:43], v[132:135], v[220:223], v[40:43]
	v_mfma_f32_16x16x32_bf16 v[36:39], v[140:143], v[220:223], v[36:39]
	v_mfma_f32_16x16x32_bf16 v[68:71], v[136:139], v[192:195], v[68:71]
	v_mfma_f32_16x16x32_bf16 v[60:63], v[144:147], v[192:195], v[60:63]
	v_mfma_f32_16x16x32_bf16 v[56:59], v[136:139], v[208:211], v[56:59]
	v_mfma_f32_16x16x32_bf16 v[52:55], v[144:147], v[208:211], v[52:55]
	v_mfma_f32_16x16x32_bf16 v[48:51], v[136:139], v[216:219], v[48:51]
	v_mfma_f32_16x16x32_bf16 v[44:47], v[144:147], v[216:219], v[44:47]
	v_mfma_f32_16x16x32_bf16 v[40:43], v[136:139], v[224:227], v[40:43]
	v_mfma_f32_16x16x32_bf16 v[36:39], v[144:147], v[224:227], v[36:39]
	v_mfma_f32_16x16x32_bf16 v[32:35], v[148:151], v[188:191], v[32:35]
	v_mfma_f32_16x16x32_bf16 v[28:31], v[156:159], v[188:191], v[28:31]
	v_mfma_f32_16x16x32_bf16 v[24:27], v[148:151], v[196:199], v[24:27]
	v_mfma_f32_16x16x32_bf16 v[20:23], v[156:159], v[196:199], v[20:23]
	v_mfma_f32_16x16x32_bf16 v[16:19], v[148:151], v[212:215], v[16:19]
	v_mfma_f32_16x16x32_bf16 v[12:15], v[156:159], v[212:215], v[12:15]
	v_mfma_f32_16x16x32_bf16 v[8:11], v[148:151], v[220:223], v[8:11]
	v_mfma_f32_16x16x32_bf16 v[2:5], v[156:159], v[220:223], v[4:7]
	v_mfma_f32_16x16x32_bf16 v[32:35], v[152:155], v[192:195], v[32:35]
	v_mfma_f32_16x16x32_bf16 v[28:31], v[184:187], v[192:195], v[28:31]
	v_mfma_f32_16x16x32_bf16 v[24:27], v[152:155], v[208:211], v[24:27]
	v_mfma_f32_16x16x32_bf16 v[20:23], v[184:187], v[208:211], v[20:23]
	v_mfma_f32_16x16x32_bf16 v[16:19], v[152:155], v[216:219], v[16:19]
	v_mfma_f32_16x16x32_bf16 v[12:15], v[184:187], v[216:219], v[12:15]
	v_mfma_f32_16x16x32_bf16 v[8:11], v[152:155], v[224:227], v[8:11]
	v_mfma_f32_16x16x32_bf16 v[2:5], v[184:187], v[224:227], v[2:5]
	s_barrier
	s_setprio 0
	s_add_i32 s76, 0, 0x18000
	v_add_u32_e32 v0, s76, v205
	s_add_i32 s77, 0, 0x1c000
	ds_read_b128 v[132:135], v0
	ds_read_b128 v[136:139], v0 offset:1024
	ds_read_b128 v[140:143], v0 offset:2048
	ds_read_b128 v[144:147], v0 offset:3072
	v_add_u32_e32 v0, s77, v205
	ds_read_b128 v[148:151], v0
	ds_read_b128 v[152:155], v0 offset:1024
	ds_read_b128 v[156:159], v0 offset:2048
	ds_read_b128 v[184:187], v0 offset:3072
	s_add_u32 s72, s72, 0x4000
	s_addc_u32 s73, s73, 0
	s_mov_b32 m0, s33
	v_lshl_add_u64 v[6:7], s[72:73], 0, v[178:179]
	ds_read_b128 v[188:191], v207 offset:32768
	ds_read_b128 v[192:195], v207 offset:33792
	ds_read_b128 v[196:199], v207 offset:34816
	ds_read_b128 v[208:211], v207 offset:35840
	ds_read_b128 v[212:215], v207 offset:36864
	ds_read_b128 v[216:219], v207 offset:37888
	ds_read_b128 v[220:223], v207 offset:38912
	ds_read_b128 v[224:227], v207 offset:39936
	global_load_lds_dwordx4 v[6:7], off
	v_lshl_add_u64 v[6:7], s[72:73], 0, v[174:175]
	s_mov_b32 m0, s93
	s_nop 0
	global_load_lds_dwordx4 v[6:7], off
	s_waitcnt vmcnt(8)
	s_waitcnt lgkmcnt(0)
	s_setprio 1
	s_barrier
	v_mfma_f32_16x16x32_bf16 v[128:131], v[132:135], v[188:191], v[128:131]
	v_mfma_f32_16x16x32_bf16 v[124:127], v[140:143], v[188:191], v[124:127]
	v_mfma_f32_16x16x32_bf16 v[120:123], v[132:135], v[196:199], v[120:123]
	v_mfma_f32_16x16x32_bf16 v[116:119], v[140:143], v[196:199], v[116:119]
	v_mfma_f32_16x16x32_bf16 v[112:115], v[132:135], v[212:215], v[112:115]
	v_mfma_f32_16x16x32_bf16 v[108:111], v[140:143], v[212:215], v[108:111]
	v_mfma_f32_16x16x32_bf16 v[104:107], v[132:135], v[220:223], v[104:107]
	v_mfma_f32_16x16x32_bf16 v[100:103], v[140:143], v[220:223], v[100:103]
	v_mfma_f32_16x16x32_bf16 v[128:131], v[136:139], v[192:195], v[128:131]
	v_mfma_f32_16x16x32_bf16 v[124:127], v[144:147], v[192:195], v[124:127]
	v_mfma_f32_16x16x32_bf16 v[120:123], v[136:139], v[208:211], v[120:123]
	v_mfma_f32_16x16x32_bf16 v[116:119], v[144:147], v[208:211], v[116:119]
	v_mfma_f32_16x16x32_bf16 v[112:115], v[136:139], v[216:219], v[112:115]
	v_mfma_f32_16x16x32_bf16 v[108:111], v[144:147], v[216:219], v[108:111]
	v_mfma_f32_16x16x32_bf16 v[104:107], v[136:139], v[224:227], v[104:107]
	v_mfma_f32_16x16x32_bf16 v[100:103], v[144:147], v[224:227], v[100:103]
	v_mfma_f32_16x16x32_bf16 v[96:99], v[148:151], v[188:191], v[96:99]
	v_mfma_f32_16x16x32_bf16 v[92:95], v[156:159], v[188:191], v[92:95]
	v_mfma_f32_16x16x32_bf16 v[88:91], v[148:151], v[196:199], v[88:91]
	v_mfma_f32_16x16x32_bf16 v[84:87], v[156:159], v[196:199], v[84:87]
	v_mfma_f32_16x16x32_bf16 v[80:83], v[148:151], v[212:215], v[80:83]
	v_mfma_f32_16x16x32_bf16 v[76:79], v[156:159], v[212:215], v[76:79]
	v_mfma_f32_16x16x32_bf16 v[72:75], v[148:151], v[220:223], v[72:75]
	v_mfma_f32_16x16x32_bf16 v[64:67], v[156:159], v[220:223], v[64:67]
	v_mfma_f32_16x16x32_bf16 v[96:99], v[152:155], v[192:195], v[96:99]
	v_mfma_f32_16x16x32_bf16 v[92:95], v[184:187], v[192:195], v[92:95]
	v_mfma_f32_16x16x32_bf16 v[88:91], v[152:155], v[208:211], v[88:91]
	v_mfma_f32_16x16x32_bf16 v[84:87], v[184:187], v[208:211], v[84:87]
	v_mfma_f32_16x16x32_bf16 v[80:83], v[152:155], v[216:219], v[80:83]
	v_mfma_f32_16x16x32_bf16 v[76:79], v[184:187], v[216:219], v[76:79]
	v_mfma_f32_16x16x32_bf16 v[72:75], v[152:155], v[224:227], v[72:75]
	v_mfma_f32_16x16x32_bf16 v[64:67], v[184:187], v[224:227], v[64:67]
	s_barrier
	s_setprio 0
	s_add_u32 s72, s84, 0x8000
	s_addc_u32 s73, s85, 0
	s_add_i32 s76, s76, s4
	v_lshl_add_u64 v[6:7], s[72:73], 0, v[176:177]
	s_mov_b32 m0, s76
	ds_read_b128 v[188:191], v207 offset:49152
	ds_read_b128 v[192:195], v207 offset:50176
	ds_read_b128 v[196:199], v207 offset:51200
	ds_read_b128 v[208:211], v207 offset:52224
	ds_read_b128 v[212:215], v207 offset:53248
	ds_read_b128 v[216:219], v207 offset:54272
	ds_read_b128 v[220:223], v207 offset:55296
	ds_read_b128 v[224:227], v207 offset:56320
	global_load_lds_dwordx4 v[6:7], off
	s_add_i32 m0, s76, 0x2000
	v_lshl_add_u64 v[6:7], s[72:73], 0, v[160:161]
	s_add_u32 s72, s84, 0xc000
	s_addc_u32 s73, s85, 0
	s_add_i32 s76, s77, s4
	global_load_lds_dwordx4 v[6:7], off
	v_lshl_add_u64 v[6:7], s[72:73], 0, v[176:177]
	s_mov_b32 m0, s76
	s_nop 0
	global_load_lds_dwordx4 v[6:7], off
	v_lshl_add_u64 v[6:7], s[72:73], 0, v[160:161]
	s_add_i32 m0, s76, 0x2000
	s_nop 0
	global_load_lds_dwordx4 v[6:7], off
	v_lshl_add_u64 v[6:7], vcc, 0, v[178:179]
	s_mov_b32 m0, s97
	s_nop 0
	global_load_lds_dwordx4 v[6:7], off
	v_lshl_add_u64 v[6:7], vcc, 0, v[174:175]
	s_mov_b32 m0, s38
	s_nop 0
	global_load_lds_dwordx4 v[6:7], off
	s_waitcnt vmcnt(8)
	s_waitcnt lgkmcnt(0)
	s_setprio 1
	s_barrier
	v_mfma_f32_16x16x32_bf16 v[68:71], v[132:135], v[188:191], v[68:71]
	v_mfma_f32_16x16x32_bf16 v[60:63], v[140:143], v[188:191], v[60:63]
	v_mfma_f32_16x16x32_bf16 v[56:59], v[132:135], v[196:199], v[56:59]
	v_mfma_f32_16x16x32_bf16 v[52:55], v[140:143], v[196:199], v[52:55]
	v_mfma_f32_16x16x32_bf16 v[48:51], v[132:135], v[212:215], v[48:51]
	v_mfma_f32_16x16x32_bf16 v[44:47], v[140:143], v[212:215], v[44:47]
	v_mfma_f32_16x16x32_bf16 v[40:43], v[132:135], v[220:223], v[40:43]
	v_mfma_f32_16x16x32_bf16 v[36:39], v[140:143], v[220:223], v[36:39]
	v_mfma_f32_16x16x32_bf16 v[68:71], v[136:139], v[192:195], v[68:71]
	v_mfma_f32_16x16x32_bf16 v[60:63], v[144:147], v[192:195], v[60:63]
	v_mfma_f32_16x16x32_bf16 v[56:59], v[136:139], v[208:211], v[56:59]
	v_mfma_f32_16x16x32_bf16 v[52:55], v[144:147], v[208:211], v[52:55]
	v_mfma_f32_16x16x32_bf16 v[48:51], v[136:139], v[216:219], v[48:51]
	v_mfma_f32_16x16x32_bf16 v[44:47], v[144:147], v[216:219], v[44:47]
	v_mfma_f32_16x16x32_bf16 v[40:43], v[136:139], v[224:227], v[40:43]
	v_mfma_f32_16x16x32_bf16 v[36:39], v[144:147], v[224:227], v[36:39]
	v_mfma_f32_16x16x32_bf16 v[32:35], v[148:151], v[188:191], v[32:35]
	v_mfma_f32_16x16x32_bf16 v[28:31], v[156:159], v[188:191], v[28:31]
	v_mfma_f32_16x16x32_bf16 v[24:27], v[148:151], v[196:199], v[24:27]
	v_mfma_f32_16x16x32_bf16 v[20:23], v[156:159], v[196:199], v[20:23]
	v_mfma_f32_16x16x32_bf16 v[16:19], v[148:151], v[212:215], v[16:19]
	v_mfma_f32_16x16x32_bf16 v[12:15], v[156:159], v[212:215], v[12:15]
	v_mfma_f32_16x16x32_bf16 v[6:9], v[148:151], v[220:223], v[8:11]
	v_mfma_f32_16x16x32_bf16 v[2:5], v[156:159], v[220:223], v[2:5]
	v_mfma_f32_16x16x32_bf16 v[32:35], v[152:155], v[192:195], v[32:35]
	v_mfma_f32_16x16x32_bf16 v[28:31], v[184:187], v[192:195], v[28:31]
	v_mfma_f32_16x16x32_bf16 v[24:27], v[152:155], v[208:211], v[24:27]
	v_mfma_f32_16x16x32_bf16 v[20:23], v[184:187], v[208:211], v[20:23]
	v_mfma_f32_16x16x32_bf16 v[16:19], v[152:155], v[216:219], v[16:19]
	v_mfma_f32_16x16x32_bf16 v[12:15], v[184:187], v[216:219], v[12:15]
	v_mfma_f32_16x16x32_bf16 v[8:11], v[152:155], v[224:227], v[6:9]
	v_mfma_f32_16x16x32_bf16 v[4:7], v[184:187], v[224:227], v[2:5]
	s_barrier
	s_setprio 0
	s_add_u32 s29, s29, 0x10000
	s_addc_u32 s74, s74, 0
	s_add_u32 s16, s16, 0x10000
	s_addc_u32 s17, s17, 0
	s_cmp_ge_i32 s75, s39
	s_mov_b32 s72, s75
	s_cbranch_scc0 .LBB7_434

.LBB7_523:
	s_add_i32 s56, s42, 2
	s_add_u32 s29, s16, 0xfffc0080
	s_addc_u32 s37, s17, -1
	s_add_i32 s57, 0, 0x10000
	s_cmp_eq_u32 s84, s42
	s_cselect_b32 s45, s13, s37
	s_cselect_b32 s44, s15, s29
	v_add_u32_e32 v0, s57, v195
	s_cselect_b32 s43, s38, s49
	s_cselect_b32 s42, s39, s48
	s_add_i32 s29, 0, 0x14000
	ds_read_b128 v[130:133], v0
	ds_read_b128 v[150:153], v0 offset:1024
	ds_read_b128 v[154:157], v0 offset:2048
	ds_read_b128 v[158:161], v0 offset:3072
	v_add_u32_e32 v0, s29, v195
	ds_read_b128 v[174:177], v0
	ds_read_b128 v[178:181], v0 offset:1024
	ds_read_b128 v[182:185], v0 offset:2048
	ds_read_b128 v[186:189], v0 offset:3072
	v_lshl_add_u64 v[170:171], s[16:17], 0, v[146:147]
	s_add_i32 m0, s5, 0xc000
	ds_read_b128 v[190:193], v196
	ds_read_b128 v[204:207], v196 offset:1024
	ds_read_b128 v[208:211], v196 offset:2048
	ds_read_b128 v[212:215], v196 offset:3072
	ds_read_b128 v[216:219], v196 offset:4096
	ds_read_b128 v[220:223], v196 offset:5120
	ds_read_b128 v[224:227], v196 offset:6144
	ds_read_b128 v[228:231], v196 offset:7168
	global_load_lds_dwordx4 v[170:171], off
	v_lshl_add_u64 v[170:171], s[16:17], 0, v[148:149]
	s_add_i32 m0, s5, 0xe000
	s_nop 0
	global_load_lds_dwordx4 v[170:171], off
	s_waitcnt vmcnt(8)
	s_waitcnt lgkmcnt(0)
	s_setprio 1
	s_barrier
	v_mfma_f32_16x16x32_bf16 v[126:129], v[130:133], v[190:193], v[126:129]
	v_mfma_f32_16x16x32_bf16 v[122:125], v[154:157], v[190:193], v[122:125]
	v_mfma_f32_16x16x32_bf16 v[110:113], v[130:133], v[208:211], v[110:113]
	v_mfma_f32_16x16x32_bf16 v[106:109], v[154:157], v[208:211], v[106:109]
	v_mfma_f32_16x16x32_bf16 v[94:97], v[130:133], v[216:219], v[94:97]
	v_mfma_f32_16x16x32_bf16 v[90:93], v[154:157], v[216:219], v[90:93]
	v_mfma_f32_16x16x32_bf16 v[78:81], v[130:133], v[224:227], v[78:81]
	v_mfma_f32_16x16x32_bf16 v[74:77], v[154:157], v[224:227], v[74:77]
	v_mfma_f32_16x16x32_bf16 v[126:129], v[150:153], v[204:207], v[126:129]
	v_mfma_f32_16x16x32_bf16 v[122:125], v[158:161], v[204:207], v[122:125]
	v_mfma_f32_16x16x32_bf16 v[110:113], v[150:153], v[212:215], v[110:113]
	v_mfma_f32_16x16x32_bf16 v[106:109], v[158:161], v[212:215], v[106:109]
	v_mfma_f32_16x16x32_bf16 v[94:97], v[150:153], v[220:223], v[94:97]
	v_mfma_f32_16x16x32_bf16 v[90:93], v[158:161], v[220:223], v[90:93]
	v_mfma_f32_16x16x32_bf16 v[78:81], v[150:153], v[228:231], v[78:81]
	v_mfma_f32_16x16x32_bf16 v[74:77], v[158:161], v[228:231], v[74:77]
	v_mfma_f32_16x16x32_bf16 v[118:121], v[174:177], v[190:193], v[118:121]
	v_mfma_f32_16x16x32_bf16 v[114:117], v[182:185], v[190:193], v[114:117]
	v_mfma_f32_16x16x32_bf16 v[102:105], v[174:177], v[208:211], v[102:105]
	v_mfma_f32_16x16x32_bf16 v[98:101], v[182:185], v[208:211], v[98:101]
	v_mfma_f32_16x16x32_bf16 v[86:89], v[174:177], v[216:219], v[86:89]
	v_mfma_f32_16x16x32_bf16 v[82:85], v[182:185], v[216:219], v[82:85]
	v_mfma_f32_16x16x32_bf16 v[70:73], v[174:177], v[224:227], v[70:73]
	v_mfma_f32_16x16x32_bf16 v[66:69], v[182:185], v[224:227], v[66:69]
	v_mfma_f32_16x16x32_bf16 v[118:121], v[178:181], v[204:207], v[118:121]
	v_mfma_f32_16x16x32_bf16 v[114:117], v[186:189], v[204:207], v[114:117]
	v_mfma_f32_16x16x32_bf16 v[102:105], v[178:181], v[212:215], v[102:105]
	v_mfma_f32_16x16x32_bf16 v[98:101], v[186:189], v[212:215], v[98:101]
	v_mfma_f32_16x16x32_bf16 v[86:89], v[178:181], v[220:223], v[86:89]
	v_mfma_f32_16x16x32_bf16 v[82:85], v[186:189], v[220:223], v[82:85]
	v_mfma_f32_16x16x32_bf16 v[70:73], v[178:181], v[228:231], v[70:73]
	v_mfma_f32_16x16x32_bf16 v[66:69], v[186:189], v[228:231], v[66:69]
	s_barrier
	s_setprio 0
	s_add_i32 s37, s57, s4
	v_lshl_add_u64 v[170:171], s[42:43], 0, v[138:139]
	s_mov_b32 m0, s37
	ds_read_b128 v[190:193], v196 offset:16384
	ds_read_b128 v[204:207], v196 offset:17408
	ds_read_b128 v[208:211], v196 offset:18432
	ds_read_b128 v[212:215], v196 offset:19456
	ds_read_b128 v[216:219], v196 offset:20480
	ds_read_b128 v[220:223], v196 offset:21504
	ds_read_b128 v[224:227], v196 offset:22528
	ds_read_b128 v[228:231], v196 offset:23552
	global_load_lds_dwordx4 v[170:171], off
	s_add_i32 m0, s37, 0x2000
	s_add_u32 s74, s42, 0x40000
	v_lshl_add_u64 v[172:173], s[42:43], 0, v[134:135]
	s_addc_u32 s75, s43, 0
	s_add_i32 s29, s29, s4
	global_load_lds_dwordx4 v[172:173], off
	v_lshl_add_u64 v[198:199], s[74:75], 0, v[138:139]
	s_mov_b32 m0, s29
	v_lshl_add_u64 v[232:233], s[44:45], 0, v[136:137]
	global_load_lds_dwordx4 v[198:199], off
	v_lshl_add_u64 v[198:199], s[74:75], 0, v[134:135]
	s_add_i32 m0, s29, 0x2000
	s_nop 0
	global_load_lds_dwordx4 v[198:199], off
	v_lshl_add_u64 v[198:199], s[44:45], 0, v[140:141]
	s_mov_b32 m0, s5
	s_nop 0
	global_load_lds_dwordx4 v[198:199], off
	s_mov_b32 m0, s20
	s_nop 0
	global_load_lds_dwordx4 v[232:233], off
	s_waitcnt vmcnt(8)
	s_waitcnt lgkmcnt(0)
	s_setprio 1
	s_barrier
	v_mfma_f32_16x16x32_bf16 v[62:65], v[130:133], v[190:193], v[62:65]
	v_mfma_f32_16x16x32_bf16 v[58:61], v[154:157], v[190:193], v[58:61]
	v_mfma_f32_16x16x32_bf16 v[46:49], v[130:133], v[208:211], v[46:49]
	v_mfma_f32_16x16x32_bf16 v[42:45], v[154:157], v[208:211], v[42:45]
	v_mfma_f32_16x16x32_bf16 v[30:33], v[130:133], v[216:219], v[30:33]
	v_mfma_f32_16x16x32_bf16 v[26:29], v[154:157], v[216:219], v[26:29]
	v_mfma_f32_16x16x32_bf16 v[14:17], v[130:133], v[224:227], v[14:17]
	v_mfma_f32_16x16x32_bf16 v[10:13], v[154:157], v[224:227], v[10:13]
	v_mfma_f32_16x16x32_bf16 v[62:65], v[150:153], v[204:207], v[62:65]
	v_mfma_f32_16x16x32_bf16 v[58:61], v[158:161], v[204:207], v[58:61]
	v_mfma_f32_16x16x32_bf16 v[46:49], v[150:153], v[212:215], v[46:49]
	v_mfma_f32_16x16x32_bf16 v[42:45], v[158:161], v[212:215], v[42:45]
	v_mfma_f32_16x16x32_bf16 v[30:33], v[150:153], v[220:223], v[30:33]
	v_mfma_f32_16x16x32_bf16 v[26:29], v[158:161], v[220:223], v[26:29]
	v_mfma_f32_16x16x32_bf16 v[14:17], v[150:153], v[228:231], v[14:17]
	v_mfma_f32_16x16x32_bf16 v[10:13], v[158:161], v[228:231], v[10:13]
	v_mfma_f32_16x16x32_bf16 v[54:57], v[174:177], v[190:193], v[54:57]
	v_mfma_f32_16x16x32_bf16 v[50:53], v[182:185], v[190:193], v[50:53]
	v_mfma_f32_16x16x32_bf16 v[38:41], v[174:177], v[208:211], v[38:41]
	v_mfma_f32_16x16x32_bf16 v[34:37], v[182:185], v[208:211], v[34:37]
	v_mfma_f32_16x16x32_bf16 v[22:25], v[174:177], v[216:219], v[22:25]
	v_mfma_f32_16x16x32_bf16 v[18:21], v[182:185], v[216:219], v[18:21]
	v_mfma_f32_16x16x32_bf16 v[6:9], v[174:177], v[224:227], v[6:9]
	v_mfma_f32_16x16x32_bf16 v[2:5], v[182:185], v[224:227], v[2:5]
	v_mfma_f32_16x16x32_bf16 v[54:57], v[178:181], v[204:207], v[54:57]
	v_mfma_f32_16x16x32_bf16 v[50:53], v[186:189], v[204:207], v[50:53]
	v_mfma_f32_16x16x32_bf16 v[38:41], v[178:181], v[212:215], v[38:41]
	v_mfma_f32_16x16x32_bf16 v[34:37], v[186:189], v[212:215], v[34:37]
	v_mfma_f32_16x16x32_bf16 v[22:25], v[178:181], v[220:223], v[22:25]
	v_mfma_f32_16x16x32_bf16 v[18:21], v[186:189], v[220:223], v[18:21]
	v_mfma_f32_16x16x32_bf16 v[6:9], v[178:181], v[228:231], v[6:9]
	v_mfma_f32_16x16x32_bf16 v[2:5], v[186:189], v[228:231], v[2:5]
	s_barrier
	s_setprio 0
	s_add_i32 s29, 0, 0x18000
	v_add_u32_e32 v0, s29, v195
	s_add_i32 s37, 0, 0x1c000
	ds_read_b128 v[130:133], v0
	ds_read_b128 v[150:153], v0 offset:1024
	ds_read_b128 v[154:157], v0 offset:2048
	ds_read_b128 v[158:161], v0 offset:3072
	v_add_u32_e32 v0, s37, v195
	ds_read_b128 v[174:177], v0
	ds_read_b128 v[178:181], v0 offset:1024
	ds_read_b128 v[182:185], v0 offset:2048
	ds_read_b128 v[186:189], v0 offset:3072
	s_add_u32 s44, s44, 0x40000
	s_addc_u32 s45, s45, 0
	s_mov_b32 m0, s22
	v_lshl_add_u64 v[234:235], s[44:45], 0, v[140:141]
	ds_read_b128 v[190:193], v196 offset:32768
	ds_read_b128 v[204:207], v196 offset:33792
	ds_read_b128 v[208:211], v196 offset:34816
	ds_read_b128 v[212:215], v196 offset:35840
	ds_read_b128 v[216:219], v196 offset:36864
	ds_read_b128 v[220:223], v196 offset:37888
	ds_read_b128 v[224:227], v196 offset:38912
	ds_read_b128 v[228:231], v196 offset:39936
	global_load_lds_dwordx4 v[234:235], off
	v_lshl_add_u64 v[234:235], s[44:45], 0, v[136:137]
	s_mov_b32 m0, s23
	s_nop 0
	global_load_lds_dwordx4 v[234:235], off
	s_waitcnt vmcnt(8)
	s_waitcnt lgkmcnt(0)
	s_setprio 1
	s_barrier
	v_mfma_f32_16x16x32_bf16 v[126:129], v[130:133], v[190:193], v[126:129]
	v_mfma_f32_16x16x32_bf16 v[122:125], v[154:157], v[190:193], v[122:125]
	v_mfma_f32_16x16x32_bf16 v[110:113], v[130:133], v[208:211], v[110:113]
	v_mfma_f32_16x16x32_bf16 v[106:109], v[154:157], v[208:211], v[106:109]
	v_mfma_f32_16x16x32_bf16 v[94:97], v[130:133], v[216:219], v[94:97]
	v_mfma_f32_16x16x32_bf16 v[90:93], v[154:157], v[216:219], v[90:93]
	v_mfma_f32_16x16x32_bf16 v[78:81], v[130:133], v[224:227], v[78:81]
	v_mfma_f32_16x16x32_bf16 v[74:77], v[154:157], v[224:227], v[74:77]
	v_mfma_f32_16x16x32_bf16 v[126:129], v[150:153], v[204:207], v[126:129]
	v_mfma_f32_16x16x32_bf16 v[122:125], v[158:161], v[204:207], v[122:125]
	v_mfma_f32_16x16x32_bf16 v[110:113], v[150:153], v[212:215], v[110:113]
	v_mfma_f32_16x16x32_bf16 v[106:109], v[158:161], v[212:215], v[106:109]
	v_mfma_f32_16x16x32_bf16 v[94:97], v[150:153], v[220:223], v[94:97]
	v_mfma_f32_16x16x32_bf16 v[90:93], v[158:161], v[220:223], v[90:93]
	v_mfma_f32_16x16x32_bf16 v[78:81], v[150:153], v[228:231], v[78:81]
	v_mfma_f32_16x16x32_bf16 v[74:77], v[158:161], v[228:231], v[74:77]
	v_mfma_f32_16x16x32_bf16 v[118:121], v[174:177], v[190:193], v[118:121]
	v_mfma_f32_16x16x32_bf16 v[114:117], v[182:185], v[190:193], v[114:117]
	v_mfma_f32_16x16x32_bf16 v[102:105], v[174:177], v[208:211], v[102:105]
	v_mfma_f32_16x16x32_bf16 v[98:101], v[182:185], v[208:211], v[98:101]
	v_mfma_f32_16x16x32_bf16 v[86:89], v[174:177], v[216:219], v[86:89]
	v_mfma_f32_16x16x32_bf16 v[82:85], v[182:185], v[216:219], v[82:85]
	v_mfma_f32_16x16x32_bf16 v[70:73], v[174:177], v[224:227], v[70:73]
	v_mfma_f32_16x16x32_bf16 v[66:69], v[182:185], v[224:227], v[66:69]
	v_mfma_f32_16x16x32_bf16 v[118:121], v[178:181], v[204:207], v[118:121]
	v_mfma_f32_16x16x32_bf16 v[114:117], v[186:189], v[204:207], v[114:117]
	v_mfma_f32_16x16x32_bf16 v[102:105], v[178:181], v[212:215], v[102:105]
	v_mfma_f32_16x16x32_bf16 v[98:101], v[186:189], v[212:215], v[98:101]
	v_mfma_f32_16x16x32_bf16 v[86:89], v[178:181], v[220:223], v[86:89]
	v_mfma_f32_16x16x32_bf16 v[82:85], v[186:189], v[220:223], v[82:85]
	v_mfma_f32_16x16x32_bf16 v[70:73], v[178:181], v[228:231], v[70:73]
	v_mfma_f32_16x16x32_bf16 v[66:69], v[186:189], v[228:231], v[66:69]
	s_barrier
	s_setprio 0
	s_add_i32 s29, s29, s4
	v_lshl_add_u64 v[170:171], v[170:171], 0, s[24:25]
	s_mov_b32 m0, s29
	ds_read_b128 v[190:193], v196 offset:49152
	ds_read_b128 v[204:207], v196 offset:50176
	ds_read_b128 v[208:211], v196 offset:51200
	ds_read_b128 v[212:215], v196 offset:52224
	ds_read_b128 v[216:219], v196 offset:53248
	ds_read_b128 v[220:223], v196 offset:54272
	ds_read_b128 v[224:227], v196 offset:55296
	ds_read_b128 v[228:231], v196 offset:56320
	global_load_lds_dwordx4 v[170:171], off
	s_add_i32 m0, s29, 0x2000
	s_add_u32 s42, s42, 0x40080
	v_lshl_add_u64 v[170:171], v[172:173], 0, s[24:25]
	s_addc_u32 s43, s43, 0
	s_add_i32 s29, s37, s4
	global_load_lds_dwordx4 v[170:171], off
	v_lshl_add_u64 v[170:171], s[42:43], 0, v[138:139]
	s_mov_b32 m0, s29
	s_nop 0
	global_load_lds_dwordx4 v[170:171], off
	v_lshl_add_u64 v[170:171], s[42:43], 0, v[134:135]
	s_add_i32 m0, s29, 0x2000
	s_nop 0
	global_load_lds_dwordx4 v[170:171], off
	v_lshl_add_u64 v[170:171], v[198:199], 0, s[24:25]
	s_mov_b32 m0, s33
	s_nop 0
	global_load_lds_dwordx4 v[170:171], off
	v_lshl_add_u64 v[170:171], v[232:233], 0, s[24:25]
	s_mov_b32 m0, s72
	s_nop 0
	global_load_lds_dwordx4 v[170:171], off
	s_waitcnt vmcnt(8)
	s_waitcnt lgkmcnt(0)
	s_setprio 1
	s_barrier
	v_mfma_f32_16x16x32_bf16 v[62:65], v[130:133], v[190:193], v[62:65]
	v_mfma_f32_16x16x32_bf16 v[58:61], v[154:157], v[190:193], v[58:61]
	v_mfma_f32_16x16x32_bf16 v[46:49], v[130:133], v[208:211], v[46:49]
	v_mfma_f32_16x16x32_bf16 v[42:45], v[154:157], v[208:211], v[42:45]
	v_mfma_f32_16x16x32_bf16 v[30:33], v[130:133], v[216:219], v[30:33]
	v_mfma_f32_16x16x32_bf16 v[26:29], v[154:157], v[216:219], v[26:29]
	v_mfma_f32_16x16x32_bf16 v[14:17], v[130:133], v[224:227], v[14:17]
	v_mfma_f32_16x16x32_bf16 v[10:13], v[154:157], v[224:227], v[10:13]
	v_mfma_f32_16x16x32_bf16 v[62:65], v[150:153], v[204:207], v[62:65]
	v_mfma_f32_16x16x32_bf16 v[58:61], v[158:161], v[204:207], v[58:61]
	v_mfma_f32_16x16x32_bf16 v[46:49], v[150:153], v[212:215], v[46:49]
	v_mfma_f32_16x16x32_bf16 v[42:45], v[158:161], v[212:215], v[42:45]
	v_mfma_f32_16x16x32_bf16 v[30:33], v[150:153], v[220:223], v[30:33]
	v_mfma_f32_16x16x32_bf16 v[26:29], v[158:161], v[220:223], v[26:29]
	v_mfma_f32_16x16x32_bf16 v[14:17], v[150:153], v[228:231], v[14:17]
	v_mfma_f32_16x16x32_bf16 v[10:13], v[158:161], v[228:231], v[10:13]
	v_mfma_f32_16x16x32_bf16 v[54:57], v[174:177], v[190:193], v[54:57]
	v_mfma_f32_16x16x32_bf16 v[50:53], v[182:185], v[190:193], v[50:53]
	v_mfma_f32_16x16x32_bf16 v[38:41], v[174:177], v[208:211], v[38:41]
	v_mfma_f32_16x16x32_bf16 v[34:37], v[182:185], v[208:211], v[34:37]
	v_mfma_f32_16x16x32_bf16 v[22:25], v[174:177], v[216:219], v[22:25]
	v_mfma_f32_16x16x32_bf16 v[18:21], v[182:185], v[216:219], v[18:21]
	v_mfma_f32_16x16x32_bf16 v[6:9], v[174:177], v[224:227], v[6:9]
	v_mfma_f32_16x16x32_bf16 v[2:5], v[182:185], v[224:227], v[2:5]
	v_mfma_f32_16x16x32_bf16 v[54:57], v[178:181], v[204:207], v[54:57]
	v_mfma_f32_16x16x32_bf16 v[50:53], v[186:189], v[204:207], v[50:53]
	v_mfma_f32_16x16x32_bf16 v[38:41], v[178:181], v[212:215], v[38:41]
	v_mfma_f32_16x16x32_bf16 v[34:37], v[186:189], v[212:215], v[34:37]
	v_mfma_f32_16x16x32_bf16 v[22:25], v[178:181], v[220:223], v[22:25]
	v_mfma_f32_16x16x32_bf16 v[18:21], v[186:189], v[220:223], v[18:21]
	v_mfma_f32_16x16x32_bf16 v[6:9], v[178:181], v[228:231], v[6:9]
	v_mfma_f32_16x16x32_bf16 v[2:5], v[186:189], v[228:231], v[2:5]
	s_barrier
	s_setprio 0
	s_add_u32 s16, s16, 0x100
	s_addc_u32 s17, s17, 0
	s_add_u32 s48, s48, 0x100
	s_addc_u32 s49, s49, 0
	s_cmp_ge_i32 s56, s3
	s_mov_b32 s42, s56
	s_cbranch_scc0 .LBB7_523
	s_mov_b32 s56, s61
	s_and_b64 vcc, exec, s[6:7]
	s_cbranch_vccz .LBB7_526

.LBB7_676:
	s_add_i32 s29, s37, 2
	s_add_u32 s44, s42, 0x100
	s_addc_u32 s45, s43, 0
	s_add_i32 s74, 0, 0x10000
	v_add_u32_e32 v81, s74, v79
	ds_read_b128 v[82:85], v81
	ds_read_b128 v[86:89], v81 offset:1024
	ds_read_b128 v[90:93], v81 offset:2048
	ds_read_b128 v[94:97], v81 offset:3072
	s_cmp_eq_u32 s53, s37
	s_cselect_b32 s51, s56, s45
	s_cselect_b32 s50, s57, s44
	s_cselect_b32 s49, s72, s85
	s_cselect_b32 s48, s73, s84
	v_lshl_add_u64 v[130:131], s[42:43], 0, v[74:75]
	s_add_i32 m0, s5, 0xc000
	ds_read_b128 v[98:101], v80
	ds_read_b128 v[102:105], v80 offset:1024
	ds_read_b128 v[106:109], v80 offset:2048
	ds_read_b128 v[110:113], v80 offset:3072
	ds_read_b128 v[114:117], v80 offset:4096
	ds_read_b128 v[118:121], v80 offset:5120
	ds_read_b128 v[122:125], v80 offset:6144
	ds_read_b128 v[126:129], v80 offset:7168
	global_load_lds_dwordx4 v[130:131], off
	v_lshl_add_u64 v[130:131], s[42:43], 0, v[76:77]
	s_add_i32 m0, s5, 0xe000
	s_nop 0
	global_load_lds_dwordx4 v[130:131], off
	s_waitcnt vmcnt(8)
	s_waitcnt lgkmcnt(0)
	s_setprio 1
	s_barrier
	v_mfma_f32_16x16x32_bf16 v[62:65], v[82:85], v[98:101], v[62:65]
	v_mfma_f32_16x16x32_bf16 v[58:61], v[90:93], v[98:101], v[58:61]
	v_mfma_f32_16x16x32_bf16 v[54:57], v[82:85], v[106:109], v[54:57]
	v_mfma_f32_16x16x32_bf16 v[50:53], v[90:93], v[106:109], v[50:53]
	v_mfma_f32_16x16x32_bf16 v[46:49], v[82:85], v[114:117], v[46:49]
	v_mfma_f32_16x16x32_bf16 v[42:45], v[90:93], v[114:117], v[42:45]
	v_mfma_f32_16x16x32_bf16 v[38:41], v[82:85], v[122:125], v[38:41]
	v_mfma_f32_16x16x32_bf16 v[34:37], v[90:93], v[122:125], v[34:37]
	v_mfma_f32_16x16x32_bf16 v[62:65], v[86:89], v[102:105], v[62:65]
	v_mfma_f32_16x16x32_bf16 v[58:61], v[94:97], v[102:105], v[58:61]
	v_mfma_f32_16x16x32_bf16 v[54:57], v[86:89], v[110:113], v[54:57]
	v_mfma_f32_16x16x32_bf16 v[50:53], v[94:97], v[110:113], v[50:53]
	v_mfma_f32_16x16x32_bf16 v[46:49], v[86:89], v[118:121], v[46:49]
	v_mfma_f32_16x16x32_bf16 v[42:45], v[94:97], v[118:121], v[42:45]
	v_mfma_f32_16x16x32_bf16 v[38:41], v[86:89], v[126:129], v[38:41]
	v_mfma_f32_16x16x32_bf16 v[34:37], v[94:97], v[126:129], v[34:37]
	s_barrier
	s_setprio 0
	s_add_i32 s37, s74, s4
	v_lshl_add_u64 v[130:131], s[48:49], 0, v[70:71]
	s_mov_b32 m0, s37
	ds_read_b128 v[98:101], v80 offset:16384
	ds_read_b128 v[102:105], v80 offset:17408
	ds_read_b128 v[106:109], v80 offset:18432
	ds_read_b128 v[110:113], v80 offset:19456
	ds_read_b128 v[114:117], v80 offset:20480
	ds_read_b128 v[118:121], v80 offset:21504
	ds_read_b128 v[122:125], v80 offset:22528
	ds_read_b128 v[126:129], v80 offset:23552
	global_load_lds_dwordx4 v[130:131], off
	s_add_i32 m0, s37, 0x2000
	s_add_u32 s42, s48, 0x20000
	v_lshl_add_u64 v[132:133], s[48:49], 0, v[66:67]
	s_addc_u32 s43, s49, 0
	global_load_lds_dwordx4 v[132:133], off
	v_lshl_add_u64 v[134:135], s[42:43], 0, v[70:71]
	s_mov_b32 m0, s10
	v_lshl_add_u64 v[136:137], s[50:51], 0, v[68:69]
	global_load_lds_dwordx4 v[134:135], off
	v_lshl_add_u64 v[134:135], s[42:43], 0, v[66:67]
	s_mov_b32 m0, s20
	s_nop 0
	global_load_lds_dwordx4 v[134:135], off
	v_lshl_add_u64 v[134:135], s[50:51], 0, v[0:1]
	s_mov_b32 m0, s5
	s_nop 0
	global_load_lds_dwordx4 v[134:135], off
	s_mov_b32 m0, s22
	s_nop 0
	global_load_lds_dwordx4 v[136:137], off
	s_waitcnt vmcnt(8)
	s_waitcnt lgkmcnt(0)
	s_setprio 1
	s_barrier
	v_mfma_f32_16x16x32_bf16 v[30:33], v[82:85], v[98:101], v[30:33]
	v_mfma_f32_16x16x32_bf16 v[26:29], v[90:93], v[98:101], v[26:29]
	v_mfma_f32_16x16x32_bf16 v[22:25], v[82:85], v[106:109], v[22:25]
	v_mfma_f32_16x16x32_bf16 v[18:21], v[90:93], v[106:109], v[18:21]
	v_mfma_f32_16x16x32_bf16 v[14:17], v[82:85], v[114:117], v[14:17]
	v_mfma_f32_16x16x32_bf16 v[10:13], v[90:93], v[114:117], v[10:13]
	v_mfma_f32_16x16x32_bf16 v[6:9], v[82:85], v[122:125], v[6:9]
	v_mfma_f32_16x16x32_bf16 v[2:5], v[90:93], v[122:125], v[2:5]
	v_mfma_f32_16x16x32_bf16 v[30:33], v[86:89], v[102:105], v[30:33]
	v_mfma_f32_16x16x32_bf16 v[26:29], v[94:97], v[102:105], v[26:29]
	v_mfma_f32_16x16x32_bf16 v[22:25], v[86:89], v[110:113], v[22:25]
	v_mfma_f32_16x16x32_bf16 v[18:21], v[94:97], v[110:113], v[18:21]
	v_mfma_f32_16x16x32_bf16 v[14:17], v[86:89], v[118:121], v[14:17]
	v_mfma_f32_16x16x32_bf16 v[10:13], v[94:97], v[118:121], v[10:13]
	v_mfma_f32_16x16x32_bf16 v[6:9], v[86:89], v[126:129], v[6:9]
	v_mfma_f32_16x16x32_bf16 v[2:5], v[94:97], v[126:129], v[2:5]
	s_barrier
	s_setprio 0
	s_add_i32 s37, 0, 0x18000
	v_add_u32_e32 v81, s37, v79
	ds_read_b128 v[82:85], v81
	ds_read_b128 v[86:89], v81 offset:1024
	ds_read_b128 v[90:93], v81 offset:2048
	ds_read_b128 v[94:97], v81 offset:3072
	s_add_u32 s42, s50, 0x28000
	s_addc_u32 s43, s51, 0
	s_mov_b32 m0, s23
	v_lshl_add_u64 v[138:139], s[42:43], 0, v[0:1]
	ds_read_b128 v[98:101], v80 offset:32768
	ds_read_b128 v[102:105], v80 offset:33792
	ds_read_b128 v[106:109], v80 offset:34816
	ds_read_b128 v[110:113], v80 offset:35840
	ds_read_b128 v[114:117], v80 offset:36864
	ds_read_b128 v[118:121], v80 offset:37888
	ds_read_b128 v[122:125], v80 offset:38912
	ds_read_b128 v[126:129], v80 offset:39936
	global_load_lds_dwordx4 v[138:139], off
	v_lshl_add_u64 v[138:139], s[42:43], 0, v[68:69]
	s_mov_b32 m0, s28
	s_nop 0
	global_load_lds_dwordx4 v[138:139], off
	s_waitcnt vmcnt(8)
	s_waitcnt lgkmcnt(0)
	s_setprio 1
	s_barrier
	v_mfma_f32_16x16x32_bf16 v[62:65], v[82:85], v[98:101], v[62:65]
	v_mfma_f32_16x16x32_bf16 v[58:61], v[90:93], v[98:101], v[58:61]
	v_mfma_f32_16x16x32_bf16 v[54:57], v[82:85], v[106:109], v[54:57]
	v_mfma_f32_16x16x32_bf16 v[50:53], v[90:93], v[106:109], v[50:53]
	v_mfma_f32_16x16x32_bf16 v[46:49], v[82:85], v[114:117], v[46:49]
	v_mfma_f32_16x16x32_bf16 v[42:45], v[90:93], v[114:117], v[42:45]
	v_mfma_f32_16x16x32_bf16 v[38:41], v[82:85], v[122:125], v[38:41]
	v_mfma_f32_16x16x32_bf16 v[34:37], v[90:93], v[122:125], v[34:37]
	v_mfma_f32_16x16x32_bf16 v[62:65], v[86:89], v[102:105], v[62:65]
	v_mfma_f32_16x16x32_bf16 v[58:61], v[94:97], v[102:105], v[58:61]
	v_mfma_f32_16x16x32_bf16 v[54:57], v[86:89], v[110:113], v[54:57]
	v_mfma_f32_16x16x32_bf16 v[50:53], v[94:97], v[110:113], v[50:53]
	v_mfma_f32_16x16x32_bf16 v[46:49], v[86:89], v[118:121], v[46:49]
	v_mfma_f32_16x16x32_bf16 v[42:45], v[94:97], v[118:121], v[42:45]
	v_mfma_f32_16x16x32_bf16 v[38:41], v[86:89], v[126:129], v[38:41]
	v_mfma_f32_16x16x32_bf16 v[34:37], v[94:97], v[126:129], v[34:37]
	s_barrier
	s_setprio 0
	s_add_i32 s37, s37, s4
	v_lshl_add_u64 v[130:131], v[130:131], 0, s[24:25]
	s_mov_b32 m0, s37
	ds_read_b128 v[98:101], v80 offset:49152
	ds_read_b128 v[102:105], v80 offset:50176
	ds_read_b128 v[106:109], v80 offset:51200
	ds_read_b128 v[110:113], v80 offset:52224
	ds_read_b128 v[114:117], v80 offset:53248
	ds_read_b128 v[118:121], v80 offset:54272
	ds_read_b128 v[122:125], v80 offset:55296
	ds_read_b128 v[126:129], v80 offset:56320
	global_load_lds_dwordx4 v[130:131], off
	s_add_i32 m0, s37, 0x2000
	s_add_u32 s42, s48, 0x20080
	v_lshl_add_u64 v[130:131], v[132:133], 0, s[24:25]
	s_addc_u32 s43, s49, 0
	global_load_lds_dwordx4 v[130:131], off
	v_lshl_add_u64 v[130:131], s[42:43], 0, v[70:71]
	s_mov_b32 m0, s38
	s_nop 0
	global_load_lds_dwordx4 v[130:131], off
	v_lshl_add_u64 v[130:131], s[42:43], 0, v[66:67]
	s_mov_b32 m0, s39
	s_nop 0
	global_load_lds_dwordx4 v[130:131], off
	v_lshl_add_u64 v[130:131], v[134:135], 0, s[24:25]
	s_mov_b32 m0, s31
	s_nop 0
	global_load_lds_dwordx4 v[130:131], off
	v_lshl_add_u64 v[130:131], v[136:137], 0, s[24:25]
	s_mov_b32 m0, s33
	s_nop 0
	global_load_lds_dwordx4 v[130:131], off
	s_waitcnt vmcnt(8)
	s_waitcnt lgkmcnt(0)
	s_setprio 1
	s_barrier
	v_mfma_f32_16x16x32_bf16 v[30:33], v[82:85], v[98:101], v[30:33]
	v_mfma_f32_16x16x32_bf16 v[26:29], v[90:93], v[98:101], v[26:29]
	v_mfma_f32_16x16x32_bf16 v[22:25], v[82:85], v[106:109], v[22:25]
	v_mfma_f32_16x16x32_bf16 v[18:21], v[90:93], v[106:109], v[18:21]
	v_mfma_f32_16x16x32_bf16 v[14:17], v[82:85], v[114:117], v[14:17]
	v_mfma_f32_16x16x32_bf16 v[10:13], v[90:93], v[114:117], v[10:13]
	v_mfma_f32_16x16x32_bf16 v[6:9], v[82:85], v[122:125], v[6:9]
	v_mfma_f32_16x16x32_bf16 v[2:5], v[90:93], v[122:125], v[2:5]
	v_mfma_f32_16x16x32_bf16 v[30:33], v[86:89], v[102:105], v[30:33]
	v_mfma_f32_16x16x32_bf16 v[26:29], v[94:97], v[102:105], v[26:29]
	v_mfma_f32_16x16x32_bf16 v[22:25], v[86:89], v[110:113], v[22:25]
	v_mfma_f32_16x16x32_bf16 v[18:21], v[94:97], v[110:113], v[18:21]
	v_mfma_f32_16x16x32_bf16 v[14:17], v[86:89], v[118:121], v[14:17]
	v_mfma_f32_16x16x32_bf16 v[10:13], v[94:97], v[118:121], v[10:13]
	v_mfma_f32_16x16x32_bf16 v[6:9], v[86:89], v[126:129], v[6:9]
	v_mfma_f32_16x16x32_bf16 v[2:5], v[94:97], v[126:129], v[2:5]
	s_barrier
	s_setprio 0
	s_add_u32 s84, s84, 0x100
	s_addc_u32 s85, s85, 0
	s_cmp_ge_i32 s29, s3
	s_mov_b64 s[42:43], s[44:45]
	s_mov_b32 s37, s29
	s_cbranch_scc0 .LBB7_676
	s_mov_b32 s56, s61
	s_and_b64 vcc, exec, s[6:7]
	s_cbranch_vccz .LBB7_679

.LBB7_886:
	s_add_i32 s37, s44, 2
	s_add_u32 s42, s16, 0x100
	s_addc_u32 s43, s17, 0
	s_add_i32 s29, 0, 0x10000
	s_cmp_eq_u32 s57, s44
	s_cselect_b32 s49, s39, s43
	s_cselect_b32 s48, s54, s42
	s_cselect_b32 s45, s55, s73
	s_cselect_b32 s44, s56, s72
	s_add_i32 s74, 0, 0x14000
	v_add_u32_e32 v142, s29, v193
	v_add_u32_e32 v158, s74, v193
	ds_read_b128 v[74:77], v142
	ds_read_b128 v[78:81], v142 offset:1024
	ds_read_b128 v[138:141], v142 offset:2048
	ds_read_b128 v[142:145], v142 offset:3072
	ds_read_b128 v[146:149], v158
	ds_read_b128 v[150:153], v158 offset:1024
	ds_read_b128 v[154:157], v158 offset:2048
	ds_read_b128 v[158:161], v158 offset:3072
	v_lshl_add_u64 v[170:171], s[16:17], 0, v[184:185]
	s_add_i32 m0, s5, 0xc000
	ds_read_b128 v[188:191], v195
	ds_read_b128 v[196:199], v195 offset:1024
	ds_read_b128 v[204:207], v195 offset:2048
	ds_read_b128 v[208:211], v195 offset:3072
	ds_read_b128 v[212:215], v195 offset:4096
	ds_read_b128 v[216:219], v195 offset:5120
	ds_read_b128 v[220:223], v195 offset:6144
	ds_read_b128 v[224:227], v195 offset:7168
	global_load_lds_dwordx4 v[170:171], off
	v_lshl_add_u64 v[170:171], s[16:17], 0, v[186:187]
	s_add_i32 m0, s5, 0xe000
	s_nop 0
	global_load_lds_dwordx4 v[170:171], off
	s_waitcnt vmcnt(8)
	s_waitcnt lgkmcnt(0)
	s_setprio 1
	s_barrier
	v_mfma_f32_16x16x32_bf16 v[134:137], v[74:77], v[188:191], v[134:137]
	v_mfma_f32_16x16x32_bf16 v[130:133], v[138:141], v[188:191], v[130:133]
	v_mfma_f32_16x16x32_bf16 v[118:121], v[74:77], v[204:207], v[118:121]
	v_mfma_f32_16x16x32_bf16 v[114:117], v[138:141], v[204:207], v[114:117]
	v_mfma_f32_16x16x32_bf16 v[102:105], v[74:77], v[212:215], v[102:105]
	v_mfma_f32_16x16x32_bf16 v[98:101], v[138:141], v[212:215], v[98:101]
	v_mfma_f32_16x16x32_bf16 v[86:89], v[74:77], v[220:223], v[86:89]
	v_mfma_f32_16x16x32_bf16 v[82:85], v[138:141], v[220:223], v[82:85]
	v_mfma_f32_16x16x32_bf16 v[134:137], v[78:81], v[196:199], v[134:137]
	v_mfma_f32_16x16x32_bf16 v[130:133], v[142:145], v[196:199], v[130:133]
	v_mfma_f32_16x16x32_bf16 v[118:121], v[78:81], v[208:211], v[118:121]
	v_mfma_f32_16x16x32_bf16 v[114:117], v[142:145], v[208:211], v[114:117]
	v_mfma_f32_16x16x32_bf16 v[102:105], v[78:81], v[216:219], v[102:105]
	v_mfma_f32_16x16x32_bf16 v[98:101], v[142:145], v[216:219], v[98:101]
	v_mfma_f32_16x16x32_bf16 v[86:89], v[78:81], v[224:227], v[86:89]
	v_mfma_f32_16x16x32_bf16 v[82:85], v[142:145], v[224:227], v[82:85]
	v_mfma_f32_16x16x32_bf16 v[126:129], v[146:149], v[188:191], v[126:129]
	v_mfma_f32_16x16x32_bf16 v[122:125], v[154:157], v[188:191], v[122:125]
	v_mfma_f32_16x16x32_bf16 v[110:113], v[146:149], v[204:207], v[110:113]
	v_mfma_f32_16x16x32_bf16 v[106:109], v[154:157], v[204:207], v[106:109]
	v_mfma_f32_16x16x32_bf16 v[94:97], v[146:149], v[212:215], v[94:97]
	v_mfma_f32_16x16x32_bf16 v[90:93], v[154:157], v[212:215], v[90:93]
	v_mfma_f32_16x16x32_bf16 v[70:73], v[146:149], v[220:223], v[70:73]
	v_mfma_f32_16x16x32_bf16 v[66:69], v[154:157], v[220:223], v[66:69]
	v_mfma_f32_16x16x32_bf16 v[126:129], v[150:153], v[196:199], v[126:129]
	v_mfma_f32_16x16x32_bf16 v[122:125], v[158:161], v[196:199], v[122:125]
	v_mfma_f32_16x16x32_bf16 v[110:113], v[150:153], v[208:211], v[110:113]
	v_mfma_f32_16x16x32_bf16 v[106:109], v[158:161], v[208:211], v[106:109]
	v_mfma_f32_16x16x32_bf16 v[94:97], v[150:153], v[216:219], v[94:97]
	v_mfma_f32_16x16x32_bf16 v[90:93], v[158:161], v[216:219], v[90:93]
	v_mfma_f32_16x16x32_bf16 v[70:73], v[150:153], v[224:227], v[70:73]
	v_mfma_f32_16x16x32_bf16 v[66:69], v[158:161], v[224:227], v[66:69]
	s_barrier
	s_setprio 0
	s_add_i32 s16, s29, s4
	v_lshl_add_u64 v[170:171], s[44:45], 0, v[178:179]
	s_mov_b32 m0, s16
	ds_read_b128 v[188:191], v195 offset:16384
	ds_read_b128 v[196:199], v195 offset:17408
	ds_read_b128 v[204:207], v195 offset:18432
	ds_read_b128 v[208:211], v195 offset:19456
	ds_read_b128 v[212:215], v195 offset:20480
	ds_read_b128 v[216:219], v195 offset:21504
	ds_read_b128 v[220:223], v195 offset:22528
	ds_read_b128 v[224:227], v195 offset:23552
	global_load_lds_dwordx4 v[170:171], off
	s_add_i32 m0, s16, 0x2000
	s_add_u32 s16, s44, 0x28000
	v_lshl_add_u64 v[172:173], s[44:45], 0, v[174:175]
	s_addc_u32 s17, s45, 0
	s_add_i32 s29, s74, s4
	global_load_lds_dwordx4 v[172:173], off
	v_lshl_add_u64 v[228:229], s[16:17], 0, v[178:179]
	s_mov_b32 m0, s29
	v_lshl_add_u64 v[230:231], s[48:49], 0, v[176:177]
	global_load_lds_dwordx4 v[228:229], off
	v_lshl_add_u64 v[228:229], s[16:17], 0, v[174:175]
	s_add_i32 m0, s29, 0x2000
	s_nop 0
	global_load_lds_dwordx4 v[228:229], off
	v_lshl_add_u64 v[228:229], s[48:49], 0, v[180:181]
	s_mov_b32 m0, s5
	s_nop 0
	global_load_lds_dwordx4 v[228:229], off
	s_mov_b32 m0, s20
	s_nop 0
	global_load_lds_dwordx4 v[230:231], off
	s_waitcnt vmcnt(8)
	s_waitcnt lgkmcnt(0)
	s_setprio 1
	s_barrier
	v_mfma_f32_16x16x32_bf16 v[62:65], v[74:77], v[188:191], v[62:65]
	v_mfma_f32_16x16x32_bf16 v[58:61], v[138:141], v[188:191], v[58:61]
	v_mfma_f32_16x16x32_bf16 v[46:49], v[74:77], v[204:207], v[46:49]
	v_mfma_f32_16x16x32_bf16 v[42:45], v[138:141], v[204:207], v[42:45]
	v_mfma_f32_16x16x32_bf16 v[30:33], v[74:77], v[212:215], v[30:33]
	v_mfma_f32_16x16x32_bf16 v[26:29], v[138:141], v[212:215], v[26:29]
	v_mfma_f32_16x16x32_bf16 v[14:17], v[74:77], v[220:223], v[14:17]
	v_mfma_f32_16x16x32_bf16 v[10:13], v[138:141], v[220:223], v[10:13]
	v_mfma_f32_16x16x32_bf16 v[62:65], v[78:81], v[196:199], v[62:65]
	v_mfma_f32_16x16x32_bf16 v[58:61], v[142:145], v[196:199], v[58:61]
	v_mfma_f32_16x16x32_bf16 v[46:49], v[78:81], v[208:211], v[46:49]
	v_mfma_f32_16x16x32_bf16 v[42:45], v[142:145], v[208:211], v[42:45]
	v_mfma_f32_16x16x32_bf16 v[30:33], v[78:81], v[216:219], v[30:33]
	v_mfma_f32_16x16x32_bf16 v[26:29], v[142:145], v[216:219], v[26:29]
	v_mfma_f32_16x16x32_bf16 v[14:17], v[78:81], v[224:227], v[14:17]
	v_mfma_f32_16x16x32_bf16 v[10:13], v[142:145], v[224:227], v[10:13]
	v_mfma_f32_16x16x32_bf16 v[54:57], v[146:149], v[188:191], v[54:57]
	v_mfma_f32_16x16x32_bf16 v[50:53], v[154:157], v[188:191], v[50:53]
	v_mfma_f32_16x16x32_bf16 v[38:41], v[146:149], v[204:207], v[38:41]
	v_mfma_f32_16x16x32_bf16 v[34:37], v[154:157], v[204:207], v[34:37]
	v_mfma_f32_16x16x32_bf16 v[22:25], v[146:149], v[212:215], v[22:25]
	v_mfma_f32_16x16x32_bf16 v[18:21], v[154:157], v[212:215], v[18:21]
	v_mfma_f32_16x16x32_bf16 v[6:9], v[146:149], v[220:223], v[6:9]
	v_mfma_f32_16x16x32_bf16 v[2:5], v[154:157], v[220:223], v[2:5]
	v_mfma_f32_16x16x32_bf16 v[54:57], v[150:153], v[196:199], v[54:57]
	v_mfma_f32_16x16x32_bf16 v[50:53], v[158:161], v[196:199], v[50:53]
	v_mfma_f32_16x16x32_bf16 v[38:41], v[150:153], v[208:211], v[38:41]
	v_mfma_f32_16x16x32_bf16 v[34:37], v[158:161], v[208:211], v[34:37]
	v_mfma_f32_16x16x32_bf16 v[22:25], v[150:153], v[216:219], v[22:25]
	v_mfma_f32_16x16x32_bf16 v[18:21], v[158:161], v[216:219], v[18:21]
	v_mfma_f32_16x16x32_bf16 v[6:9], v[150:153], v[224:227], v[6:9]
	v_mfma_f32_16x16x32_bf16 v[2:5], v[158:161], v[224:227], v[2:5]
	s_barrier
	s_setprio 0
	s_add_i32 s29, 0, 0x18000
	s_add_i32 s74, 0, 0x1c000
	v_add_u32_e32 v142, s29, v193
	v_add_u32_e32 v158, s74, v193
	ds_read_b128 v[74:77], v142
	ds_read_b128 v[78:81], v142 offset:1024
	ds_read_b128 v[138:141], v142 offset:2048
	ds_read_b128 v[142:145], v142 offset:3072
	ds_read_b128 v[146:149], v158
	ds_read_b128 v[150:153], v158 offset:1024
	ds_read_b128 v[154:157], v158 offset:2048
	ds_read_b128 v[158:161], v158 offset:3072
	s_add_u32 s16, s48, 0x28000
	s_addc_u32 s17, s49, 0
	s_mov_b32 m0, s22
	v_lshl_add_u64 v[232:233], s[16:17], 0, v[180:181]
	ds_read_b128 v[188:191], v195 offset:32768
	ds_read_b128 v[196:199], v195 offset:33792
	ds_read_b128 v[204:207], v195 offset:34816
	ds_read_b128 v[208:211], v195 offset:35840
	ds_read_b128 v[212:215], v195 offset:36864
	ds_read_b128 v[216:219], v195 offset:37888
	ds_read_b128 v[220:223], v195 offset:38912
	ds_read_b128 v[224:227], v195 offset:39936
	global_load_lds_dwordx4 v[232:233], off
	v_lshl_add_u64 v[232:233], s[16:17], 0, v[176:177]
	s_mov_b32 m0, s23
	s_nop 0
	global_load_lds_dwordx4 v[232:233], off
	s_waitcnt vmcnt(8)
	s_waitcnt lgkmcnt(0)
	s_setprio 1
	s_barrier
	v_mfma_f32_16x16x32_bf16 v[134:137], v[74:77], v[188:191], v[134:137]
	v_mfma_f32_16x16x32_bf16 v[130:133], v[138:141], v[188:191], v[130:133]
	v_mfma_f32_16x16x32_bf16 v[118:121], v[74:77], v[204:207], v[118:121]
	v_mfma_f32_16x16x32_bf16 v[114:117], v[138:141], v[204:207], v[114:117]
	v_mfma_f32_16x16x32_bf16 v[102:105], v[74:77], v[212:215], v[102:105]
	v_mfma_f32_16x16x32_bf16 v[98:101], v[138:141], v[212:215], v[98:101]
	v_mfma_f32_16x16x32_bf16 v[86:89], v[74:77], v[220:223], v[86:89]
	v_mfma_f32_16x16x32_bf16 v[82:85], v[138:141], v[220:223], v[82:85]
	v_mfma_f32_16x16x32_bf16 v[134:137], v[78:81], v[196:199], v[134:137]
	v_mfma_f32_16x16x32_bf16 v[130:133], v[142:145], v[196:199], v[130:133]
	v_mfma_f32_16x16x32_bf16 v[118:121], v[78:81], v[208:211], v[118:121]
	v_mfma_f32_16x16x32_bf16 v[114:117], v[142:145], v[208:211], v[114:117]
	v_mfma_f32_16x16x32_bf16 v[102:105], v[78:81], v[216:219], v[102:105]
	v_mfma_f32_16x16x32_bf16 v[98:101], v[142:145], v[216:219], v[98:101]
	v_mfma_f32_16x16x32_bf16 v[86:89], v[78:81], v[224:227], v[86:89]
	v_mfma_f32_16x16x32_bf16 v[82:85], v[142:145], v[224:227], v[82:85]
	v_mfma_f32_16x16x32_bf16 v[126:129], v[146:149], v[188:191], v[126:129]
	v_mfma_f32_16x16x32_bf16 v[122:125], v[154:157], v[188:191], v[122:125]
	v_mfma_f32_16x16x32_bf16 v[110:113], v[146:149], v[204:207], v[110:113]
	v_mfma_f32_16x16x32_bf16 v[106:109], v[154:157], v[204:207], v[106:109]
	v_mfma_f32_16x16x32_bf16 v[94:97], v[146:149], v[212:215], v[94:97]
	v_mfma_f32_16x16x32_bf16 v[90:93], v[154:157], v[212:215], v[90:93]
	v_mfma_f32_16x16x32_bf16 v[70:73], v[146:149], v[220:223], v[70:73]
	v_mfma_f32_16x16x32_bf16 v[66:69], v[154:157], v[220:223], v[66:69]
	v_mfma_f32_16x16x32_bf16 v[126:129], v[150:153], v[196:199], v[126:129]
	v_mfma_f32_16x16x32_bf16 v[122:125], v[158:161], v[196:199], v[122:125]
	v_mfma_f32_16x16x32_bf16 v[110:113], v[150:153], v[208:211], v[110:113]
	v_mfma_f32_16x16x32_bf16 v[106:109], v[158:161], v[208:211], v[106:109]
	v_mfma_f32_16x16x32_bf16 v[94:97], v[150:153], v[216:219], v[94:97]
	v_mfma_f32_16x16x32_bf16 v[90:93], v[158:161], v[216:219], v[90:93]
	v_mfma_f32_16x16x32_bf16 v[70:73], v[150:153], v[224:227], v[70:73]
	v_mfma_f32_16x16x32_bf16 v[66:69], v[158:161], v[224:227], v[66:69]
	s_barrier
	s_setprio 0
	s_add_i32 s16, s29, s4
	v_lshl_add_u64 v[170:171], v[170:171], 0, s[24:25]
	s_mov_b32 m0, s16
	ds_read_b128 v[188:191], v195 offset:49152
	ds_read_b128 v[196:199], v195 offset:50176
	ds_read_b128 v[204:207], v195 offset:51200
	ds_read_b128 v[208:211], v195 offset:52224
	ds_read_b128 v[212:215], v195 offset:53248
	ds_read_b128 v[216:219], v195 offset:54272
	ds_read_b128 v[220:223], v195 offset:55296
	ds_read_b128 v[224:227], v195 offset:56320
	global_load_lds_dwordx4 v[170:171], off
	s_add_i32 m0, s16, 0x2000
	s_add_u32 s16, s44, 0x28080
	v_lshl_add_u64 v[170:171], v[172:173], 0, s[24:25]
	s_addc_u32 s17, s45, 0
	s_add_i32 s29, s74, s4
	global_load_lds_dwordx4 v[170:171], off
	v_lshl_add_u64 v[170:171], s[16:17], 0, v[178:179]
	s_mov_b32 m0, s29
	s_nop 0
	global_load_lds_dwordx4 v[170:171], off
	v_lshl_add_u64 v[170:171], s[16:17], 0, v[174:175]
	s_add_i32 m0, s29, 0x2000
	s_nop 0
	global_load_lds_dwordx4 v[170:171], off
	v_lshl_add_u64 v[170:171], v[228:229], 0, s[24:25]
	s_mov_b32 m0, s31
	s_nop 0
	global_load_lds_dwordx4 v[170:171], off
	v_lshl_add_u64 v[170:171], v[230:231], 0, s[24:25]
	s_mov_b32 m0, s33
	s_nop 0
	global_load_lds_dwordx4 v[170:171], off
	s_waitcnt vmcnt(8)
	s_waitcnt lgkmcnt(0)
	s_setprio 1
	s_barrier
	v_mfma_f32_16x16x32_bf16 v[62:65], v[74:77], v[188:191], v[62:65]
	v_mfma_f32_16x16x32_bf16 v[58:61], v[138:141], v[188:191], v[58:61]
	v_mfma_f32_16x16x32_bf16 v[46:49], v[74:77], v[204:207], v[46:49]
	v_mfma_f32_16x16x32_bf16 v[42:45], v[138:141], v[204:207], v[42:45]
	v_mfma_f32_16x16x32_bf16 v[30:33], v[74:77], v[212:215], v[30:33]
	v_mfma_f32_16x16x32_bf16 v[26:29], v[138:141], v[212:215], v[26:29]
	v_mfma_f32_16x16x32_bf16 v[14:17], v[74:77], v[220:223], v[14:17]
	v_mfma_f32_16x16x32_bf16 v[10:13], v[138:141], v[220:223], v[10:13]
	v_mfma_f32_16x16x32_bf16 v[62:65], v[78:81], v[196:199], v[62:65]
	v_mfma_f32_16x16x32_bf16 v[58:61], v[142:145], v[196:199], v[58:61]
	v_mfma_f32_16x16x32_bf16 v[46:49], v[78:81], v[208:211], v[46:49]
	v_mfma_f32_16x16x32_bf16 v[42:45], v[142:145], v[208:211], v[42:45]
	v_mfma_f32_16x16x32_bf16 v[30:33], v[78:81], v[216:219], v[30:33]
	v_mfma_f32_16x16x32_bf16 v[26:29], v[142:145], v[216:219], v[26:29]
	v_mfma_f32_16x16x32_bf16 v[14:17], v[78:81], v[224:227], v[14:17]
	v_mfma_f32_16x16x32_bf16 v[10:13], v[142:145], v[224:227], v[10:13]
	v_mfma_f32_16x16x32_bf16 v[54:57], v[146:149], v[188:191], v[54:57]
	v_mfma_f32_16x16x32_bf16 v[50:53], v[154:157], v[188:191], v[50:53]
	v_mfma_f32_16x16x32_bf16 v[38:41], v[146:149], v[204:207], v[38:41]
	v_mfma_f32_16x16x32_bf16 v[34:37], v[154:157], v[204:207], v[34:37]
	v_mfma_f32_16x16x32_bf16 v[22:25], v[146:149], v[212:215], v[22:25]
	v_mfma_f32_16x16x32_bf16 v[18:21], v[154:157], v[212:215], v[18:21]
	v_mfma_f32_16x16x32_bf16 v[6:9], v[146:149], v[220:223], v[6:9]
	v_mfma_f32_16x16x32_bf16 v[2:5], v[154:157], v[220:223], v[2:5]
	v_mfma_f32_16x16x32_bf16 v[54:57], v[150:153], v[196:199], v[54:57]
	v_mfma_f32_16x16x32_bf16 v[50:53], v[158:161], v[196:199], v[50:53]
	v_mfma_f32_16x16x32_bf16 v[38:41], v[150:153], v[208:211], v[38:41]
	v_mfma_f32_16x16x32_bf16 v[34:37], v[158:161], v[208:211], v[34:37]
	v_mfma_f32_16x16x32_bf16 v[22:25], v[150:153], v[216:219], v[22:25]
	v_mfma_f32_16x16x32_bf16 v[18:21], v[158:161], v[216:219], v[18:21]
	v_mfma_f32_16x16x32_bf16 v[6:9], v[150:153], v[224:227], v[6:9]
	v_mfma_f32_16x16x32_bf16 v[2:5], v[158:161], v[224:227], v[2:5]
	s_barrier
	s_setprio 0
	s_add_u32 s72, s72, 0x100
	s_addc_u32 s73, s73, 0
	s_cmp_ge_i32 s37, s38
	s_mov_b64 s[16:17], s[42:43]
	s_mov_b32 s44, s37
	s_cbranch_scc0 .LBB7_886
	s_mov_b32 s56, s61
	s_and_b64 vcc, exec, s[6:7]
	s_cbranch_vccz .LBB7_889

.LBB7_963:
	s_add_i32 s37, s48, 2
	s_add_u32 s42, s16, 0x100
	s_addc_u32 s43, s17, 0
	s_add_i32 s29, 0, 0x10000
	s_cmp_eq_u32 s53, s48
	s_cselect_b32 s51, s38, s43
	s_cselect_b32 s50, s39, s42
	s_cselect_b32 s49, s56, s73
	s_cselect_b32 s48, s57, s72
	s_add_i32 s74, 0, 0x14000
	v_add_u32_e32 v142, s29, v197
	v_add_u32_e32 v158, s74, v197
	ds_read_b128 v[130:133], v142
	ds_read_b128 v[134:137], v142 offset:1024
	ds_read_b128 v[138:141], v142 offset:2048
	ds_read_b128 v[142:145], v142 offset:3072
	ds_read_b128 v[146:149], v158
	ds_read_b128 v[150:153], v158 offset:1024
	ds_read_b128 v[154:157], v158 offset:2048
	ds_read_b128 v[158:161], v158 offset:3072
	v_lshl_add_u64 v[170:171], s[16:17], 0, v[180:181]
	s_add_i32 m0, s5, 0xc000
	ds_read_b128 v[184:187], v199
	ds_read_b128 v[188:191], v199 offset:1024
	ds_read_b128 v[192:195], v199 offset:2048
	ds_read_b128 v[204:207], v199 offset:3072
	ds_read_b128 v[208:211], v199 offset:4096
	ds_read_b128 v[212:215], v199 offset:5120
	ds_read_b128 v[216:219], v199 offset:6144
	ds_read_b128 v[220:223], v199 offset:7168
	global_load_lds_dwordx4 v[170:171], off
	v_lshl_add_u64 v[170:171], s[16:17], 0, v[182:183]
	s_add_i32 m0, s5, 0xe000
	s_nop 0
	global_load_lds_dwordx4 v[170:171], off
	s_waitcnt vmcnt(8)
	s_waitcnt lgkmcnt(0)
	s_setprio 1
	s_barrier
	v_mfma_f32_16x16x32_bf16 v[126:129], v[130:133], v[184:187], v[126:129]
	v_mfma_f32_16x16x32_bf16 v[122:125], v[138:141], v[184:187], v[122:125]
	v_mfma_f32_16x16x32_bf16 v[110:113], v[130:133], v[192:195], v[110:113]
	v_mfma_f32_16x16x32_bf16 v[106:109], v[138:141], v[192:195], v[106:109]
	v_mfma_f32_16x16x32_bf16 v[94:97], v[130:133], v[208:211], v[94:97]
	v_mfma_f32_16x16x32_bf16 v[90:93], v[138:141], v[208:211], v[90:93]
	v_mfma_f32_16x16x32_bf16 v[78:81], v[130:133], v[216:219], v[78:81]
	v_mfma_f32_16x16x32_bf16 v[74:77], v[138:141], v[216:219], v[74:77]
	v_mfma_f32_16x16x32_bf16 v[126:129], v[134:137], v[188:191], v[126:129]
	v_mfma_f32_16x16x32_bf16 v[122:125], v[142:145], v[188:191], v[122:125]
	v_mfma_f32_16x16x32_bf16 v[110:113], v[134:137], v[204:207], v[110:113]
	v_mfma_f32_16x16x32_bf16 v[106:109], v[142:145], v[204:207], v[106:109]
	v_mfma_f32_16x16x32_bf16 v[94:97], v[134:137], v[212:215], v[94:97]
	v_mfma_f32_16x16x32_bf16 v[90:93], v[142:145], v[212:215], v[90:93]
	v_mfma_f32_16x16x32_bf16 v[78:81], v[134:137], v[220:223], v[78:81]
	v_mfma_f32_16x16x32_bf16 v[74:77], v[142:145], v[220:223], v[74:77]
	v_mfma_f32_16x16x32_bf16 v[118:121], v[146:149], v[184:187], v[118:121]
	v_mfma_f32_16x16x32_bf16 v[114:117], v[154:157], v[184:187], v[114:117]
	v_mfma_f32_16x16x32_bf16 v[102:105], v[146:149], v[192:195], v[102:105]
	v_mfma_f32_16x16x32_bf16 v[98:101], v[154:157], v[192:195], v[98:101]
	v_mfma_f32_16x16x32_bf16 v[86:89], v[146:149], v[208:211], v[86:89]
	v_mfma_f32_16x16x32_bf16 v[82:85], v[154:157], v[208:211], v[82:85]
	v_mfma_f32_16x16x32_bf16 v[70:73], v[146:149], v[216:219], v[70:73]
	v_mfma_f32_16x16x32_bf16 v[66:69], v[154:157], v[216:219], v[66:69]
	v_mfma_f32_16x16x32_bf16 v[118:121], v[150:153], v[188:191], v[118:121]
	v_mfma_f32_16x16x32_bf16 v[114:117], v[158:161], v[188:191], v[114:117]
	v_mfma_f32_16x16x32_bf16 v[102:105], v[150:153], v[204:207], v[102:105]
	v_mfma_f32_16x16x32_bf16 v[98:101], v[158:161], v[204:207], v[98:101]
	v_mfma_f32_16x16x32_bf16 v[86:89], v[150:153], v[212:215], v[86:89]
	v_mfma_f32_16x16x32_bf16 v[82:85], v[158:161], v[212:215], v[82:85]
	v_mfma_f32_16x16x32_bf16 v[70:73], v[150:153], v[220:223], v[70:73]
	v_mfma_f32_16x16x32_bf16 v[66:69], v[158:161], v[220:223], v[66:69]
	s_barrier
	s_setprio 0
	s_add_i32 s16, s29, s4
	v_lshl_add_u64 v[170:171], s[48:49], 0, v[0:1]
	s_mov_b32 m0, s16
	ds_read_b128 v[184:187], v199 offset:16384
	ds_read_b128 v[188:191], v199 offset:17408
	ds_read_b128 v[192:195], v199 offset:18432
	ds_read_b128 v[204:207], v199 offset:19456
	ds_read_b128 v[208:211], v199 offset:20480
	ds_read_b128 v[212:215], v199 offset:21504
	ds_read_b128 v[216:219], v199 offset:22528
	ds_read_b128 v[220:223], v199 offset:23552
	global_load_lds_dwordx4 v[170:171], off
	s_add_i32 m0, s16, 0x2000
	s_add_u32 s16, s48, 0x18000
	v_lshl_add_u64 v[172:173], s[48:49], 0, v[174:175]
	s_addc_u32 s17, s49, 0
	s_add_i32 s29, s74, s4
	global_load_lds_dwordx4 v[172:173], off
	v_lshl_add_u64 v[224:225], s[16:17], 0, v[0:1]
	s_mov_b32 m0, s29
	v_lshl_add_u64 v[226:227], s[50:51], 0, v[176:177]
	global_load_lds_dwordx4 v[224:225], off
	v_lshl_add_u64 v[224:225], s[16:17], 0, v[174:175]
	s_add_i32 m0, s29, 0x2000
	s_nop 0
	global_load_lds_dwordx4 v[224:225], off
	v_lshl_add_u64 v[224:225], s[50:51], 0, v[178:179]
	s_mov_b32 m0, s5
	s_nop 0
	global_load_lds_dwordx4 v[224:225], off
	s_mov_b32 m0, s20
	s_nop 0
	global_load_lds_dwordx4 v[226:227], off
	s_waitcnt vmcnt(8)
	s_waitcnt lgkmcnt(0)
	s_setprio 1
	s_barrier
	v_mfma_f32_16x16x32_bf16 v[62:65], v[130:133], v[184:187], v[62:65]
	v_mfma_f32_16x16x32_bf16 v[58:61], v[138:141], v[184:187], v[58:61]
	v_mfma_f32_16x16x32_bf16 v[46:49], v[130:133], v[192:195], v[46:49]
	v_mfma_f32_16x16x32_bf16 v[42:45], v[138:141], v[192:195], v[42:45]
	v_mfma_f32_16x16x32_bf16 v[30:33], v[130:133], v[208:211], v[30:33]
	v_mfma_f32_16x16x32_bf16 v[26:29], v[138:141], v[208:211], v[26:29]
	v_mfma_f32_16x16x32_bf16 v[14:17], v[130:133], v[216:219], v[14:17]
	v_mfma_f32_16x16x32_bf16 v[10:13], v[138:141], v[216:219], v[10:13]
	v_mfma_f32_16x16x32_bf16 v[62:65], v[134:137], v[188:191], v[62:65]
	v_mfma_f32_16x16x32_bf16 v[58:61], v[142:145], v[188:191], v[58:61]
	v_mfma_f32_16x16x32_bf16 v[46:49], v[134:137], v[204:207], v[46:49]
	v_mfma_f32_16x16x32_bf16 v[42:45], v[142:145], v[204:207], v[42:45]
	v_mfma_f32_16x16x32_bf16 v[30:33], v[134:137], v[212:215], v[30:33]
	v_mfma_f32_16x16x32_bf16 v[26:29], v[142:145], v[212:215], v[26:29]
	v_mfma_f32_16x16x32_bf16 v[14:17], v[134:137], v[220:223], v[14:17]
	v_mfma_f32_16x16x32_bf16 v[10:13], v[142:145], v[220:223], v[10:13]
	v_mfma_f32_16x16x32_bf16 v[54:57], v[146:149], v[184:187], v[54:57]
	v_mfma_f32_16x16x32_bf16 v[50:53], v[154:157], v[184:187], v[50:53]
	v_mfma_f32_16x16x32_bf16 v[38:41], v[146:149], v[192:195], v[38:41]
	v_mfma_f32_16x16x32_bf16 v[34:37], v[154:157], v[192:195], v[34:37]
	v_mfma_f32_16x16x32_bf16 v[22:25], v[146:149], v[208:211], v[22:25]
	v_mfma_f32_16x16x32_bf16 v[18:21], v[154:157], v[208:211], v[18:21]
	v_mfma_f32_16x16x32_bf16 v[6:9], v[146:149], v[216:219], v[6:9]
	v_mfma_f32_16x16x32_bf16 v[2:5], v[154:157], v[216:219], v[2:5]
	v_mfma_f32_16x16x32_bf16 v[54:57], v[150:153], v[188:191], v[54:57]
	v_mfma_f32_16x16x32_bf16 v[50:53], v[158:161], v[188:191], v[50:53]
	v_mfma_f32_16x16x32_bf16 v[38:41], v[150:153], v[204:207], v[38:41]
	v_mfma_f32_16x16x32_bf16 v[34:37], v[158:161], v[204:207], v[34:37]
	v_mfma_f32_16x16x32_bf16 v[22:25], v[150:153], v[212:215], v[22:25]
	v_mfma_f32_16x16x32_bf16 v[18:21], v[158:161], v[212:215], v[18:21]
	v_mfma_f32_16x16x32_bf16 v[6:9], v[150:153], v[220:223], v[6:9]
	v_mfma_f32_16x16x32_bf16 v[2:5], v[158:161], v[220:223], v[2:5]
	s_barrier
	s_setprio 0
	s_add_i32 s29, 0, 0x18000
	s_add_i32 s74, 0, 0x1c000
	v_add_u32_e32 v142, s29, v197
	v_add_u32_e32 v158, s74, v197
	ds_read_b128 v[130:133], v142
	ds_read_b128 v[134:137], v142 offset:1024
	ds_read_b128 v[138:141], v142 offset:2048
	ds_read_b128 v[142:145], v142 offset:3072
	ds_read_b128 v[146:149], v158
	ds_read_b128 v[150:153], v158 offset:1024
	ds_read_b128 v[154:157], v158 offset:2048
	ds_read_b128 v[158:161], v158 offset:3072
	s_add_u32 s16, s50, 0x18000
	s_addc_u32 s17, s51, 0
	s_mov_b32 m0, s22
	v_lshl_add_u64 v[228:229], s[16:17], 0, v[178:179]
	ds_read_b128 v[184:187], v199 offset:32768
	ds_read_b128 v[188:191], v199 offset:33792
	ds_read_b128 v[192:195], v199 offset:34816
	ds_read_b128 v[204:207], v199 offset:35840
	ds_read_b128 v[208:211], v199 offset:36864
	ds_read_b128 v[212:215], v199 offset:37888
	ds_read_b128 v[216:219], v199 offset:38912
	ds_read_b128 v[220:223], v199 offset:39936
	global_load_lds_dwordx4 v[228:229], off
	v_lshl_add_u64 v[228:229], s[16:17], 0, v[176:177]
	s_mov_b32 m0, s23
	s_nop 0
	global_load_lds_dwordx4 v[228:229], off
	s_waitcnt vmcnt(8)
	s_waitcnt lgkmcnt(0)
	s_setprio 1
	s_barrier
	v_mfma_f32_16x16x32_bf16 v[126:129], v[130:133], v[184:187], v[126:129]
	v_mfma_f32_16x16x32_bf16 v[122:125], v[138:141], v[184:187], v[122:125]
	v_mfma_f32_16x16x32_bf16 v[110:113], v[130:133], v[192:195], v[110:113]
	v_mfma_f32_16x16x32_bf16 v[106:109], v[138:141], v[192:195], v[106:109]
	v_mfma_f32_16x16x32_bf16 v[94:97], v[130:133], v[208:211], v[94:97]
	v_mfma_f32_16x16x32_bf16 v[90:93], v[138:141], v[208:211], v[90:93]
	v_mfma_f32_16x16x32_bf16 v[78:81], v[130:133], v[216:219], v[78:81]
	v_mfma_f32_16x16x32_bf16 v[74:77], v[138:141], v[216:219], v[74:77]
	v_mfma_f32_16x16x32_bf16 v[126:129], v[134:137], v[188:191], v[126:129]
	v_mfma_f32_16x16x32_bf16 v[122:125], v[142:145], v[188:191], v[122:125]
	v_mfma_f32_16x16x32_bf16 v[110:113], v[134:137], v[204:207], v[110:113]
	v_mfma_f32_16x16x32_bf16 v[106:109], v[142:145], v[204:207], v[106:109]
	v_mfma_f32_16x16x32_bf16 v[94:97], v[134:137], v[212:215], v[94:97]
	v_mfma_f32_16x16x32_bf16 v[90:93], v[142:145], v[212:215], v[90:93]
	v_mfma_f32_16x16x32_bf16 v[78:81], v[134:137], v[220:223], v[78:81]
	v_mfma_f32_16x16x32_bf16 v[74:77], v[142:145], v[220:223], v[74:77]
	v_mfma_f32_16x16x32_bf16 v[118:121], v[146:149], v[184:187], v[118:121]
	v_mfma_f32_16x16x32_bf16 v[114:117], v[154:157], v[184:187], v[114:117]
	v_mfma_f32_16x16x32_bf16 v[102:105], v[146:149], v[192:195], v[102:105]
	v_mfma_f32_16x16x32_bf16 v[98:101], v[154:157], v[192:195], v[98:101]
	v_mfma_f32_16x16x32_bf16 v[86:89], v[146:149], v[208:211], v[86:89]
	v_mfma_f32_16x16x32_bf16 v[82:85], v[154:157], v[208:211], v[82:85]
	v_mfma_f32_16x16x32_bf16 v[70:73], v[146:149], v[216:219], v[70:73]
	v_mfma_f32_16x16x32_bf16 v[66:69], v[154:157], v[216:219], v[66:69]
	v_mfma_f32_16x16x32_bf16 v[118:121], v[150:153], v[188:191], v[118:121]
	v_mfma_f32_16x16x32_bf16 v[114:117], v[158:161], v[188:191], v[114:117]
	v_mfma_f32_16x16x32_bf16 v[102:105], v[150:153], v[204:207], v[102:105]
	v_mfma_f32_16x16x32_bf16 v[98:101], v[158:161], v[204:207], v[98:101]
	v_mfma_f32_16x16x32_bf16 v[86:89], v[150:153], v[212:215], v[86:89]
	v_mfma_f32_16x16x32_bf16 v[82:85], v[158:161], v[212:215], v[82:85]
	v_mfma_f32_16x16x32_bf16 v[70:73], v[150:153], v[220:223], v[70:73]
	v_mfma_f32_16x16x32_bf16 v[66:69], v[158:161], v[220:223], v[66:69]
	s_barrier
	s_setprio 0
	s_add_i32 s16, s29, s4
	v_lshl_add_u64 v[170:171], v[170:171], 0, s[24:25]
	s_mov_b32 m0, s16
	ds_read_b128 v[184:187], v199 offset:49152
	ds_read_b128 v[188:191], v199 offset:50176
	ds_read_b128 v[192:195], v199 offset:51200
	ds_read_b128 v[204:207], v199 offset:52224
	ds_read_b128 v[208:211], v199 offset:53248
	ds_read_b128 v[212:215], v199 offset:54272
	ds_read_b128 v[216:219], v199 offset:55296
	ds_read_b128 v[220:223], v199 offset:56320
	global_load_lds_dwordx4 v[170:171], off
	s_add_i32 m0, s16, 0x2000
	s_add_u32 s16, s48, 0x18080
	v_lshl_add_u64 v[170:171], v[172:173], 0, s[24:25]
	s_addc_u32 s17, s49, 0
	s_add_i32 s29, s74, s4
	global_load_lds_dwordx4 v[170:171], off
	v_lshl_add_u64 v[170:171], s[16:17], 0, v[0:1]
	s_mov_b32 m0, s29
	s_nop 0
	global_load_lds_dwordx4 v[170:171], off
	v_lshl_add_u64 v[170:171], s[16:17], 0, v[174:175]
	s_add_i32 m0, s29, 0x2000
	s_nop 0
	global_load_lds_dwordx4 v[170:171], off
	v_lshl_add_u64 v[170:171], v[224:225], 0, s[24:25]
	s_mov_b32 m0, s31
	s_nop 0
	global_load_lds_dwordx4 v[170:171], off
	v_lshl_add_u64 v[170:171], v[226:227], 0, s[24:25]
	s_mov_b32 m0, s33
	s_nop 0
	global_load_lds_dwordx4 v[170:171], off
	s_waitcnt vmcnt(8)
	s_waitcnt lgkmcnt(0)
	s_setprio 1
	s_barrier
	v_mfma_f32_16x16x32_bf16 v[62:65], v[130:133], v[184:187], v[62:65]
	v_mfma_f32_16x16x32_bf16 v[58:61], v[138:141], v[184:187], v[58:61]
	v_mfma_f32_16x16x32_bf16 v[46:49], v[130:133], v[192:195], v[46:49]
	v_mfma_f32_16x16x32_bf16 v[42:45], v[138:141], v[192:195], v[42:45]
	v_mfma_f32_16x16x32_bf16 v[30:33], v[130:133], v[208:211], v[30:33]
	v_mfma_f32_16x16x32_bf16 v[26:29], v[138:141], v[208:211], v[26:29]
	v_mfma_f32_16x16x32_bf16 v[14:17], v[130:133], v[216:219], v[14:17]
	v_mfma_f32_16x16x32_bf16 v[10:13], v[138:141], v[216:219], v[10:13]
	v_mfma_f32_16x16x32_bf16 v[62:65], v[134:137], v[188:191], v[62:65]
	v_mfma_f32_16x16x32_bf16 v[58:61], v[142:145], v[188:191], v[58:61]
	v_mfma_f32_16x16x32_bf16 v[46:49], v[134:137], v[204:207], v[46:49]
	v_mfma_f32_16x16x32_bf16 v[42:45], v[142:145], v[204:207], v[42:45]
	v_mfma_f32_16x16x32_bf16 v[30:33], v[134:137], v[212:215], v[30:33]
	v_mfma_f32_16x16x32_bf16 v[26:29], v[142:145], v[212:215], v[26:29]
	v_mfma_f32_16x16x32_bf16 v[14:17], v[134:137], v[220:223], v[14:17]
	v_mfma_f32_16x16x32_bf16 v[10:13], v[142:145], v[220:223], v[10:13]
	v_mfma_f32_16x16x32_bf16 v[54:57], v[146:149], v[184:187], v[54:57]
	v_mfma_f32_16x16x32_bf16 v[50:53], v[154:157], v[184:187], v[50:53]
	v_mfma_f32_16x16x32_bf16 v[38:41], v[146:149], v[192:195], v[38:41]
	v_mfma_f32_16x16x32_bf16 v[34:37], v[154:157], v[192:195], v[34:37]
	v_mfma_f32_16x16x32_bf16 v[22:25], v[146:149], v[208:211], v[22:25]
	v_mfma_f32_16x16x32_bf16 v[18:21], v[154:157], v[208:211], v[18:21]
	v_mfma_f32_16x16x32_bf16 v[6:9], v[146:149], v[216:219], v[6:9]
	v_mfma_f32_16x16x32_bf16 v[2:5], v[154:157], v[216:219], v[2:5]
	v_mfma_f32_16x16x32_bf16 v[54:57], v[150:153], v[188:191], v[54:57]
	v_mfma_f32_16x16x32_bf16 v[50:53], v[158:161], v[188:191], v[50:53]
	v_mfma_f32_16x16x32_bf16 v[38:41], v[150:153], v[204:207], v[38:41]
	v_mfma_f32_16x16x32_bf16 v[34:37], v[158:161], v[204:207], v[34:37]
	v_mfma_f32_16x16x32_bf16 v[22:25], v[150:153], v[212:215], v[22:25]
	v_mfma_f32_16x16x32_bf16 v[18:21], v[158:161], v[212:215], v[18:21]
	v_mfma_f32_16x16x32_bf16 v[6:9], v[150:153], v[220:223], v[6:9]
	v_mfma_f32_16x16x32_bf16 v[2:5], v[158:161], v[220:223], v[2:5]
	s_barrier
	s_setprio 0
	s_add_u32 s72, s72, 0x100
	s_addc_u32 s73, s73, 0
	s_cmp_ge_i32 s37, s3
	s_mov_b64 s[16:17], s[42:43]
	s_mov_b32 s48, s37
	s_cbranch_scc0 .LBB7_963
	s_mov_b32 s56, s61
	s_and_b64 vcc, exec, s[6:7]
	s_cbranch_vccz .LBB7_966

.LBB7_1104:
	s_add_i32 s74, s72, 2
	s_add_u32 s75, vcc_lo, 0xfffc0080
	s_addc_u32 s73, vcc_hi, -1
	s_add_i32 s76, 0, 0x10000
	s_cmp_eq_u32 s39, s72
	s_cselect_b32 s73, s19, s73
	s_cselect_b32 s72, s20, s75
	v_add_u32_e32 v0, s76, v205
	s_cselect_b32 s85, s28, s49
	s_cselect_b32 s84, s29, s37
	s_add_i32 s75, 0, 0x14000
	ds_read_b128 v[132:135], v0
	ds_read_b128 v[136:139], v0 offset:1024
	ds_read_b128 v[140:143], v0 offset:2048
	ds_read_b128 v[144:147], v0 offset:3072
	v_add_u32_e32 v0, s75, v205
	ds_read_b128 v[148:151], v0
	ds_read_b128 v[152:155], v0 offset:1024
	ds_read_b128 v[156:159], v0 offset:2048
	ds_read_b128 v[184:187], v0 offset:3072
	s_waitcnt lgkmcnt(0)
	v_lshl_add_u64 v[2:3], vcc, 0, v[180:181]
	s_add_i32 m0, s5, 0xc000
	ds_read_b128 v[188:191], v207
	ds_read_b128 v[192:195], v207 offset:1024
	ds_read_b128 v[196:199], v207 offset:2048
	ds_read_b128 v[208:211], v207 offset:3072
	ds_read_b128 v[212:215], v207 offset:4096
	ds_read_b128 v[216:219], v207 offset:5120
	ds_read_b128 v[220:223], v207 offset:6144
	ds_read_b128 v[224:227], v207 offset:7168
	global_load_lds_dwordx4 v[2:3], off
	v_lshl_add_u64 v[2:3], vcc, 0, v[182:183]
	s_add_i32 m0, s5, 0xe000
	s_nop 0
	global_load_lds_dwordx4 v[2:3], off
	s_waitcnt vmcnt(8)
	s_waitcnt lgkmcnt(0)
	s_setprio 1
	s_barrier
	v_mfma_f32_16x16x32_bf16 v[128:131], v[132:135], v[188:191], v[128:131]
	v_mfma_f32_16x16x32_bf16 v[124:127], v[140:143], v[188:191], v[124:127]
	v_mfma_f32_16x16x32_bf16 v[120:123], v[132:135], v[196:199], v[120:123]
	v_mfma_f32_16x16x32_bf16 v[116:119], v[140:143], v[196:199], v[116:119]
	v_mfma_f32_16x16x32_bf16 v[112:115], v[132:135], v[212:215], v[112:115]
	v_mfma_f32_16x16x32_bf16 v[108:111], v[140:143], v[212:215], v[108:111]
	v_mfma_f32_16x16x32_bf16 v[104:107], v[132:135], v[220:223], v[104:107]
	v_mfma_f32_16x16x32_bf16 v[100:103], v[140:143], v[220:223], v[100:103]
	v_mfma_f32_16x16x32_bf16 v[128:131], v[136:139], v[192:195], v[128:131]
	v_mfma_f32_16x16x32_bf16 v[124:127], v[144:147], v[192:195], v[124:127]
	v_mfma_f32_16x16x32_bf16 v[120:123], v[136:139], v[208:211], v[120:123]
	v_mfma_f32_16x16x32_bf16 v[116:119], v[144:147], v[208:211], v[116:119]
	v_mfma_f32_16x16x32_bf16 v[112:115], v[136:139], v[216:219], v[112:115]
	v_mfma_f32_16x16x32_bf16 v[108:111], v[144:147], v[216:219], v[108:111]
	v_mfma_f32_16x16x32_bf16 v[104:107], v[136:139], v[224:227], v[104:107]
	v_mfma_f32_16x16x32_bf16 v[100:103], v[144:147], v[224:227], v[100:103]
	v_mfma_f32_16x16x32_bf16 v[96:99], v[148:151], v[188:191], v[96:99]
	v_mfma_f32_16x16x32_bf16 v[92:95], v[156:159], v[188:191], v[92:95]
	v_mfma_f32_16x16x32_bf16 v[88:91], v[148:151], v[196:199], v[88:91]
	v_mfma_f32_16x16x32_bf16 v[84:87], v[156:159], v[196:199], v[84:87]
	v_mfma_f32_16x16x32_bf16 v[80:83], v[148:151], v[212:215], v[80:83]
	v_mfma_f32_16x16x32_bf16 v[76:79], v[156:159], v[212:215], v[76:79]
	v_mfma_f32_16x16x32_bf16 v[72:75], v[148:151], v[220:223], v[72:75]
	v_mfma_f32_16x16x32_bf16 v[68:71], v[156:159], v[220:223], v[68:71]
	v_mfma_f32_16x16x32_bf16 v[96:99], v[152:155], v[192:195], v[96:99]
	v_mfma_f32_16x16x32_bf16 v[92:95], v[184:187], v[192:195], v[92:95]
	v_mfma_f32_16x16x32_bf16 v[88:91], v[152:155], v[208:211], v[88:91]
	v_mfma_f32_16x16x32_bf16 v[84:87], v[184:187], v[208:211], v[84:87]
	v_mfma_f32_16x16x32_bf16 v[80:83], v[152:155], v[216:219], v[80:83]
	v_mfma_f32_16x16x32_bf16 v[76:79], v[184:187], v[216:219], v[76:79]
	v_mfma_f32_16x16x32_bf16 v[72:75], v[152:155], v[224:227], v[72:75]
	v_mfma_f32_16x16x32_bf16 v[68:71], v[184:187], v[224:227], v[68:71]
	s_barrier
	s_setprio 0
	s_add_i32 s76, s76, s4
	v_lshl_add_u64 v[170:171], s[84:85], 0, v[176:177]
	s_mov_b32 m0, s76
	ds_read_b128 v[188:191], v207 offset:16384
	ds_read_b128 v[192:195], v207 offset:17408
	ds_read_b128 v[196:199], v207 offset:18432
	ds_read_b128 v[208:211], v207 offset:19456
	ds_read_b128 v[212:215], v207 offset:20480
	ds_read_b128 v[216:219], v207 offset:21504
	ds_read_b128 v[220:223], v207 offset:22528
	ds_read_b128 v[224:227], v207 offset:23552
	global_load_lds_dwordx4 v[170:171], off
	s_add_i32 m0, s76, 0x2000
	s_add_u32 s76, s84, 0x40000
	v_lshl_add_u64 v[172:173], s[84:85], 0, v[160:161]
	s_addc_u32 s77, s85, 0
	s_add_i32 s75, s75, s4
	global_load_lds_dwordx4 v[172:173], off
	v_lshl_add_u64 v[2:3], s[76:77], 0, v[176:177]
	s_mov_b32 m0, s75
	v_lshl_add_u64 v[228:229], s[72:73], 0, v[178:179]
	global_load_lds_dwordx4 v[2:3], off
	v_lshl_add_u64 v[2:3], s[76:77], 0, v[160:161]
	s_add_i32 m0, s75, 0x2000
	v_lshl_add_u64 v[230:231], s[72:73], 0, v[174:175]
	global_load_lds_dwordx4 v[2:3], off
	s_mov_b32 m0, s5
	s_nop 0
	global_load_lds_dwordx4 v[228:229], off
	s_mov_b32 m0, s22
	s_nop 0
	global_load_lds_dwordx4 v[230:231], off
	s_waitcnt vmcnt(8)
	s_waitcnt lgkmcnt(0)
	s_setprio 1
	s_barrier
	v_mfma_f32_16x16x32_bf16 v[64:67], v[132:135], v[188:191], v[64:67]
	v_mfma_f32_16x16x32_bf16 v[60:63], v[140:143], v[188:191], v[60:63]
	v_mfma_f32_16x16x32_bf16 v[56:59], v[132:135], v[196:199], v[56:59]
	v_mfma_f32_16x16x32_bf16 v[52:55], v[140:143], v[196:199], v[52:55]
	v_mfma_f32_16x16x32_bf16 v[48:51], v[132:135], v[212:215], v[48:51]
	v_mfma_f32_16x16x32_bf16 v[44:47], v[140:143], v[212:215], v[44:47]
	v_mfma_f32_16x16x32_bf16 v[40:43], v[132:135], v[220:223], v[40:43]
	v_mfma_f32_16x16x32_bf16 v[36:39], v[140:143], v[220:223], v[36:39]
	v_mfma_f32_16x16x32_bf16 v[64:67], v[136:139], v[192:195], v[64:67]
	v_mfma_f32_16x16x32_bf16 v[60:63], v[144:147], v[192:195], v[60:63]
	v_mfma_f32_16x16x32_bf16 v[56:59], v[136:139], v[208:211], v[56:59]
	v_mfma_f32_16x16x32_bf16 v[52:55], v[144:147], v[208:211], v[52:55]
	v_mfma_f32_16x16x32_bf16 v[48:51], v[136:139], v[216:219], v[48:51]
	v_mfma_f32_16x16x32_bf16 v[44:47], v[144:147], v[216:219], v[44:47]
	v_mfma_f32_16x16x32_bf16 v[40:43], v[136:139], v[224:227], v[40:43]
	v_mfma_f32_16x16x32_bf16 v[36:39], v[144:147], v[224:227], v[36:39]
	v_mfma_f32_16x16x32_bf16 v[32:35], v[148:151], v[188:191], v[32:35]
	v_mfma_f32_16x16x32_bf16 v[28:31], v[156:159], v[188:191], v[28:31]
	v_mfma_f32_16x16x32_bf16 v[24:27], v[148:151], v[196:199], v[24:27]
	v_mfma_f32_16x16x32_bf16 v[20:23], v[156:159], v[196:199], v[20:23]
	v_mfma_f32_16x16x32_bf16 v[16:19], v[148:151], v[212:215], v[16:19]
	v_mfma_f32_16x16x32_bf16 v[12:15], v[156:159], v[212:215], v[12:15]
	v_mfma_f32_16x16x32_bf16 v[8:11], v[148:151], v[220:223], v[8:11]
	v_mfma_f32_16x16x32_bf16 v[2:5], v[156:159], v[220:223], v[4:7]
	v_mfma_f32_16x16x32_bf16 v[32:35], v[152:155], v[192:195], v[32:35]
	v_mfma_f32_16x16x32_bf16 v[28:31], v[184:187], v[192:195], v[28:31]
	v_mfma_f32_16x16x32_bf16 v[24:27], v[152:155], v[208:211], v[24:27]
	v_mfma_f32_16x16x32_bf16 v[20:23], v[184:187], v[208:211], v[20:23]
	v_mfma_f32_16x16x32_bf16 v[16:19], v[152:155], v[216:219], v[16:19]
	v_mfma_f32_16x16x32_bf16 v[12:15], v[184:187], v[216:219], v[12:15]
	v_mfma_f32_16x16x32_bf16 v[8:11], v[152:155], v[224:227], v[8:11]
	v_mfma_f32_16x16x32_bf16 v[2:5], v[184:187], v[224:227], v[2:5]
	s_barrier
	s_setprio 0
	s_add_i32 s75, 0, 0x18000
	v_add_u32_e32 v0, s75, v205
	s_add_i32 s76, 0, 0x1c000
	ds_read_b128 v[132:135], v0
	ds_read_b128 v[136:139], v0 offset:1024
	ds_read_b128 v[140:143], v0 offset:2048
	ds_read_b128 v[144:147], v0 offset:3072
	v_add_u32_e32 v0, s76, v205
	ds_read_b128 v[148:151], v0
	ds_read_b128 v[152:155], v0 offset:1024
	ds_read_b128 v[156:159], v0 offset:2048
	ds_read_b128 v[184:187], v0 offset:3072
	s_add_u32 s72, s72, 0x40000
	s_addc_u32 s73, s73, 0
	s_mov_b32 m0, s23
	v_lshl_add_u64 v[6:7], s[72:73], 0, v[178:179]
	ds_read_b128 v[188:191], v207 offset:32768
	ds_read_b128 v[192:195], v207 offset:33792
	ds_read_b128 v[196:199], v207 offset:34816
	ds_read_b128 v[208:211], v207 offset:35840
	ds_read_b128 v[212:215], v207 offset:36864
	ds_read_b128 v[216:219], v207 offset:37888
	ds_read_b128 v[220:223], v207 offset:38912
	ds_read_b128 v[224:227], v207 offset:39936
	global_load_lds_dwordx4 v[6:7], off
	v_lshl_add_u64 v[6:7], s[72:73], 0, v[174:175]
	s_mov_b32 m0, s31
	s_nop 0
	global_load_lds_dwordx4 v[6:7], off
	s_waitcnt vmcnt(8)
	s_waitcnt lgkmcnt(0)
	s_setprio 1
	s_barrier
	v_mfma_f32_16x16x32_bf16 v[128:131], v[132:135], v[188:191], v[128:131]
	v_mfma_f32_16x16x32_bf16 v[124:127], v[140:143], v[188:191], v[124:127]
	v_mfma_f32_16x16x32_bf16 v[120:123], v[132:135], v[196:199], v[120:123]
	v_mfma_f32_16x16x32_bf16 v[116:119], v[140:143], v[196:199], v[116:119]
	v_mfma_f32_16x16x32_bf16 v[112:115], v[132:135], v[212:215], v[112:115]
	v_mfma_f32_16x16x32_bf16 v[108:111], v[140:143], v[212:215], v[108:111]
	v_mfma_f32_16x16x32_bf16 v[104:107], v[132:135], v[220:223], v[104:107]
	v_mfma_f32_16x16x32_bf16 v[100:103], v[140:143], v[220:223], v[100:103]
	v_mfma_f32_16x16x32_bf16 v[128:131], v[136:139], v[192:195], v[128:131]
	v_mfma_f32_16x16x32_bf16 v[124:127], v[144:147], v[192:195], v[124:127]
	v_mfma_f32_16x16x32_bf16 v[120:123], v[136:139], v[208:211], v[120:123]
	v_mfma_f32_16x16x32_bf16 v[116:119], v[144:147], v[208:211], v[116:119]
	v_mfma_f32_16x16x32_bf16 v[112:115], v[136:139], v[216:219], v[112:115]
	v_mfma_f32_16x16x32_bf16 v[108:111], v[144:147], v[216:219], v[108:111]
	v_mfma_f32_16x16x32_bf16 v[104:107], v[136:139], v[224:227], v[104:107]
	v_mfma_f32_16x16x32_bf16 v[100:103], v[144:147], v[224:227], v[100:103]
	v_mfma_f32_16x16x32_bf16 v[96:99], v[148:151], v[188:191], v[96:99]
	v_mfma_f32_16x16x32_bf16 v[92:95], v[156:159], v[188:191], v[92:95]
	v_mfma_f32_16x16x32_bf16 v[88:91], v[148:151], v[196:199], v[88:91]
	v_mfma_f32_16x16x32_bf16 v[84:87], v[156:159], v[196:199], v[84:87]
	v_mfma_f32_16x16x32_bf16 v[80:83], v[148:151], v[212:215], v[80:83]
	v_mfma_f32_16x16x32_bf16 v[76:79], v[156:159], v[212:215], v[76:79]
	v_mfma_f32_16x16x32_bf16 v[72:75], v[148:151], v[220:223], v[72:75]
	v_mfma_f32_16x16x32_bf16 v[68:71], v[156:159], v[220:223], v[68:71]
	v_mfma_f32_16x16x32_bf16 v[96:99], v[152:155], v[192:195], v[96:99]
	v_mfma_f32_16x16x32_bf16 v[92:95], v[184:187], v[192:195], v[92:95]
	v_mfma_f32_16x16x32_bf16 v[88:91], v[152:155], v[208:211], v[88:91]
	v_mfma_f32_16x16x32_bf16 v[84:87], v[184:187], v[208:211], v[84:87]
	v_mfma_f32_16x16x32_bf16 v[80:83], v[152:155], v[216:219], v[80:83]
	v_mfma_f32_16x16x32_bf16 v[76:79], v[184:187], v[216:219], v[76:79]
	v_mfma_f32_16x16x32_bf16 v[72:75], v[152:155], v[224:227], v[72:75]
	v_mfma_f32_16x16x32_bf16 v[68:71], v[184:187], v[224:227], v[68:71]
	s_barrier
	s_setprio 0
	s_add_i32 s72, s75, s4
	v_lshl_add_u64 v[6:7], v[170:171], 0, s[24:25]
	s_mov_b32 m0, s72
	ds_read_b128 v[188:191], v207 offset:49152
	ds_read_b128 v[192:195], v207 offset:50176
	ds_read_b128 v[196:199], v207 offset:51200
	ds_read_b128 v[208:211], v207 offset:52224
	ds_read_b128 v[212:215], v207 offset:53248
	ds_read_b128 v[216:219], v207 offset:54272
	ds_read_b128 v[220:223], v207 offset:55296
	ds_read_b128 v[224:227], v207 offset:56320
	global_load_lds_dwordx4 v[6:7], off
	s_add_i32 m0, s72, 0x2000
	s_add_u32 s72, s84, 0x40080
	v_lshl_add_u64 v[6:7], v[172:173], 0, s[24:25]
	s_addc_u32 s73, s85, 0
	s_add_i32 s75, s76, s4
	global_load_lds_dwordx4 v[6:7], off
	v_lshl_add_u64 v[6:7], s[72:73], 0, v[176:177]
	s_mov_b32 m0, s75
	s_nop 0
	global_load_lds_dwordx4 v[6:7], off
	v_lshl_add_u64 v[6:7], s[72:73], 0, v[160:161]
	s_add_i32 m0, s75, 0x2000
	s_nop 0
	global_load_lds_dwordx4 v[6:7], off
	v_lshl_add_u64 v[6:7], v[228:229], 0, s[24:25]
	s_mov_b32 m0, s33
	s_nop 0
	global_load_lds_dwordx4 v[6:7], off
	v_lshl_add_u64 v[6:7], v[230:231], 0, s[24:25]
	s_mov_b32 m0, s38
	s_nop 0
	global_load_lds_dwordx4 v[6:7], off
	s_waitcnt vmcnt(8)
	s_waitcnt lgkmcnt(0)
	s_setprio 1
	s_barrier
	v_mfma_f32_16x16x32_bf16 v[64:67], v[132:135], v[188:191], v[64:67]
	v_mfma_f32_16x16x32_bf16 v[60:63], v[140:143], v[188:191], v[60:63]
	v_mfma_f32_16x16x32_bf16 v[56:59], v[132:135], v[196:199], v[56:59]
	v_mfma_f32_16x16x32_bf16 v[52:55], v[140:143], v[196:199], v[52:55]
	v_mfma_f32_16x16x32_bf16 v[48:51], v[132:135], v[212:215], v[48:51]
	v_mfma_f32_16x16x32_bf16 v[44:47], v[140:143], v[212:215], v[44:47]
	v_mfma_f32_16x16x32_bf16 v[40:43], v[132:135], v[220:223], v[40:43]
	v_mfma_f32_16x16x32_bf16 v[36:39], v[140:143], v[220:223], v[36:39]
	v_mfma_f32_16x16x32_bf16 v[64:67], v[136:139], v[192:195], v[64:67]
	v_mfma_f32_16x16x32_bf16 v[60:63], v[144:147], v[192:195], v[60:63]
	v_mfma_f32_16x16x32_bf16 v[56:59], v[136:139], v[208:211], v[56:59]
	v_mfma_f32_16x16x32_bf16 v[52:55], v[144:147], v[208:211], v[52:55]
	v_mfma_f32_16x16x32_bf16 v[48:51], v[136:139], v[216:219], v[48:51]
	v_mfma_f32_16x16x32_bf16 v[44:47], v[144:147], v[216:219], v[44:47]
	v_mfma_f32_16x16x32_bf16 v[40:43], v[136:139], v[224:227], v[40:43]
	v_mfma_f32_16x16x32_bf16 v[36:39], v[144:147], v[224:227], v[36:39]
	v_mfma_f32_16x16x32_bf16 v[32:35], v[148:151], v[188:191], v[32:35]
	v_mfma_f32_16x16x32_bf16 v[28:31], v[156:159], v[188:191], v[28:31]
	v_mfma_f32_16x16x32_bf16 v[24:27], v[148:151], v[196:199], v[24:27]
	v_mfma_f32_16x16x32_bf16 v[20:23], v[156:159], v[196:199], v[20:23]
	v_mfma_f32_16x16x32_bf16 v[16:19], v[148:151], v[212:215], v[16:19]
	v_mfma_f32_16x16x32_bf16 v[12:15], v[156:159], v[212:215], v[12:15]
	v_mfma_f32_16x16x32_bf16 v[6:9], v[148:151], v[220:223], v[8:11]
	v_mfma_f32_16x16x32_bf16 v[2:5], v[156:159], v[220:223], v[2:5]
	v_mfma_f32_16x16x32_bf16 v[32:35], v[152:155], v[192:195], v[32:35]
	v_mfma_f32_16x16x32_bf16 v[28:31], v[184:187], v[192:195], v[28:31]
	v_mfma_f32_16x16x32_bf16 v[24:27], v[152:155], v[208:211], v[24:27]
	v_mfma_f32_16x16x32_bf16 v[20:23], v[184:187], v[208:211], v[20:23]
	v_mfma_f32_16x16x32_bf16 v[16:19], v[152:155], v[216:219], v[16:19]
	v_mfma_f32_16x16x32_bf16 v[12:15], v[184:187], v[216:219], v[12:15]
	v_mfma_f32_16x16x32_bf16 v[8:11], v[152:155], v[224:227], v[6:9]
	v_mfma_f32_16x16x32_bf16 v[4:7], v[184:187], v[224:227], v[2:5]
	s_barrier
	s_setprio 0
	s_add_u32 s37, s37, 0x100
	s_addc_u32 s49, s49, 0
	s_add_u32 vcc_lo, vcc_lo, 0x100
	s_addc_u32 vcc_hi, vcc_hi, 0
	s_cmp_ge_i32 s74, s3
	s_mov_b32 s72, s74
	s_cbranch_scc0 .LBB7_1104

.LBB7_1196:
	s_add_i32 s72, s42, 2
	s_add_u32 s29, s16, 0xfffc0080
	s_addc_u32 s37, s17, -1
	s_add_i32 s73, 0, 0x10000
	s_cmp_eq_u32 s55, s42
	s_cselect_b32 s53, s13, s37
	s_cselect_b32 s52, s15, s29
	v_add_u32_e32 v146, s73, v153
	s_cselect_b32 s43, s28, s57
	s_cselect_b32 s42, s39, s56
	s_add_i32 s29, 0, 0x14000
	ds_read_b128 v[130:133], v146
	ds_read_b128 v[156:159], v146 offset:1024
	ds_read_b128 v[174:177], v146 offset:2048
	ds_read_b128 v[178:181], v146 offset:3072
	v_add_u32_e32 v146, s29, v153
	ds_read_b128 v[182:185], v146
	ds_read_b128 v[186:189], v146 offset:1024
	ds_read_b128 v[190:193], v146 offset:2048
	ds_read_b128 v[194:197], v146 offset:3072
	v_lshl_add_u64 v[146:147], s[16:17], 0, v[142:143]
	s_add_i32 m0, s5, 0xc000
	ds_read_b128 v[204:207], v161
	ds_read_b128 v[208:211], v161 offset:1024
	ds_read_b128 v[212:215], v161 offset:2048
	ds_read_b128 v[216:219], v161 offset:3072
	ds_read_b128 v[220:223], v161 offset:4096
	ds_read_b128 v[224:227], v161 offset:5120
	ds_read_b128 v[228:231], v161 offset:6144
	ds_read_b128 v[232:235], v161 offset:7168
	global_load_lds_dwordx4 v[146:147], off
	v_lshl_add_u64 v[146:147], s[16:17], 0, v[144:145]
	s_add_i32 m0, s5, 0xe000
	s_nop 0
	global_load_lds_dwordx4 v[146:147], off
	s_waitcnt vmcnt(8)
	s_waitcnt lgkmcnt(0)
	s_setprio 1
	s_barrier
	v_mfma_f32_16x16x32_bf16 v[126:129], v[130:133], v[204:207], v[126:129]
	v_mfma_f32_16x16x32_bf16 v[122:125], v[174:177], v[204:207], v[122:125]
	v_mfma_f32_16x16x32_bf16 v[110:113], v[130:133], v[212:215], v[110:113]
	v_mfma_f32_16x16x32_bf16 v[106:109], v[174:177], v[212:215], v[106:109]
	v_mfma_f32_16x16x32_bf16 v[94:97], v[130:133], v[220:223], v[94:97]
	v_mfma_f32_16x16x32_bf16 v[90:93], v[174:177], v[220:223], v[90:93]
	v_mfma_f32_16x16x32_bf16 v[78:81], v[130:133], v[228:231], v[78:81]
	v_mfma_f32_16x16x32_bf16 v[74:77], v[174:177], v[228:231], v[74:77]
	v_mfma_f32_16x16x32_bf16 v[126:129], v[156:159], v[208:211], v[126:129]
	v_mfma_f32_16x16x32_bf16 v[122:125], v[178:181], v[208:211], v[122:125]
	v_mfma_f32_16x16x32_bf16 v[110:113], v[156:159], v[216:219], v[110:113]
	v_mfma_f32_16x16x32_bf16 v[106:109], v[178:181], v[216:219], v[106:109]
	v_mfma_f32_16x16x32_bf16 v[94:97], v[156:159], v[224:227], v[94:97]
	v_mfma_f32_16x16x32_bf16 v[90:93], v[178:181], v[224:227], v[90:93]
	v_mfma_f32_16x16x32_bf16 v[78:81], v[156:159], v[232:235], v[78:81]
	v_mfma_f32_16x16x32_bf16 v[74:77], v[178:181], v[232:235], v[74:77]
	v_mfma_f32_16x16x32_bf16 v[118:121], v[182:185], v[204:207], v[118:121]
	v_mfma_f32_16x16x32_bf16 v[114:117], v[190:193], v[204:207], v[114:117]
	v_mfma_f32_16x16x32_bf16 v[102:105], v[182:185], v[212:215], v[102:105]
	v_mfma_f32_16x16x32_bf16 v[98:101], v[190:193], v[212:215], v[98:101]
	v_mfma_f32_16x16x32_bf16 v[86:89], v[182:185], v[220:223], v[86:89]
	v_mfma_f32_16x16x32_bf16 v[82:85], v[190:193], v[220:223], v[82:85]
	v_mfma_f32_16x16x32_bf16 v[70:73], v[182:185], v[228:231], v[70:73]
	v_mfma_f32_16x16x32_bf16 v[66:69], v[190:193], v[228:231], v[66:69]
	v_mfma_f32_16x16x32_bf16 v[118:121], v[186:189], v[208:211], v[118:121]
	v_mfma_f32_16x16x32_bf16 v[114:117], v[194:197], v[208:211], v[114:117]
	v_mfma_f32_16x16x32_bf16 v[102:105], v[186:189], v[216:219], v[102:105]
	v_mfma_f32_16x16x32_bf16 v[98:101], v[194:197], v[216:219], v[98:101]
	v_mfma_f32_16x16x32_bf16 v[86:89], v[186:189], v[224:227], v[86:89]
	v_mfma_f32_16x16x32_bf16 v[82:85], v[194:197], v[224:227], v[82:85]
	v_mfma_f32_16x16x32_bf16 v[70:73], v[186:189], v[232:235], v[70:73]
	v_mfma_f32_16x16x32_bf16 v[66:69], v[194:197], v[232:235], v[66:69]
	s_barrier
	s_setprio 0
	s_add_i32 s37, s73, s4
	v_lshl_add_u64 v[146:147], s[42:43], 0, v[0:1]
	s_mov_b32 m0, s37
	ds_read_b128 v[204:207], v161 offset:16384
	ds_read_b128 v[208:211], v161 offset:17408
	ds_read_b128 v[212:215], v161 offset:18432
	ds_read_b128 v[216:219], v161 offset:19456
	ds_read_b128 v[220:223], v161 offset:20480
	ds_read_b128 v[224:227], v161 offset:21504
	ds_read_b128 v[228:231], v161 offset:22528
	ds_read_b128 v[232:235], v161 offset:23552
	global_load_lds_dwordx4 v[146:147], off
	s_add_i32 m0, s37, 0x2000
	s_add_u32 s74, s42, 0x40000
	v_lshl_add_u64 v[150:151], s[42:43], 0, v[134:135]
	s_addc_u32 s75, s43, 0
	s_add_i32 s29, s29, s4
	global_load_lds_dwordx4 v[150:151], off
	v_lshl_add_u64 v[170:171], s[74:75], 0, v[0:1]
	s_mov_b32 m0, s29
	v_lshl_add_u64 v[172:173], s[52:53], 0, v[136:137]
	global_load_lds_dwordx4 v[170:171], off
	v_lshl_add_u64 v[170:171], s[74:75], 0, v[134:135]
	s_add_i32 m0, s29, 0x2000
	s_nop 0
	global_load_lds_dwordx4 v[170:171], off
	v_lshl_add_u64 v[170:171], s[52:53], 0, v[138:139]
	s_mov_b32 m0, s5
	s_nop 0
	global_load_lds_dwordx4 v[170:171], off
	s_mov_b32 m0, s20
	s_nop 0
	global_load_lds_dwordx4 v[172:173], off
	s_waitcnt vmcnt(8)
	s_waitcnt lgkmcnt(0)
	s_setprio 1
	s_barrier
	v_mfma_f32_16x16x32_bf16 v[62:65], v[130:133], v[204:207], v[62:65]
	v_mfma_f32_16x16x32_bf16 v[58:61], v[174:177], v[204:207], v[58:61]
	v_mfma_f32_16x16x32_bf16 v[46:49], v[130:133], v[212:215], v[46:49]
	v_mfma_f32_16x16x32_bf16 v[42:45], v[174:177], v[212:215], v[42:45]
	v_mfma_f32_16x16x32_bf16 v[30:33], v[130:133], v[220:223], v[30:33]
	v_mfma_f32_16x16x32_bf16 v[26:29], v[174:177], v[220:223], v[26:29]
	v_mfma_f32_16x16x32_bf16 v[14:17], v[130:133], v[228:231], v[14:17]
	v_mfma_f32_16x16x32_bf16 v[10:13], v[174:177], v[228:231], v[10:13]
	v_mfma_f32_16x16x32_bf16 v[62:65], v[156:159], v[208:211], v[62:65]
	v_mfma_f32_16x16x32_bf16 v[58:61], v[178:181], v[208:211], v[58:61]
	v_mfma_f32_16x16x32_bf16 v[46:49], v[156:159], v[216:219], v[46:49]
	v_mfma_f32_16x16x32_bf16 v[42:45], v[178:181], v[216:219], v[42:45]
	v_mfma_f32_16x16x32_bf16 v[30:33], v[156:159], v[224:227], v[30:33]
	v_mfma_f32_16x16x32_bf16 v[26:29], v[178:181], v[224:227], v[26:29]
	v_mfma_f32_16x16x32_bf16 v[14:17], v[156:159], v[232:235], v[14:17]
	v_mfma_f32_16x16x32_bf16 v[10:13], v[178:181], v[232:235], v[10:13]
	v_mfma_f32_16x16x32_bf16 v[54:57], v[182:185], v[204:207], v[54:57]
	v_mfma_f32_16x16x32_bf16 v[50:53], v[190:193], v[204:207], v[50:53]
	v_mfma_f32_16x16x32_bf16 v[38:41], v[182:185], v[212:215], v[38:41]
	v_mfma_f32_16x16x32_bf16 v[34:37], v[190:193], v[212:215], v[34:37]
	v_mfma_f32_16x16x32_bf16 v[22:25], v[182:185], v[220:223], v[22:25]
	v_mfma_f32_16x16x32_bf16 v[18:21], v[190:193], v[220:223], v[18:21]
	v_mfma_f32_16x16x32_bf16 v[6:9], v[182:185], v[228:231], v[6:9]
	v_mfma_f32_16x16x32_bf16 v[2:5], v[190:193], v[228:231], v[2:5]
	v_mfma_f32_16x16x32_bf16 v[54:57], v[186:189], v[208:211], v[54:57]
	v_mfma_f32_16x16x32_bf16 v[50:53], v[194:197], v[208:211], v[50:53]
	v_mfma_f32_16x16x32_bf16 v[38:41], v[186:189], v[216:219], v[38:41]
	v_mfma_f32_16x16x32_bf16 v[34:37], v[194:197], v[216:219], v[34:37]
	v_mfma_f32_16x16x32_bf16 v[22:25], v[186:189], v[224:227], v[22:25]
	v_mfma_f32_16x16x32_bf16 v[18:21], v[194:197], v[224:227], v[18:21]
	v_mfma_f32_16x16x32_bf16 v[6:9], v[186:189], v[232:235], v[6:9]
	v_mfma_f32_16x16x32_bf16 v[2:5], v[194:197], v[232:235], v[2:5]
	s_barrier
	s_setprio 0
	s_add_i32 s29, 0, 0x18000
	v_add_u32_e32 v148, s29, v153
	s_add_i32 s37, 0, 0x1c000
	ds_read_b128 v[130:133], v148
	ds_read_b128 v[156:159], v148 offset:1024
	ds_read_b128 v[174:177], v148 offset:2048
	ds_read_b128 v[178:181], v148 offset:3072
	v_add_u32_e32 v148, s37, v153
	ds_read_b128 v[182:185], v148
	ds_read_b128 v[186:189], v148 offset:1024
	ds_read_b128 v[190:193], v148 offset:2048
	ds_read_b128 v[194:197], v148 offset:3072
	s_add_u32 s52, s52, 0x40000
	s_addc_u32 s53, s53, 0
	s_mov_b32 m0, s22
	v_lshl_add_u64 v[198:199], s[52:53], 0, v[138:139]
	ds_read_b128 v[204:207], v161 offset:32768
	ds_read_b128 v[208:211], v161 offset:33792
	ds_read_b128 v[212:215], v161 offset:34816
	ds_read_b128 v[216:219], v161 offset:35840
	ds_read_b128 v[220:223], v161 offset:36864
	ds_read_b128 v[224:227], v161 offset:37888
	ds_read_b128 v[228:231], v161 offset:38912
	ds_read_b128 v[232:235], v161 offset:39936
	global_load_lds_dwordx4 v[198:199], off
	v_lshl_add_u64 v[198:199], s[52:53], 0, v[136:137]
	s_mov_b32 m0, s23
	s_nop 0
	global_load_lds_dwordx4 v[198:199], off
	s_waitcnt vmcnt(8)
	s_waitcnt lgkmcnt(0)
	s_setprio 1
	s_barrier
	v_mfma_f32_16x16x32_bf16 v[126:129], v[130:133], v[204:207], v[126:129]
	v_mfma_f32_16x16x32_bf16 v[122:125], v[174:177], v[204:207], v[122:125]
	v_mfma_f32_16x16x32_bf16 v[110:113], v[130:133], v[212:215], v[110:113]
	v_mfma_f32_16x16x32_bf16 v[106:109], v[174:177], v[212:215], v[106:109]
	v_mfma_f32_16x16x32_bf16 v[94:97], v[130:133], v[220:223], v[94:97]
	v_mfma_f32_16x16x32_bf16 v[90:93], v[174:177], v[220:223], v[90:93]
	v_mfma_f32_16x16x32_bf16 v[78:81], v[130:133], v[228:231], v[78:81]
	v_mfma_f32_16x16x32_bf16 v[74:77], v[174:177], v[228:231], v[74:77]
	v_mfma_f32_16x16x32_bf16 v[126:129], v[156:159], v[208:211], v[126:129]
	v_mfma_f32_16x16x32_bf16 v[122:125], v[178:181], v[208:211], v[122:125]
	v_mfma_f32_16x16x32_bf16 v[110:113], v[156:159], v[216:219], v[110:113]
	v_mfma_f32_16x16x32_bf16 v[106:109], v[178:181], v[216:219], v[106:109]
	v_mfma_f32_16x16x32_bf16 v[94:97], v[156:159], v[224:227], v[94:97]
	v_mfma_f32_16x16x32_bf16 v[90:93], v[178:181], v[224:227], v[90:93]
	v_mfma_f32_16x16x32_bf16 v[78:81], v[156:159], v[232:235], v[78:81]
	v_mfma_f32_16x16x32_bf16 v[74:77], v[178:181], v[232:235], v[74:77]
	v_mfma_f32_16x16x32_bf16 v[118:121], v[182:185], v[204:207], v[118:121]
	v_mfma_f32_16x16x32_bf16 v[114:117], v[190:193], v[204:207], v[114:117]
	v_mfma_f32_16x16x32_bf16 v[102:105], v[182:185], v[212:215], v[102:105]
	v_mfma_f32_16x16x32_bf16 v[98:101], v[190:193], v[212:215], v[98:101]
	v_mfma_f32_16x16x32_bf16 v[86:89], v[182:185], v[220:223], v[86:89]
	v_mfma_f32_16x16x32_bf16 v[82:85], v[190:193], v[220:223], v[82:85]
	v_mfma_f32_16x16x32_bf16 v[70:73], v[182:185], v[228:231], v[70:73]
	v_mfma_f32_16x16x32_bf16 v[66:69], v[190:193], v[228:231], v[66:69]
	v_mfma_f32_16x16x32_bf16 v[118:121], v[186:189], v[208:211], v[118:121]
	v_mfma_f32_16x16x32_bf16 v[114:117], v[194:197], v[208:211], v[114:117]
	v_mfma_f32_16x16x32_bf16 v[102:105], v[186:189], v[216:219], v[102:105]
	v_mfma_f32_16x16x32_bf16 v[98:101], v[194:197], v[216:219], v[98:101]
	v_mfma_f32_16x16x32_bf16 v[86:89], v[186:189], v[224:227], v[86:89]
	v_mfma_f32_16x16x32_bf16 v[82:85], v[194:197], v[224:227], v[82:85]
	v_mfma_f32_16x16x32_bf16 v[70:73], v[186:189], v[232:235], v[70:73]
	v_mfma_f32_16x16x32_bf16 v[66:69], v[194:197], v[232:235], v[66:69]
	s_barrier
	s_setprio 0
	s_add_i32 s29, s29, s4
	v_lshl_add_u64 v[146:147], v[146:147], 0, s[24:25]
	s_mov_b32 m0, s29
	ds_read_b128 v[204:207], v161 offset:49152
	ds_read_b128 v[208:211], v161 offset:50176
	ds_read_b128 v[212:215], v161 offset:51200
	ds_read_b128 v[216:219], v161 offset:52224
	ds_read_b128 v[220:223], v161 offset:53248
	ds_read_b128 v[224:227], v161 offset:54272
	ds_read_b128 v[228:231], v161 offset:55296
	ds_read_b128 v[232:235], v161 offset:56320
	global_load_lds_dwordx4 v[146:147], off
	s_add_i32 m0, s29, 0x2000
	s_add_u32 s42, s42, 0x40080
	v_lshl_add_u64 v[146:147], v[150:151], 0, s[24:25]
	s_addc_u32 s43, s43, 0
	s_add_i32 s29, s37, s4
	global_load_lds_dwordx4 v[146:147], off
	v_lshl_add_u64 v[146:147], s[42:43], 0, v[0:1]
	s_mov_b32 m0, s29
	s_nop 0
	global_load_lds_dwordx4 v[146:147], off
	v_lshl_add_u64 v[146:147], s[42:43], 0, v[134:135]
	s_add_i32 m0, s29, 0x2000
	s_nop 0
	global_load_lds_dwordx4 v[146:147], off
	v_lshl_add_u64 v[146:147], v[170:171], 0, s[24:25]
	s_mov_b32 m0, s31
	s_nop 0
	global_load_lds_dwordx4 v[146:147], off
	v_lshl_add_u64 v[146:147], v[172:173], 0, s[24:25]
	s_mov_b32 m0, s33
	s_nop 0
	global_load_lds_dwordx4 v[146:147], off
	s_waitcnt vmcnt(8)
	s_waitcnt lgkmcnt(0)
	s_setprio 1
	s_barrier
	v_mfma_f32_16x16x32_bf16 v[62:65], v[130:133], v[204:207], v[62:65]
	v_mfma_f32_16x16x32_bf16 v[58:61], v[174:177], v[204:207], v[58:61]
	v_mfma_f32_16x16x32_bf16 v[46:49], v[130:133], v[212:215], v[46:49]
	v_mfma_f32_16x16x32_bf16 v[42:45], v[174:177], v[212:215], v[42:45]
	v_mfma_f32_16x16x32_bf16 v[30:33], v[130:133], v[220:223], v[30:33]
	v_mfma_f32_16x16x32_bf16 v[26:29], v[174:177], v[220:223], v[26:29]
	v_mfma_f32_16x16x32_bf16 v[14:17], v[130:133], v[228:231], v[14:17]
	v_mfma_f32_16x16x32_bf16 v[10:13], v[174:177], v[228:231], v[10:13]
	v_mfma_f32_16x16x32_bf16 v[62:65], v[156:159], v[208:211], v[62:65]
	v_mfma_f32_16x16x32_bf16 v[58:61], v[178:181], v[208:211], v[58:61]
	v_mfma_f32_16x16x32_bf16 v[46:49], v[156:159], v[216:219], v[46:49]
	v_mfma_f32_16x16x32_bf16 v[42:45], v[178:181], v[216:219], v[42:45]
	v_mfma_f32_16x16x32_bf16 v[30:33], v[156:159], v[224:227], v[30:33]
	v_mfma_f32_16x16x32_bf16 v[26:29], v[178:181], v[224:227], v[26:29]
	v_mfma_f32_16x16x32_bf16 v[14:17], v[156:159], v[232:235], v[14:17]
	v_mfma_f32_16x16x32_bf16 v[10:13], v[178:181], v[232:235], v[10:13]
	v_mfma_f32_16x16x32_bf16 v[54:57], v[182:185], v[204:207], v[54:57]
	v_mfma_f32_16x16x32_bf16 v[50:53], v[190:193], v[204:207], v[50:53]
	v_mfma_f32_16x16x32_bf16 v[38:41], v[182:185], v[212:215], v[38:41]
	v_mfma_f32_16x16x32_bf16 v[34:37], v[190:193], v[212:215], v[34:37]
	v_mfma_f32_16x16x32_bf16 v[22:25], v[182:185], v[220:223], v[22:25]
	v_mfma_f32_16x16x32_bf16 v[18:21], v[190:193], v[220:223], v[18:21]
	v_mfma_f32_16x16x32_bf16 v[6:9], v[182:185], v[228:231], v[6:9]
	v_mfma_f32_16x16x32_bf16 v[2:5], v[190:193], v[228:231], v[2:5]
	v_mfma_f32_16x16x32_bf16 v[54:57], v[186:189], v[208:211], v[54:57]
	v_mfma_f32_16x16x32_bf16 v[50:53], v[194:197], v[208:211], v[50:53]
	v_mfma_f32_16x16x32_bf16 v[38:41], v[186:189], v[216:219], v[38:41]
	v_mfma_f32_16x16x32_bf16 v[34:37], v[194:197], v[216:219], v[34:37]
	v_mfma_f32_16x16x32_bf16 v[22:25], v[186:189], v[224:227], v[22:25]
	v_mfma_f32_16x16x32_bf16 v[18:21], v[194:197], v[224:227], v[18:21]
	v_mfma_f32_16x16x32_bf16 v[6:9], v[186:189], v[232:235], v[6:9]
	v_mfma_f32_16x16x32_bf16 v[2:5], v[194:197], v[232:235], v[2:5]
	s_barrier
	s_setprio 0
	s_add_u32 s16, s16, 0x100
	s_addc_u32 s17, s17, 0
	s_add_u32 s56, s56, 0x100
	s_addc_u32 s57, s57, 0
	s_cmp_ge_i32 s72, s3
	s_mov_b32 s42, s72
	s_cbranch_scc0 .LBB7_1196
	s_mov_b32 s56, s61
	s_and_b64 vcc, exec, s[6:7]
	s_cbranch_vccz .LBB7_1199

.LBB7_1219:
	s_add_i32 s56, s52, 2
	s_add_u32 s29, s16, 0xfffc0080
	s_addc_u32 s37, s17, -1
	s_add_i32 s57, 0, 0x10000
	s_cmp_eq_u32 s84, s52
	s_cselect_b32 s55, s10, s37
	s_cselect_b32 s54, s13, s29
	s_cselect_b32 s53, s15, s39
	s_cselect_b32 s52, s28, s38
	s_add_i32 s29, 0, 0x14000
	v_add_u32_e32 v152, s57, v157
	v_add_u32_e32 v170, s29, v157
	ds_read_b128 v[140:143], v152
	ds_read_b128 v[144:147], v152 offset:1024
	ds_read_b128 v[148:151], v152 offset:2048
	ds_read_b128 v[152:155], v152 offset:3072
	ds_read_b128 v[184:187], v170
	ds_read_b128 v[188:191], v170 offset:1024
	ds_read_b128 v[192:195], v170 offset:2048
	ds_read_b128 v[196:199], v170 offset:3072
	v_lshl_add_u64 v[170:171], s[16:17], 0, v[136:137]
	s_add_i32 m0, s5, 0xc000
	ds_read_b128 v[204:207], v181
	ds_read_b128 v[208:211], v181 offset:1024
	ds_read_b128 v[212:215], v181 offset:2048
	ds_read_b128 v[216:219], v181 offset:3072
	ds_read_b128 v[220:223], v181 offset:4096
	ds_read_b128 v[224:227], v181 offset:5120
	ds_read_b128 v[228:231], v181 offset:6144
	ds_read_b128 v[232:235], v181 offset:7168
	global_load_lds_dwordx4 v[170:171], off
	v_lshl_add_u64 v[170:171], s[16:17], 0, v[138:139]
	s_add_i32 m0, s5, 0xe000
	s_nop 0
	global_load_lds_dwordx4 v[170:171], off
	s_waitcnt vmcnt(8)
	s_waitcnt lgkmcnt(0)
	s_setprio 1
	s_barrier
	v_mfma_f32_16x16x32_bf16 v[126:129], v[140:143], v[204:207], v[126:129]
	v_mfma_f32_16x16x32_bf16 v[122:125], v[148:151], v[204:207], v[122:125]
	v_mfma_f32_16x16x32_bf16 v[118:121], v[140:143], v[212:215], v[118:121]
	v_mfma_f32_16x16x32_bf16 v[114:117], v[148:151], v[212:215], v[114:117]
	v_mfma_f32_16x16x32_bf16 v[106:109], v[140:143], v[220:223], v[106:109]
	v_mfma_f32_16x16x32_bf16 v[98:101], v[148:151], v[220:223], v[98:101]
	v_mfma_f32_16x16x32_bf16 v[90:93], v[140:143], v[228:231], v[90:93]
	v_mfma_f32_16x16x32_bf16 v[82:85], v[148:151], v[228:231], v[82:85]
	v_mfma_f32_16x16x32_bf16 v[126:129], v[144:147], v[208:211], v[126:129]
	v_mfma_f32_16x16x32_bf16 v[122:125], v[152:155], v[208:211], v[122:125]
	v_mfma_f32_16x16x32_bf16 v[118:121], v[144:147], v[216:219], v[118:121]
	v_mfma_f32_16x16x32_bf16 v[114:117], v[152:155], v[216:219], v[114:117]
	v_mfma_f32_16x16x32_bf16 v[106:109], v[144:147], v[224:227], v[106:109]
	v_mfma_f32_16x16x32_bf16 v[98:101], v[152:155], v[224:227], v[98:101]
	v_mfma_f32_16x16x32_bf16 v[90:93], v[144:147], v[232:235], v[90:93]
	v_mfma_f32_16x16x32_bf16 v[82:85], v[152:155], v[232:235], v[82:85]
	v_mfma_f32_16x16x32_bf16 v[110:113], v[184:187], v[204:207], v[110:113]
	v_mfma_f32_16x16x32_bf16 v[102:105], v[192:195], v[204:207], v[102:105]
	v_mfma_f32_16x16x32_bf16 v[94:97], v[184:187], v[212:215], v[94:97]
	v_mfma_f32_16x16x32_bf16 v[86:89], v[192:195], v[212:215], v[86:89]
	v_mfma_f32_16x16x32_bf16 v[78:81], v[184:187], v[220:223], v[78:81]
	v_mfma_f32_16x16x32_bf16 v[74:77], v[192:195], v[220:223], v[74:77]
	v_mfma_f32_16x16x32_bf16 v[70:73], v[184:187], v[228:231], v[70:73]
	v_mfma_f32_16x16x32_bf16 v[66:69], v[192:195], v[228:231], v[66:69]
	v_mfma_f32_16x16x32_bf16 v[110:113], v[188:191], v[208:211], v[110:113]
	v_mfma_f32_16x16x32_bf16 v[102:105], v[196:199], v[208:211], v[102:105]
	v_mfma_f32_16x16x32_bf16 v[94:97], v[188:191], v[216:219], v[94:97]
	v_mfma_f32_16x16x32_bf16 v[86:89], v[196:199], v[216:219], v[86:89]
	v_mfma_f32_16x16x32_bf16 v[78:81], v[188:191], v[224:227], v[78:81]
	v_mfma_f32_16x16x32_bf16 v[74:77], v[196:199], v[224:227], v[74:77]
	v_mfma_f32_16x16x32_bf16 v[70:73], v[188:191], v[232:235], v[70:73]
	v_mfma_f32_16x16x32_bf16 v[66:69], v[196:199], v[232:235], v[66:69]
	s_barrier
	s_setprio 0
	s_add_i32 s37, s57, s4
	v_lshl_add_u64 v[170:171], s[52:53], 0, v[0:1]
	s_mov_b32 m0, s37
	ds_read_b128 v[204:207], v181 offset:16384
	ds_read_b128 v[208:211], v181 offset:17408
	ds_read_b128 v[212:215], v181 offset:18432
	ds_read_b128 v[216:219], v181 offset:19456
	ds_read_b128 v[220:223], v181 offset:20480
	ds_read_b128 v[224:227], v181 offset:21504
	ds_read_b128 v[228:231], v181 offset:22528
	ds_read_b128 v[232:235], v181 offset:23552
	global_load_lds_dwordx4 v[170:171], off
	s_add_i32 m0, s37, 0x2000
	s_add_u32 s74, s52, 0x40000
	v_lshl_add_u64 v[172:173], s[52:53], 0, v[130:131]
	s_addc_u32 s75, s53, 0
	s_add_i32 s29, s29, s4
	global_load_lds_dwordx4 v[172:173], off
	v_lshl_add_u64 v[236:237], s[74:75], 0, v[0:1]
	s_mov_b32 m0, s29
	v_lshl_add_u64 v[238:239], s[54:55], 0, v[132:133]
	global_load_lds_dwordx4 v[236:237], off
	v_lshl_add_u64 v[236:237], s[74:75], 0, v[130:131]
	s_add_i32 m0, s29, 0x2000
	s_nop 0
	global_load_lds_dwordx4 v[236:237], off
	v_lshl_add_u64 v[236:237], s[54:55], 0, v[134:135]
	s_mov_b32 m0, s5
	s_nop 0
	global_load_lds_dwordx4 v[236:237], off
	s_mov_b32 m0, s20
	s_nop 0
	global_load_lds_dwordx4 v[238:239], off
	s_waitcnt vmcnt(8)
	s_waitcnt lgkmcnt(0)
	s_setprio 1
	s_barrier
	v_mfma_f32_16x16x32_bf16 v[62:65], v[140:143], v[204:207], v[62:65]
	v_mfma_f32_16x16x32_bf16 v[58:61], v[148:151], v[204:207], v[58:61]
	v_mfma_f32_16x16x32_bf16 v[54:57], v[140:143], v[212:215], v[54:57]
	v_mfma_f32_16x16x32_bf16 v[50:53], v[148:151], v[212:215], v[50:53]
	v_mfma_f32_16x16x32_bf16 v[42:45], v[140:143], v[220:223], v[42:45]
	v_mfma_f32_16x16x32_bf16 v[34:37], v[148:151], v[220:223], v[34:37]
	v_mfma_f32_16x16x32_bf16 v[26:29], v[140:143], v[228:231], v[26:29]
	v_mfma_f32_16x16x32_bf16 v[18:21], v[148:151], v[228:231], v[18:21]
	v_mfma_f32_16x16x32_bf16 v[62:65], v[144:147], v[208:211], v[62:65]
	v_mfma_f32_16x16x32_bf16 v[58:61], v[152:155], v[208:211], v[58:61]
	v_mfma_f32_16x16x32_bf16 v[54:57], v[144:147], v[216:219], v[54:57]
	v_mfma_f32_16x16x32_bf16 v[50:53], v[152:155], v[216:219], v[50:53]
	v_mfma_f32_16x16x32_bf16 v[42:45], v[144:147], v[224:227], v[42:45]
	v_mfma_f32_16x16x32_bf16 v[34:37], v[152:155], v[224:227], v[34:37]
	v_mfma_f32_16x16x32_bf16 v[26:29], v[144:147], v[232:235], v[26:29]
	v_mfma_f32_16x16x32_bf16 v[18:21], v[152:155], v[232:235], v[18:21]
	v_mfma_f32_16x16x32_bf16 v[46:49], v[184:187], v[204:207], v[46:49]
	v_mfma_f32_16x16x32_bf16 v[38:41], v[192:195], v[204:207], v[38:41]
	v_mfma_f32_16x16x32_bf16 v[30:33], v[184:187], v[212:215], v[30:33]
	v_mfma_f32_16x16x32_bf16 v[22:25], v[192:195], v[212:215], v[22:25]
	v_mfma_f32_16x16x32_bf16 v[14:17], v[184:187], v[220:223], v[14:17]
	v_mfma_f32_16x16x32_bf16 v[10:13], v[192:195], v[220:223], v[10:13]
	v_mfma_f32_16x16x32_bf16 v[6:9], v[184:187], v[228:231], v[6:9]
	v_mfma_f32_16x16x32_bf16 v[2:5], v[192:195], v[228:231], v[2:5]
	v_mfma_f32_16x16x32_bf16 v[46:49], v[188:191], v[208:211], v[46:49]
	v_mfma_f32_16x16x32_bf16 v[38:41], v[196:199], v[208:211], v[38:41]
	v_mfma_f32_16x16x32_bf16 v[30:33], v[188:191], v[216:219], v[30:33]
	v_mfma_f32_16x16x32_bf16 v[22:25], v[196:199], v[216:219], v[22:25]
	v_mfma_f32_16x16x32_bf16 v[14:17], v[188:191], v[224:227], v[14:17]
	v_mfma_f32_16x16x32_bf16 v[10:13], v[196:199], v[224:227], v[10:13]
	v_mfma_f32_16x16x32_bf16 v[6:9], v[188:191], v[232:235], v[6:9]
	v_mfma_f32_16x16x32_bf16 v[2:5], v[196:199], v[232:235], v[2:5]
	s_barrier
	s_setprio 0
	s_add_i32 s29, 0, 0x18000
	s_add_i32 s37, 0, 0x1c000
	v_add_u32_e32 v152, s29, v157
	v_add_u32_e32 v183, s37, v157
	ds_read_b128 v[140:143], v152
	ds_read_b128 v[144:147], v152 offset:1024
	ds_read_b128 v[148:151], v152 offset:2048
	ds_read_b128 v[152:155], v152 offset:3072
	ds_read_b128 v[184:187], v183
	ds_read_b128 v[188:191], v183 offset:1024
	ds_read_b128 v[192:195], v183 offset:2048
	ds_read_b128 v[196:199], v183 offset:3072
	s_add_u32 s54, s54, 0x40000
	s_addc_u32 s55, s55, 0
	s_mov_b32 m0, s22
	v_lshl_add_u64 v[240:241], s[54:55], 0, v[134:135]
	ds_read_b128 v[204:207], v181 offset:32768
	ds_read_b128 v[208:211], v181 offset:33792
	ds_read_b128 v[212:215], v181 offset:34816
	ds_read_b128 v[216:219], v181 offset:35840
	ds_read_b128 v[220:223], v181 offset:36864
	ds_read_b128 v[224:227], v181 offset:37888
	ds_read_b128 v[228:231], v181 offset:38912
	ds_read_b128 v[232:235], v181 offset:39936
	global_load_lds_dwordx4 v[240:241], off
	v_lshl_add_u64 v[240:241], s[54:55], 0, v[132:133]
	s_mov_b32 m0, s23
	s_nop 0
	global_load_lds_dwordx4 v[240:241], off
	s_waitcnt vmcnt(8)
	s_waitcnt lgkmcnt(0)
	s_setprio 1
	s_barrier
	v_mfma_f32_16x16x32_bf16 v[126:129], v[140:143], v[204:207], v[126:129]
	v_mfma_f32_16x16x32_bf16 v[122:125], v[148:151], v[204:207], v[122:125]
	v_mfma_f32_16x16x32_bf16 v[118:121], v[140:143], v[212:215], v[118:121]
	v_mfma_f32_16x16x32_bf16 v[114:117], v[148:151], v[212:215], v[114:117]
	v_mfma_f32_16x16x32_bf16 v[106:109], v[140:143], v[220:223], v[106:109]
	v_mfma_f32_16x16x32_bf16 v[98:101], v[148:151], v[220:223], v[98:101]
	v_mfma_f32_16x16x32_bf16 v[90:93], v[140:143], v[228:231], v[90:93]
	v_mfma_f32_16x16x32_bf16 v[82:85], v[148:151], v[228:231], v[82:85]
	v_mfma_f32_16x16x32_bf16 v[126:129], v[144:147], v[208:211], v[126:129]
	v_mfma_f32_16x16x32_bf16 v[122:125], v[152:155], v[208:211], v[122:125]
	v_mfma_f32_16x16x32_bf16 v[118:121], v[144:147], v[216:219], v[118:121]
	v_mfma_f32_16x16x32_bf16 v[114:117], v[152:155], v[216:219], v[114:117]
	v_mfma_f32_16x16x32_bf16 v[106:109], v[144:147], v[224:227], v[106:109]
	v_mfma_f32_16x16x32_bf16 v[98:101], v[152:155], v[224:227], v[98:101]
	v_mfma_f32_16x16x32_bf16 v[90:93], v[144:147], v[232:235], v[90:93]
	v_mfma_f32_16x16x32_bf16 v[82:85], v[152:155], v[232:235], v[82:85]
	v_mfma_f32_16x16x32_bf16 v[110:113], v[184:187], v[204:207], v[110:113]
	v_mfma_f32_16x16x32_bf16 v[102:105], v[192:195], v[204:207], v[102:105]
	v_mfma_f32_16x16x32_bf16 v[94:97], v[184:187], v[212:215], v[94:97]
	v_mfma_f32_16x16x32_bf16 v[86:89], v[192:195], v[212:215], v[86:89]
	v_mfma_f32_16x16x32_bf16 v[78:81], v[184:187], v[220:223], v[78:81]
	v_mfma_f32_16x16x32_bf16 v[74:77], v[192:195], v[220:223], v[74:77]
	v_mfma_f32_16x16x32_bf16 v[70:73], v[184:187], v[228:231], v[70:73]
	v_mfma_f32_16x16x32_bf16 v[66:69], v[192:195], v[228:231], v[66:69]
	v_mfma_f32_16x16x32_bf16 v[110:113], v[188:191], v[208:211], v[110:113]
	v_mfma_f32_16x16x32_bf16 v[102:105], v[196:199], v[208:211], v[102:105]
	v_mfma_f32_16x16x32_bf16 v[94:97], v[188:191], v[216:219], v[94:97]
	v_mfma_f32_16x16x32_bf16 v[86:89], v[196:199], v[216:219], v[86:89]
	v_mfma_f32_16x16x32_bf16 v[78:81], v[188:191], v[224:227], v[78:81]
	v_mfma_f32_16x16x32_bf16 v[74:77], v[196:199], v[224:227], v[74:77]
	v_mfma_f32_16x16x32_bf16 v[70:73], v[188:191], v[232:235], v[70:73]
	v_mfma_f32_16x16x32_bf16 v[66:69], v[196:199], v[232:235], v[66:69]
	s_barrier
	s_setprio 0
	s_add_i32 s29, s29, s4
	v_lshl_add_u64 v[170:171], v[170:171], 0, s[24:25]
	s_mov_b32 m0, s29
	ds_read_b128 v[204:207], v181 offset:49152
	ds_read_b128 v[208:211], v181 offset:50176
	ds_read_b128 v[212:215], v181 offset:51200
	ds_read_b128 v[216:219], v181 offset:52224
	ds_read_b128 v[220:223], v181 offset:53248
	ds_read_b128 v[224:227], v181 offset:54272
	ds_read_b128 v[228:231], v181 offset:55296
	ds_read_b128 v[232:235], v181 offset:56320
	global_load_lds_dwordx4 v[170:171], off
	s_add_i32 m0, s29, 0x2000
	s_add_u32 s52, s52, 0x40080
	v_lshl_add_u64 v[170:171], v[172:173], 0, s[24:25]
	s_addc_u32 s53, s53, 0
	s_add_i32 s29, s37, s4
	global_load_lds_dwordx4 v[170:171], off
	v_lshl_add_u64 v[170:171], s[52:53], 0, v[0:1]
	s_mov_b32 m0, s29
	s_nop 0
	global_load_lds_dwordx4 v[170:171], off
	v_lshl_add_u64 v[170:171], s[52:53], 0, v[130:131]
	s_add_i32 m0, s29, 0x2000
	s_nop 0
	global_load_lds_dwordx4 v[170:171], off
	v_lshl_add_u64 v[170:171], v[236:237], 0, s[24:25]
	s_mov_b32 m0, s31
	s_nop 0
	global_load_lds_dwordx4 v[170:171], off
	v_lshl_add_u64 v[170:171], v[238:239], 0, s[24:25]
	s_mov_b32 m0, s33
	s_nop 0
	global_load_lds_dwordx4 v[170:171], off
	s_waitcnt vmcnt(8)
	s_waitcnt lgkmcnt(0)
	s_setprio 1
	s_barrier
	v_mfma_f32_16x16x32_bf16 v[62:65], v[140:143], v[204:207], v[62:65]
	v_mfma_f32_16x16x32_bf16 v[58:61], v[148:151], v[204:207], v[58:61]
	v_mfma_f32_16x16x32_bf16 v[54:57], v[140:143], v[212:215], v[54:57]
	v_mfma_f32_16x16x32_bf16 v[50:53], v[148:151], v[212:215], v[50:53]
	v_mfma_f32_16x16x32_bf16 v[42:45], v[140:143], v[220:223], v[42:45]
	v_mfma_f32_16x16x32_bf16 v[34:37], v[148:151], v[220:223], v[34:37]
	v_mfma_f32_16x16x32_bf16 v[26:29], v[140:143], v[228:231], v[26:29]
	v_mfma_f32_16x16x32_bf16 v[18:21], v[148:151], v[228:231], v[18:21]
	v_mfma_f32_16x16x32_bf16 v[62:65], v[144:147], v[208:211], v[62:65]
	v_mfma_f32_16x16x32_bf16 v[58:61], v[152:155], v[208:211], v[58:61]
	v_mfma_f32_16x16x32_bf16 v[54:57], v[144:147], v[216:219], v[54:57]
	v_mfma_f32_16x16x32_bf16 v[50:53], v[152:155], v[216:219], v[50:53]
	v_mfma_f32_16x16x32_bf16 v[42:45], v[144:147], v[224:227], v[42:45]
	v_mfma_f32_16x16x32_bf16 v[34:37], v[152:155], v[224:227], v[34:37]
	v_mfma_f32_16x16x32_bf16 v[26:29], v[144:147], v[232:235], v[26:29]
	v_mfma_f32_16x16x32_bf16 v[18:21], v[152:155], v[232:235], v[18:21]
	v_mfma_f32_16x16x32_bf16 v[46:49], v[184:187], v[204:207], v[46:49]
	v_mfma_f32_16x16x32_bf16 v[38:41], v[192:195], v[204:207], v[38:41]
	v_mfma_f32_16x16x32_bf16 v[30:33], v[184:187], v[212:215], v[30:33]
	v_mfma_f32_16x16x32_bf16 v[22:25], v[192:195], v[212:215], v[22:25]
	v_mfma_f32_16x16x32_bf16 v[14:17], v[184:187], v[220:223], v[14:17]
	v_mfma_f32_16x16x32_bf16 v[10:13], v[192:195], v[220:223], v[10:13]
	v_mfma_f32_16x16x32_bf16 v[6:9], v[184:187], v[228:231], v[6:9]
	v_mfma_f32_16x16x32_bf16 v[2:5], v[192:195], v[228:231], v[2:5]
	v_mfma_f32_16x16x32_bf16 v[46:49], v[188:191], v[208:211], v[46:49]
	v_mfma_f32_16x16x32_bf16 v[38:41], v[196:199], v[208:211], v[38:41]
	v_mfma_f32_16x16x32_bf16 v[30:33], v[188:191], v[216:219], v[30:33]
	v_mfma_f32_16x16x32_bf16 v[22:25], v[196:199], v[216:219], v[22:25]
	v_mfma_f32_16x16x32_bf16 v[14:17], v[188:191], v[224:227], v[14:17]
	v_mfma_f32_16x16x32_bf16 v[10:13], v[196:199], v[224:227], v[10:13]
	v_mfma_f32_16x16x32_bf16 v[6:9], v[188:191], v[232:235], v[6:9]
	v_mfma_f32_16x16x32_bf16 v[2:5], v[196:199], v[232:235], v[2:5]
	s_barrier
	s_setprio 0
	s_add_u32 s16, s16, 0x100
	s_addc_u32 s17, s17, 0
	s_add_u32 s38, s38, 0x100
	s_addc_u32 s39, s39, 0
	s_cmp_ge_i32 s56, s3
	s_mov_b32 s52, s56
	s_cbranch_scc0 .LBB7_1219
	v_pk_mul_f32 v[128:129], v[128:129], s[36:37] op_sel_hi:[1,0]
	v_pk_mul_f32 v[144:145], v[126:127], s[36:37] op_sel_hi:[1,0]
	v_pk_mul_f32 v[126:127], v[124:125], s[36:37] op_sel_hi:[1,0]
	v_pk_mul_f32 v[140:141], v[122:123], s[36:37] op_sel_hi:[1,0]
	v_pk_mul_f32 v[146:147], v[112:113], s[36:37] op_sel_hi:[1,0]
	v_pk_mul_f32 v[150:151], v[110:111], s[36:37] op_sel_hi:[1,0]
	v_pk_mul_f32 v[142:143], v[104:105], s[36:37] op_sel_hi:[1,0]
	v_pk_mul_f32 v[148:149], v[102:103], s[36:37] op_sel_hi:[1,0]
	v_pk_mul_f32 v[120:121], v[120:121], s[36:37] op_sel_hi:[1,0]
	v_pk_mul_f32 v[118:119], v[118:119], s[36:37] op_sel_hi:[1,0]
	v_pk_mul_f32 v[110:111], v[116:117], s[36:37] op_sel_hi:[1,0]
	v_pk_mul_f32 v[112:113], v[114:115], s[36:37] op_sel_hi:[1,0]
	v_pk_mul_f32 v[116:117], v[96:97], s[36:37] op_sel_hi:[1,0]
	v_pk_mul_f32 v[124:125], v[94:95], s[36:37] op_sel_hi:[1,0]
	v_pk_mul_f32 v[114:115], v[88:89], s[36:37] op_sel_hi:[1,0]
	v_pk_mul_f32 v[122:123], v[86:87], s[36:37] op_sel_hi:[1,0]
	v_pk_mul_f32 v[102:103], v[108:109], s[36:37] op_sel_hi:[1,0]
	v_pk_mul_f32 v[104:105], v[106:107], s[36:37] op_sel_hi:[1,0]
	v_pk_mul_f32 v[94:95], v[100:101], s[36:37] op_sel_hi:[1,0]
	v_pk_mul_f32 v[96:97], v[98:99], s[36:37] op_sel_hi:[1,0]
	v_pk_mul_f32 v[100:101], v[80:81], s[36:37] op_sel_hi:[1,0]
	v_pk_mul_f32 v[108:109], v[78:79], s[36:37] op_sel_hi:[1,0]
	v_pk_mul_f32 v[98:99], v[76:77], s[36:37] op_sel_hi:[1,0]
	v_pk_mul_f32 v[106:107], v[74:75], s[36:37] op_sel_hi:[1,0]
	v_pk_mul_f32 v[86:87], v[92:93], s[36:37] op_sel_hi:[1,0]
	v_pk_mul_f32 v[88:89], v[90:91], s[36:37] op_sel_hi:[1,0]
	v_pk_mul_f32 v[76:77], v[84:85], s[36:37] op_sel_hi:[1,0]
	v_pk_mul_f32 v[80:81], v[82:83], s[36:37] op_sel_hi:[1,0]
	v_pk_mul_f32 v[84:85], v[72:73], s[36:37] op_sel_hi:[1,0]
	v_pk_mul_f32 v[92:93], v[70:71], s[36:37] op_sel_hi:[1,0]
	v_pk_mul_f32 v[82:83], v[68:69], s[36:37] op_sel_hi:[1,0]
	v_pk_mul_f32 v[90:91], v[66:67], s[36:37] op_sel_hi:[1,0]
	v_pk_mul_f32 v[66:67], v[64:65], s[36:37] op_sel_hi:[1,0]
	v_pk_mul_f32 v[72:73], v[62:63], s[36:37] op_sel_hi:[1,0]
	v_pk_mul_f32 v[62:63], v[60:61], s[36:37] op_sel_hi:[1,0]
	v_pk_mul_f32 v[64:65], v[58:59], s[36:37] op_sel_hi:[1,0]
	v_pk_mul_f32 v[70:71], v[48:49], s[36:37] op_sel_hi:[1,0]
	v_pk_mul_f32 v[78:79], v[46:47], s[36:37] op_sel_hi:[1,0]
	v_pk_mul_f32 v[68:69], v[40:41], s[36:37] op_sel_hi:[1,0]
	v_pk_mul_f32 v[74:75], v[38:39], s[36:37] op_sel_hi:[1,0]
	v_pk_mul_f32 v[56:57], v[56:57], s[36:37] op_sel_hi:[1,0]
	v_pk_mul_f32 v[54:55], v[54:55], s[36:37] op_sel_hi:[1,0]
	v_pk_mul_f32 v[46:47], v[52:53], s[36:37] op_sel_hi:[1,0]
	v_pk_mul_f32 v[48:49], v[50:51], s[36:37] op_sel_hi:[1,0]
	v_pk_mul_f32 v[52:53], v[32:33], s[36:37] op_sel_hi:[1,0]
	v_pk_mul_f32 v[60:61], v[30:31], s[36:37] op_sel_hi:[1,0]
	v_pk_mul_f32 v[50:51], v[24:25], s[36:37] op_sel_hi:[1,0]
	v_pk_mul_f32 v[58:59], v[22:23], s[36:37] op_sel_hi:[1,0]
	v_pk_mul_f32 v[30:31], v[44:45], s[36:37] op_sel_hi:[1,0]
	v_pk_mul_f32 v[38:39], v[42:43], s[36:37] op_sel_hi:[1,0]
	v_pk_mul_f32 v[22:23], v[36:37], s[36:37] op_sel_hi:[1,0]
	v_pk_mul_f32 v[24:25], v[34:35], s[36:37] op_sel_hi:[1,0]
	v_pk_mul_f32 v[34:35], v[16:17], s[36:37] op_sel_hi:[1,0]
	v_pk_mul_f32 v[40:41], v[14:15], s[36:37] op_sel_hi:[1,0]
	v_pk_mul_f32 v[32:33], v[12:13], s[36:37] op_sel_hi:[1,0]
	v_pk_mul_f32 v[36:37], v[10:11], s[36:37] op_sel_hi:[1,0]
	v_pk_mul_f32 v[14:15], v[28:29], s[36:37] op_sel_hi:[1,0]
	v_pk_mul_f32 v[16:17], v[26:27], s[36:37] op_sel_hi:[1,0]
	v_pk_mul_f32 v[10:11], v[20:21], s[36:37] op_sel_hi:[1,0]
	v_pk_mul_f32 v[12:13], v[18:19], s[36:37] op_sel_hi:[1,0]
	v_pk_mul_f32 v[8:9], v[8:9], s[36:37] op_sel_hi:[1,0]
	v_pk_mul_f32 v[6:7], v[6:7], s[36:37] op_sel_hi:[1,0]
	v_pk_mul_f32 v[4:5], v[4:5], s[36:37] op_sel_hi:[1,0]
	v_pk_mul_f32 v[2:3], v[2:3], s[36:37] op_sel_hi:[1,0]
	s_mov_b32 s56, s61
	s_and_b64 vcc, exec, s[6:7]
	s_cbranch_vccz .LBB7_1222

.LBB7_1274:
	s_add_i32 s72, s50, 2
	s_add_u32 s29, s48, 0xfffc0080
	s_addc_u32 s37, s49, -1
	s_add_i32 s73, 0, 0x10000
	s_cmp_eq_u32 s33, s50
	s_cselect_b32 s53, s13, s37
	s_cselect_b32 s52, s15, s29
	s_cselect_b32 s51, s54, s57
	s_cselect_b32 s50, s55, s56
	s_add_i32 s29, 0, 0x14000
	v_add_u32_e32 v156, s73, v141
	v_add_u32_e32 v160, s29, v141
	ds_read_b128 v[144:147], v156
	ds_read_b128 v[148:151], v156 offset:1024
	ds_read_b128 v[152:155], v156 offset:2048
	ds_read_b128 v[156:159], v156 offset:3072
	ds_read_b128 v[174:177], v160
	ds_read_b128 v[178:181], v160 offset:1024
	ds_read_b128 v[182:185], v160 offset:2048
	ds_read_b128 v[186:189], v160 offset:3072
	v_lshl_add_u64 v[160:161], s[48:49], 0, v[136:137]
	s_add_i32 m0, s5, 0xc000
	ds_read_b128 v[190:193], v143
	ds_read_b128 v[194:197], v143 offset:1024
	ds_read_b128 v[204:207], v143 offset:2048
	ds_read_b128 v[208:211], v143 offset:3072
	ds_read_b128 v[212:215], v143 offset:4096
	ds_read_b128 v[216:219], v143 offset:5120
	ds_read_b128 v[220:223], v143 offset:6144
	ds_read_b128 v[224:227], v143 offset:7168
	global_load_lds_dwordx4 v[160:161], off
	v_lshl_add_u64 v[160:161], s[48:49], 0, v[138:139]
	s_add_i32 m0, s5, 0xe000
	s_nop 0
	global_load_lds_dwordx4 v[160:161], off
	s_waitcnt vmcnt(8)
	s_waitcnt lgkmcnt(0)
	s_setprio 1
	s_barrier
	v_mfma_f32_16x16x32_bf16 v[126:129], v[144:147], v[190:193], v[126:129]
	v_mfma_f32_16x16x32_bf16 v[122:125], v[152:155], v[190:193], v[122:125]
	v_mfma_f32_16x16x32_bf16 v[110:113], v[144:147], v[204:207], v[110:113]
	v_mfma_f32_16x16x32_bf16 v[106:109], v[152:155], v[204:207], v[106:109]
	v_mfma_f32_16x16x32_bf16 v[94:97], v[144:147], v[212:215], v[94:97]
	v_mfma_f32_16x16x32_bf16 v[90:93], v[152:155], v[212:215], v[90:93]
	v_mfma_f32_16x16x32_bf16 v[78:81], v[144:147], v[220:223], v[78:81]
	v_mfma_f32_16x16x32_bf16 v[74:77], v[152:155], v[220:223], v[74:77]
	v_mfma_f32_16x16x32_bf16 v[126:129], v[148:151], v[194:197], v[126:129]
	v_mfma_f32_16x16x32_bf16 v[122:125], v[156:159], v[194:197], v[122:125]
	v_mfma_f32_16x16x32_bf16 v[110:113], v[148:151], v[208:211], v[110:113]
	v_mfma_f32_16x16x32_bf16 v[106:109], v[156:159], v[208:211], v[106:109]
	v_mfma_f32_16x16x32_bf16 v[94:97], v[148:151], v[216:219], v[94:97]
	v_mfma_f32_16x16x32_bf16 v[90:93], v[156:159], v[216:219], v[90:93]
	v_mfma_f32_16x16x32_bf16 v[78:81], v[148:151], v[224:227], v[78:81]
	v_mfma_f32_16x16x32_bf16 v[74:77], v[156:159], v[224:227], v[74:77]
	v_mfma_f32_16x16x32_bf16 v[118:121], v[174:177], v[190:193], v[118:121]
	v_mfma_f32_16x16x32_bf16 v[114:117], v[182:185], v[190:193], v[114:117]
	v_mfma_f32_16x16x32_bf16 v[102:105], v[174:177], v[204:207], v[102:105]
	v_mfma_f32_16x16x32_bf16 v[98:101], v[182:185], v[204:207], v[98:101]
	v_mfma_f32_16x16x32_bf16 v[86:89], v[174:177], v[212:215], v[86:89]
	v_mfma_f32_16x16x32_bf16 v[82:85], v[182:185], v[212:215], v[82:85]
	v_mfma_f32_16x16x32_bf16 v[70:73], v[174:177], v[220:223], v[70:73]
	v_mfma_f32_16x16x32_bf16 v[66:69], v[182:185], v[220:223], v[66:69]
	v_mfma_f32_16x16x32_bf16 v[118:121], v[178:181], v[194:197], v[118:121]
	v_mfma_f32_16x16x32_bf16 v[114:117], v[186:189], v[194:197], v[114:117]
	v_mfma_f32_16x16x32_bf16 v[102:105], v[178:181], v[208:211], v[102:105]
	v_mfma_f32_16x16x32_bf16 v[98:101], v[186:189], v[208:211], v[98:101]
	v_mfma_f32_16x16x32_bf16 v[86:89], v[178:181], v[216:219], v[86:89]
	v_mfma_f32_16x16x32_bf16 v[82:85], v[186:189], v[216:219], v[82:85]
	v_mfma_f32_16x16x32_bf16 v[70:73], v[178:181], v[224:227], v[70:73]
	v_mfma_f32_16x16x32_bf16 v[66:69], v[186:189], v[224:227], v[66:69]
	s_barrier
	s_setprio 0
	s_add_i32 s37, s73, s4
	v_lshl_add_u64 v[160:161], s[50:51], 0, v[0:1]
	s_mov_b32 m0, s37
	ds_read_b128 v[190:193], v143 offset:16384
	ds_read_b128 v[194:197], v143 offset:17408
	ds_read_b128 v[204:207], v143 offset:18432
	ds_read_b128 v[208:211], v143 offset:19456
	ds_read_b128 v[212:215], v143 offset:20480
	ds_read_b128 v[216:219], v143 offset:21504
	ds_read_b128 v[220:223], v143 offset:22528
	ds_read_b128 v[224:227], v143 offset:23552
	global_load_lds_dwordx4 v[160:161], off
	s_add_i32 m0, s37, 0x2000
	s_add_u32 s74, s50, 0x100000
	v_lshl_add_u64 v[170:171], s[50:51], 0, v[130:131]
	s_addc_u32 s75, s51, 0
	s_add_i32 s29, s29, s4
	global_load_lds_dwordx4 v[170:171], off
	v_lshl_add_u64 v[172:173], s[74:75], 0, v[0:1]
	s_mov_b32 m0, s29
	v_lshl_add_u64 v[198:199], s[52:53], 0, v[132:133]
	global_load_lds_dwordx4 v[172:173], off
	v_lshl_add_u64 v[172:173], s[74:75], 0, v[130:131]
	s_add_i32 m0, s29, 0x2000
	s_nop 0
	global_load_lds_dwordx4 v[172:173], off
	v_lshl_add_u64 v[172:173], s[52:53], 0, v[134:135]
	s_mov_b32 m0, s5
	s_nop 0
	global_load_lds_dwordx4 v[172:173], off
	s_mov_b32 m0, s10
	s_nop 0
	global_load_lds_dwordx4 v[198:199], off
	s_waitcnt vmcnt(8)
	s_waitcnt lgkmcnt(0)
	s_setprio 1
	s_barrier
	v_mfma_f32_16x16x32_bf16 v[62:65], v[144:147], v[190:193], v[62:65]
	v_mfma_f32_16x16x32_bf16 v[58:61], v[152:155], v[190:193], v[58:61]
	v_mfma_f32_16x16x32_bf16 v[46:49], v[144:147], v[204:207], v[46:49]
	v_mfma_f32_16x16x32_bf16 v[42:45], v[152:155], v[204:207], v[42:45]
	v_mfma_f32_16x16x32_bf16 v[30:33], v[144:147], v[212:215], v[30:33]
	v_mfma_f32_16x16x32_bf16 v[26:29], v[152:155], v[212:215], v[26:29]
	v_mfma_f32_16x16x32_bf16 v[14:17], v[144:147], v[220:223], v[14:17]
	v_mfma_f32_16x16x32_bf16 v[10:13], v[152:155], v[220:223], v[10:13]
	v_mfma_f32_16x16x32_bf16 v[62:65], v[148:151], v[194:197], v[62:65]
	v_mfma_f32_16x16x32_bf16 v[58:61], v[156:159], v[194:197], v[58:61]
	v_mfma_f32_16x16x32_bf16 v[46:49], v[148:151], v[208:211], v[46:49]
	v_mfma_f32_16x16x32_bf16 v[42:45], v[156:159], v[208:211], v[42:45]
	v_mfma_f32_16x16x32_bf16 v[30:33], v[148:151], v[216:219], v[30:33]
	v_mfma_f32_16x16x32_bf16 v[26:29], v[156:159], v[216:219], v[26:29]
	v_mfma_f32_16x16x32_bf16 v[14:17], v[148:151], v[224:227], v[14:17]
	v_mfma_f32_16x16x32_bf16 v[10:13], v[156:159], v[224:227], v[10:13]
	v_mfma_f32_16x16x32_bf16 v[54:57], v[174:177], v[190:193], v[54:57]
	v_mfma_f32_16x16x32_bf16 v[50:53], v[182:185], v[190:193], v[50:53]
	v_mfma_f32_16x16x32_bf16 v[38:41], v[174:177], v[204:207], v[38:41]
	v_mfma_f32_16x16x32_bf16 v[34:37], v[182:185], v[204:207], v[34:37]
	v_mfma_f32_16x16x32_bf16 v[22:25], v[174:177], v[212:215], v[22:25]
	v_mfma_f32_16x16x32_bf16 v[18:21], v[182:185], v[212:215], v[18:21]
	v_mfma_f32_16x16x32_bf16 v[6:9], v[174:177], v[220:223], v[6:9]
	v_mfma_f32_16x16x32_bf16 v[2:5], v[182:185], v[220:223], v[2:5]
	v_mfma_f32_16x16x32_bf16 v[54:57], v[178:181], v[194:197], v[54:57]
	v_mfma_f32_16x16x32_bf16 v[50:53], v[186:189], v[194:197], v[50:53]
	v_mfma_f32_16x16x32_bf16 v[38:41], v[178:181], v[208:211], v[38:41]
	v_mfma_f32_16x16x32_bf16 v[34:37], v[186:189], v[208:211], v[34:37]
	v_mfma_f32_16x16x32_bf16 v[22:25], v[178:181], v[216:219], v[22:25]
	v_mfma_f32_16x16x32_bf16 v[18:21], v[186:189], v[216:219], v[18:21]
	v_mfma_f32_16x16x32_bf16 v[6:9], v[178:181], v[224:227], v[6:9]
	v_mfma_f32_16x16x32_bf16 v[2:5], v[186:189], v[224:227], v[2:5]
	s_barrier
	s_setprio 0
	s_add_i32 s29, 0, 0x18000
	s_add_i32 s37, 0, 0x1c000
	v_add_u32_e32 v156, s29, v141
	v_add_u32_e32 v186, s37, v141
	ds_read_b128 v[144:147], v156
	ds_read_b128 v[148:151], v156 offset:1024
	ds_read_b128 v[152:155], v156 offset:2048
	ds_read_b128 v[156:159], v156 offset:3072
	ds_read_b128 v[174:177], v186
	ds_read_b128 v[178:181], v186 offset:1024
	ds_read_b128 v[182:185], v186 offset:2048
	ds_read_b128 v[186:189], v186 offset:3072
	s_add_u32 s52, s52, 0x40000
	s_addc_u32 s53, s53, 0
	s_mov_b32 m0, s20
	v_lshl_add_u64 v[228:229], s[52:53], 0, v[134:135]
	ds_read_b128 v[190:193], v143 offset:32768
	ds_read_b128 v[194:197], v143 offset:33792
	ds_read_b128 v[204:207], v143 offset:34816
	ds_read_b128 v[208:211], v143 offset:35840
	ds_read_b128 v[212:215], v143 offset:36864
	ds_read_b128 v[216:219], v143 offset:37888
	ds_read_b128 v[220:223], v143 offset:38912
	ds_read_b128 v[224:227], v143 offset:39936
	global_load_lds_dwordx4 v[228:229], off
	v_lshl_add_u64 v[228:229], s[52:53], 0, v[132:133]
	s_mov_b32 m0, s22
	s_nop 0
	global_load_lds_dwordx4 v[228:229], off
	s_waitcnt vmcnt(8)
	s_waitcnt lgkmcnt(0)
	s_setprio 1
	s_barrier
	v_mfma_f32_16x16x32_bf16 v[126:129], v[144:147], v[190:193], v[126:129]
	v_mfma_f32_16x16x32_bf16 v[122:125], v[152:155], v[190:193], v[122:125]
	v_mfma_f32_16x16x32_bf16 v[110:113], v[144:147], v[204:207], v[110:113]
	v_mfma_f32_16x16x32_bf16 v[106:109], v[152:155], v[204:207], v[106:109]
	v_mfma_f32_16x16x32_bf16 v[94:97], v[144:147], v[212:215], v[94:97]
	v_mfma_f32_16x16x32_bf16 v[90:93], v[152:155], v[212:215], v[90:93]
	v_mfma_f32_16x16x32_bf16 v[78:81], v[144:147], v[220:223], v[78:81]
	v_mfma_f32_16x16x32_bf16 v[74:77], v[152:155], v[220:223], v[74:77]
	v_mfma_f32_16x16x32_bf16 v[126:129], v[148:151], v[194:197], v[126:129]
	v_mfma_f32_16x16x32_bf16 v[122:125], v[156:159], v[194:197], v[122:125]
	v_mfma_f32_16x16x32_bf16 v[110:113], v[148:151], v[208:211], v[110:113]
	v_mfma_f32_16x16x32_bf16 v[106:109], v[156:159], v[208:211], v[106:109]
	v_mfma_f32_16x16x32_bf16 v[94:97], v[148:151], v[216:219], v[94:97]
	v_mfma_f32_16x16x32_bf16 v[90:93], v[156:159], v[216:219], v[90:93]
	v_mfma_f32_16x16x32_bf16 v[78:81], v[148:151], v[224:227], v[78:81]
	v_mfma_f32_16x16x32_bf16 v[74:77], v[156:159], v[224:227], v[74:77]
	v_mfma_f32_16x16x32_bf16 v[118:121], v[174:177], v[190:193], v[118:121]
	v_mfma_f32_16x16x32_bf16 v[114:117], v[182:185], v[190:193], v[114:117]
	v_mfma_f32_16x16x32_bf16 v[102:105], v[174:177], v[204:207], v[102:105]
	v_mfma_f32_16x16x32_bf16 v[98:101], v[182:185], v[204:207], v[98:101]
	v_mfma_f32_16x16x32_bf16 v[86:89], v[174:177], v[212:215], v[86:89]
	v_mfma_f32_16x16x32_bf16 v[82:85], v[182:185], v[212:215], v[82:85]
	v_mfma_f32_16x16x32_bf16 v[70:73], v[174:177], v[220:223], v[70:73]
	v_mfma_f32_16x16x32_bf16 v[66:69], v[182:185], v[220:223], v[66:69]
	v_mfma_f32_16x16x32_bf16 v[118:121], v[178:181], v[194:197], v[118:121]
	v_mfma_f32_16x16x32_bf16 v[114:117], v[186:189], v[194:197], v[114:117]
	v_mfma_f32_16x16x32_bf16 v[102:105], v[178:181], v[208:211], v[102:105]
	v_mfma_f32_16x16x32_bf16 v[98:101], v[186:189], v[208:211], v[98:101]
	v_mfma_f32_16x16x32_bf16 v[86:89], v[178:181], v[216:219], v[86:89]
	v_mfma_f32_16x16x32_bf16 v[82:85], v[186:189], v[216:219], v[82:85]
	v_mfma_f32_16x16x32_bf16 v[70:73], v[178:181], v[224:227], v[70:73]
	v_mfma_f32_16x16x32_bf16 v[66:69], v[186:189], v[224:227], v[66:69]
	s_barrier
	s_setprio 0
	s_add_i32 s29, s29, s4
	v_lshl_add_u64 v[160:161], v[160:161], 0, s[24:25]
	s_mov_b32 m0, s29
	ds_read_b128 v[190:193], v143 offset:49152
	ds_read_b128 v[194:197], v143 offset:50176
	ds_read_b128 v[204:207], v143 offset:51200
	ds_read_b128 v[208:211], v143 offset:52224
	ds_read_b128 v[212:215], v143 offset:53248
	ds_read_b128 v[216:219], v143 offset:54272
	ds_read_b128 v[220:223], v143 offset:55296
	ds_read_b128 v[224:227], v143 offset:56320
	global_load_lds_dwordx4 v[160:161], off
	s_add_i32 m0, s29, 0x2000
	s_add_u32 s50, s50, 0x100080
	v_lshl_add_u64 v[160:161], v[170:171], 0, s[24:25]
	s_addc_u32 s51, s51, 0
	s_add_i32 s29, s37, s4
	global_load_lds_dwordx4 v[160:161], off
	v_lshl_add_u64 v[160:161], s[50:51], 0, v[0:1]
	s_mov_b32 m0, s29
	s_nop 0
	global_load_lds_dwordx4 v[160:161], off
	v_lshl_add_u64 v[160:161], s[50:51], 0, v[130:131]
	s_add_i32 m0, s29, 0x2000
	s_nop 0
	global_load_lds_dwordx4 v[160:161], off
	v_lshl_add_u64 v[160:161], v[172:173], 0, s[24:25]
	s_mov_b32 m0, s23
	s_nop 0
	global_load_lds_dwordx4 v[160:161], off
	v_lshl_add_u64 v[160:161], v[198:199], 0, s[24:25]
	s_mov_b32 m0, s28
	s_nop 0
	global_load_lds_dwordx4 v[160:161], off
	s_waitcnt vmcnt(8)
	s_waitcnt lgkmcnt(0)
	s_setprio 1
	s_barrier
	v_mfma_f32_16x16x32_bf16 v[62:65], v[144:147], v[190:193], v[62:65]
	v_mfma_f32_16x16x32_bf16 v[58:61], v[152:155], v[190:193], v[58:61]
	v_mfma_f32_16x16x32_bf16 v[46:49], v[144:147], v[204:207], v[46:49]
	v_mfma_f32_16x16x32_bf16 v[42:45], v[152:155], v[204:207], v[42:45]
	v_mfma_f32_16x16x32_bf16 v[30:33], v[144:147], v[212:215], v[30:33]
	v_mfma_f32_16x16x32_bf16 v[26:29], v[152:155], v[212:215], v[26:29]
	v_mfma_f32_16x16x32_bf16 v[14:17], v[144:147], v[220:223], v[14:17]
	v_mfma_f32_16x16x32_bf16 v[10:13], v[152:155], v[220:223], v[10:13]
	v_mfma_f32_16x16x32_bf16 v[62:65], v[148:151], v[194:197], v[62:65]
	v_mfma_f32_16x16x32_bf16 v[58:61], v[156:159], v[194:197], v[58:61]
	v_mfma_f32_16x16x32_bf16 v[46:49], v[148:151], v[208:211], v[46:49]
	v_mfma_f32_16x16x32_bf16 v[42:45], v[156:159], v[208:211], v[42:45]
	v_mfma_f32_16x16x32_bf16 v[30:33], v[148:151], v[216:219], v[30:33]
	v_mfma_f32_16x16x32_bf16 v[26:29], v[156:159], v[216:219], v[26:29]
	v_mfma_f32_16x16x32_bf16 v[14:17], v[148:151], v[224:227], v[14:17]
	v_mfma_f32_16x16x32_bf16 v[10:13], v[156:159], v[224:227], v[10:13]
	v_mfma_f32_16x16x32_bf16 v[54:57], v[174:177], v[190:193], v[54:57]
	v_mfma_f32_16x16x32_bf16 v[50:53], v[182:185], v[190:193], v[50:53]
	v_mfma_f32_16x16x32_bf16 v[38:41], v[174:177], v[204:207], v[38:41]
	v_mfma_f32_16x16x32_bf16 v[34:37], v[182:185], v[204:207], v[34:37]
	v_mfma_f32_16x16x32_bf16 v[22:25], v[174:177], v[212:215], v[22:25]
	v_mfma_f32_16x16x32_bf16 v[18:21], v[182:185], v[212:215], v[18:21]
	v_mfma_f32_16x16x32_bf16 v[6:9], v[174:177], v[220:223], v[6:9]
	v_mfma_f32_16x16x32_bf16 v[2:5], v[182:185], v[220:223], v[2:5]
	v_mfma_f32_16x16x32_bf16 v[54:57], v[178:181], v[194:197], v[54:57]
	v_mfma_f32_16x16x32_bf16 v[50:53], v[186:189], v[194:197], v[50:53]
	v_mfma_f32_16x16x32_bf16 v[38:41], v[178:181], v[208:211], v[38:41]
	v_mfma_f32_16x16x32_bf16 v[34:37], v[186:189], v[208:211], v[34:37]
	v_mfma_f32_16x16x32_bf16 v[22:25], v[178:181], v[216:219], v[22:25]
	v_mfma_f32_16x16x32_bf16 v[18:21], v[186:189], v[216:219], v[18:21]
	v_mfma_f32_16x16x32_bf16 v[6:9], v[178:181], v[224:227], v[6:9]
	v_mfma_f32_16x16x32_bf16 v[2:5], v[186:189], v[224:227], v[2:5]
	s_barrier
	s_setprio 0
	s_add_u32 s48, s48, 0x100
	s_addc_u32 s49, s49, 0
	s_add_u32 s56, s56, 0x100
	s_addc_u32 s57, s57, 0
	s_cmp_ge_i32 s72, s3
	s_mov_b32 s50, s72
	s_cbranch_scc0 .LBB7_1274
	s_mov_b32 s56, s61
	s_and_b64 vcc, exec, s[6:7]
	s_cbranch_vccz .LBB7_1277
